# v16 + second saddr pass: chained LDS-DMA address adds in the GEMM K-loops replaced by SALU-formed bases (s98..s101)
# speedup vs baseline: 1.0027x; 1.0027x over previous
; #define PG8_STAGE(bufoff, gbase, voff) do { _Pragma("unroll") for (int _i = 0; _i < 2; ++_i) \
;         __builtin_amdgcn_global_load_lds((const unsigned*)((const char*)(gbase) + (voff)[_i]), (PG8_LAS unsigned*)(lds + (bufoff) + ldsw + _i * 8192), 16, 0, 0); } while (0)
; #define PG8_LDA(dst, b, h) do { _Pragma("unroll") for (int m = 0; m < 4; ++m) _Pragma("unroll") for (int k = 0; k < 2; ++k) dst[m][k] = *(const PG8_LAS bf16x8*)(lds + PG8_SA(b, h) + aoff + m * 2048 + k * 1024); } while (0)
; #define PG8_LDB(dst, b, h) do { _Pragma("unroll") for (int n = 0; n < 2; ++n) _Pragma("unroll") for (int k = 0; k < 2; ++k) dst[n][k] = *(const PG8_LAS bf16x8*)(lds + PG8_SB(b, h) + boff + n * 2048 + k * 1024); } while (0)
; #define PG8_MMA(ai, bj, At, Bt) do { __builtin_amdgcn_s_setprio(1); _Pragma("unroll") for (int m = 0; m < 4; ++m) _Pragma("unroll") for (int n = 0; n < 2; ++n) _Pragma("unroll") for (int k = 0; k < 2; ++k) \
;         acc[ai][bj][m][n] = __builtin_amdgcn_mfma_f32_16x16x32_bf16(Bt[n][k], At[m][k], acc[ai][bj][m][n], 0, 0, 0); __builtin_amdgcn_s_setprio(0); } while (0)
; #define PG8_WAIT_V(n) asm volatile("s_waitcnt vmcnt(" #n ")" ::: "memory")
; template <class Epi, class Sched, bool ALIGN_EPI = false, bool SP2 = false>
; __device__ __forceinline__ void gemm_phase(PG8_LAS unsigned char* lds, const Gemm g, const Sched& S, const Epi& E) {
;     ...
;         const char* nA = has_next ? (const char*)g.A + (size_t)nxt.pm * tstepA : cA; const char* nB = has_next ? (const char*)g.Bt + (size_t)nxt.pn * tstepB : cB;
;         for (int t = 0; t < nt; t += 2) {
;             const bool last = (t == nt - 2);
;             const char* a1 = cA + (size_t)(t + 1) * kstep;
;             const char* a2 = last ? nA : cA + (size_t)(t + 2) * kstep; const char* b2 = last ? nB : cB + (size_t)(t + 2) * kstep;
;             const char* a3 = a2 + kstep; const char* b3 = b2 + kstep;
;             if (last && has_next) S.a_ready(nxt);
;             if constexpr (SP2) {
;             PG8_LDB(B0, 0, 0); PG8_LDB(B1, 0, 1); PG8_SCHED; PG8_LDA(At, 0, 0); PG8_STAGE(PG8_SA(1, 1), a1 + hstepA, voffA);
;             PG8_WAIT_V(8); PG8_WAIT_L(0); PG8_BAR; PG8_MMA(0, 0, At, B0); PG8_MMA(0, 1, At, B1); PG8_BAR; PG8_SCHED;
;             PG8_LDA(At, 0, 1); PG8_STAGE(PG8_SB(0, 0), b2, voffB); PG8_STAGE(PG8_SB(0, 1), b2 + hstepB, voffB); PG8_STAGE(PG8_SA(0, 0), a2, voffA);
.LBB0_163:
	ds_read_b128 v[0:3], v143
	ds_read_b128 v[4:7], v143 offset:1024
	ds_read_b128 v[8:11], v143 offset:2048
	ds_read_b128 v[12:15], v143 offset:3072
	ds_read_b128 v[16:19], v144
	ds_read_b128 v[20:23], v144 offset:1024
	ds_read_b128 v[24:27], v144 offset:2048
	ds_read_b128 v[28:31], v144 offset:3072
	s_ashr_i32 s31, s30, 31
	s_lshl_b64 s[34:35], s[30:31], 17
	s_add_u32 s34, s54, s34
	s_addc_u32 s35, s55, s35
	s_and_b64 s[36:37], s[0:1], exec
	s_cselect_b32 s51, s35, s39
	s_cselect_b32 s50, s34, s38
	s_ashr_i32 s29, s28, 31
	s_lshl_b64 s[36:37], s[28:29], 17
	s_add_u32 s36, s2, s36
	s_addc_u32 s37, s3, s37
	s_and_b64 s[44:45], s[0:1], exec
	s_cselect_b32 s47, s37, s41
	s_cselect_b32 s46, s36, s40
	s_add_u32 s44, s38, 0x10080
	s_addc_u32 s45, s39, 0
	s_add_i32 s63, s9, 0xc000
	s_mov_b32 m0, s63
	s_add_i32 s29, s9, 0xe000
	ds_read_b128 v[32:35], v145
	ds_read_b128 v[36:39], v145 offset:1024
	ds_read_b128 v[40:43], v145 offset:2048
	ds_read_b128 v[44:47], v145 offset:3072
	ds_read_b128 v[48:51], v145 offset:4096
	ds_read_b128 v[52:55], v145 offset:5120
	ds_read_b128 v[56:59], v145 offset:6144
	ds_read_b128 v[60:63], v145 offset:7168
	global_load_lds_dwordx4 v128, s[44:45]
	s_mov_b32 m0, s29
	s_nop 0
	global_load_lds_dwordx4 v132, s[44:45]
	s_waitcnt vmcnt(8)
	s_waitcnt lgkmcnt(0)
	s_barrier
	s_waitcnt lgkmcnt(0)
	v_mfma_f32_16x16x32_bf16 v[64:67], v[0:3], v[32:35], 0
	v_mfma_f32_16x16x32_bf16 v[68:71], v[8:11], v[32:35], 0
	v_mfma_f32_16x16x32_bf16 v[72:75], v[0:3], v[40:43], 0
	v_mfma_f32_16x16x32_bf16 v[76:79], v[8:11], v[40:43], 0
	v_mfma_f32_16x16x32_bf16 v[80:83], v[0:3], v[48:51], 0
	v_mfma_f32_16x16x32_bf16 v[84:87], v[8:11], v[48:51], 0
	v_mfma_f32_16x16x32_bf16 v[88:91], v[0:3], v[56:59], 0
	v_mfma_f32_16x16x32_bf16 v[92:95], v[8:11], v[56:59], 0
	v_mfma_f32_16x16x32_bf16 v[64:67], v[4:7], v[36:39], v[64:67]
	v_mfma_f32_16x16x32_bf16 v[68:71], v[12:15], v[36:39], v[68:71]
	v_mfma_f32_16x16x32_bf16 v[72:75], v[4:7], v[44:47], v[72:75]
	v_mfma_f32_16x16x32_bf16 v[76:79], v[12:15], v[44:47], v[76:79]
	v_mfma_f32_16x16x32_bf16 v[80:83], v[4:7], v[52:55], v[80:83]
	v_mfma_f32_16x16x32_bf16 v[84:87], v[12:15], v[52:55], v[84:87]
	v_mfma_f32_16x16x32_bf16 v[88:91], v[4:7], v[60:63], v[88:91]
	v_mfma_f32_16x16x32_bf16 v[92:95], v[12:15], v[60:63], v[92:95]
	v_mfma_f32_16x16x32_bf16 v[96:99], v[16:19], v[32:35], 0
	v_mfma_f32_16x16x32_bf16 v[32:35], v[24:27], v[32:35], 0
	v_mfma_f32_16x16x32_bf16 v[96:99], v[20:23], v[36:39], v[96:99]
	v_mfma_f32_16x16x32_bf16 v[32:35], v[28:31], v[36:39], v[32:35]
	v_mfma_f32_16x16x32_bf16 v[36:39], v[16:19], v[40:43], 0
	v_mfma_f32_16x16x32_bf16 v[40:43], v[24:27], v[40:43], 0
	v_mfma_f32_16x16x32_bf16 v[36:39], v[20:23], v[44:47], v[36:39]
	v_mfma_f32_16x16x32_bf16 v[40:43], v[28:31], v[44:47], v[40:43]
	v_mfma_f32_16x16x32_bf16 v[44:47], v[16:19], v[48:51], 0
	v_mfma_f32_16x16x32_bf16 v[48:51], v[24:27], v[48:51], 0
	v_mfma_f32_16x16x32_bf16 v[44:47], v[20:23], v[52:55], v[44:47]
	v_mfma_f32_16x16x32_bf16 v[48:51], v[28:31], v[52:55], v[48:51]
	v_mfma_f32_16x16x32_bf16 v[52:55], v[16:19], v[56:59], 0
	v_mfma_f32_16x16x32_bf16 v[56:59], v[24:27], v[56:59], 0
	v_mfma_f32_16x16x32_bf16 v[52:55], v[20:23], v[60:63], v[52:55]
	v_mfma_f32_16x16x32_bf16 v[56:59], v[28:31], v[60:63], v[56:59]
	s_barrier
	s_add_i32 s48, s59, s8
	v_lshl_add_u64 v[190:191], s[40:41], 0, v[130:131]
	s_add_i32 s31, s48, 0x2000
	v_lshl_add_u64 v[146:147], v[190:191], 0, s[22:23]
	s_mov_b32 m0, s48
	v_lshl_add_u64 v[216:217], s[40:41], 0, v[134:135]
	s_add_u32 s64, s40, 0x10100
	ds_read_b128 v[60:63], v145 offset:16384
	ds_read_b128 v[100:103], v145 offset:17408
	ds_read_b128 v[104:107], v145 offset:18432
	ds_read_b128 v[108:111], v145 offset:19456
	ds_read_b128 v[112:115], v145 offset:20480
	ds_read_b128 v[116:119], v145 offset:21504
	ds_read_b128 v[120:123], v145 offset:22528
	ds_read_b128 v[124:127], v145 offset:23552
	global_load_lds_dwordx4 v[146:147], off
	v_lshl_add_u64 v[146:147], v[216:217], 0, s[22:23]
	s_mov_b32 m0, s31
	s_addc_u32 s65, s41, 0
	s_add_i32 s44, s60, s8
	global_load_lds_dwordx4 v[146:147], off
	s_mov_b32 m0, s44
	s_add_i32 s45, s44, 0x2000
	global_load_lds_dwordx4 v130, s[64:65]
	s_mov_b32 m0, s45
	v_lshl_add_u64 v[218:219], s[38:39], 0, v[128:129]
	global_load_lds_dwordx4 v134, s[64:65]
	v_lshl_add_u64 v[146:147], v[218:219], 0, s[22:23]
	s_mov_b32 m0, s9
	v_lshl_add_u64 v[220:221], s[38:39], 0, v[132:133]
	global_load_lds_dwordx4 v[146:147], off
	v_lshl_add_u64 v[146:147], v[220:221], 0, s[22:23]
	s_mov_b32 m0, s27
	s_nop 0
	global_load_lds_dwordx4 v[146:147], off
	s_waitcnt vmcnt(8)
	s_waitcnt lgkmcnt(0)
	s_barrier
; #define PG8_STAGE(bufoff, gbase, voff) do { _Pragma("unroll") for (int _i = 0; _i < 2; ++_i) \
;         __builtin_amdgcn_global_load_lds((const unsigned*)((const char*)(gbase) + (voff)[_i]), (PG8_LAS unsigned*)(lds + (bufoff) + ldsw + _i * 8192), 16, 0, 0); } while (0)
; #define PG8_LDA(dst, b, h) do { _Pragma("unroll") for (int m = 0; m < 4; ++m) _Pragma("unroll") for (int k = 0; k < 2; ++k) dst[m][k] = *(const PG8_LAS bf16x8*)(lds + PG8_SA(b, h) + aoff + m * 2048 + k * 1024); } while (0)
; #define PG8_LDB(dst, b, h) do { _Pragma("unroll") for (int n = 0; n < 2; ++n) _Pragma("unroll") for (int k = 0; k < 2; ++k) dst[n][k] = *(const PG8_LAS bf16x8*)(lds + PG8_SB(b, h) + boff + n * 2048 + k * 1024); } while (0)
; #define PG8_MMA(ai, bj, At, Bt) do { __builtin_amdgcn_s_setprio(1); _Pragma("unroll") for (int m = 0; m < 4; ++m) _Pragma("unroll") for (int n = 0; n < 2; ++n) _Pragma("unroll") for (int k = 0; k < 2; ++k) \
;         acc[ai][bj][m][n] = __builtin_amdgcn_mfma_f32_16x16x32_bf16(Bt[n][k], At[m][k], acc[ai][bj][m][n], 0, 0, 0); __builtin_amdgcn_s_setprio(0); } while (0)
; #define PG8_WAIT_V(n) asm volatile("s_waitcnt vmcnt(" #n ")" ::: "memory")
; #define PG8_WAIT_L(n) asm volatile("s_waitcnt lgkmcnt(" #n ")" ::: "memory")
; #define PG8_BAR __builtin_amdgcn_s_barrier()
; #define PG8_SCHED __builtin_amdgcn_sched_barrier(0)
; template <class Epi, class Sched, bool ALIGN_EPI = false, bool SP2 = false>
; __device__ __forceinline__ void gemm_phase(PG8_LAS unsigned char* lds, const Gemm g, const Sched& S, const Epi& E) {
;     ...
;             PG8_WAIT_V(8); PG8_WAIT_L(0); PG8_BAR; PG8_MMA(1, 0, At, B0); PG8_MMA(1, 1, At, B1); PG8_BAR; PG8_SCHED;
;             PG8_LDB(B0, 1, 0); PG8_LDB(B1, 1, 1); PG8_SCHED; PG8_LDA(At, 1, 0); PG8_STAGE(PG8_SA(0, 1), a2 + hstepA, voffA);
;             PG8_WAIT_V(8); PG8_WAIT_L(0); PG8_BAR; PG8_MMA(0, 0, At, B0); PG8_MMA(0, 1, At, B1); PG8_BAR; PG8_SCHED;
	s_waitcnt lgkmcnt(0)
	v_mfma_f32_16x16x32_bf16 v[146:149], v[0:3], v[60:63], 0
	v_mfma_f32_16x16x32_bf16 v[154:157], v[0:3], v[104:107], 0
	v_mfma_f32_16x16x32_bf16 v[162:165], v[0:3], v[112:115], 0
	v_mfma_f32_16x16x32_bf16 v[0:3], v[0:3], v[120:123], 0
	v_mfma_f32_16x16x32_bf16 v[146:149], v[4:7], v[100:103], v[146:149]
	v_mfma_f32_16x16x32_bf16 v[154:157], v[4:7], v[108:111], v[154:157]
	v_mfma_f32_16x16x32_bf16 v[162:165], v[4:7], v[116:119], v[162:165]
	v_mfma_f32_16x16x32_bf16 v[0:3], v[4:7], v[124:127], v[0:3]
	v_mfma_f32_16x16x32_bf16 v[4:7], v[8:11], v[120:123], 0
	v_mfma_f32_16x16x32_bf16 v[150:153], v[8:11], v[60:63], 0
	v_mfma_f32_16x16x32_bf16 v[158:161], v[8:11], v[104:107], 0
	v_mfma_f32_16x16x32_bf16 v[166:169], v[8:11], v[112:115], 0
	v_mfma_f32_16x16x32_bf16 v[4:7], v[12:15], v[124:127], v[4:7]
	v_mfma_f32_16x16x32_bf16 v[150:153], v[12:15], v[100:103], v[150:153]
	v_mfma_f32_16x16x32_bf16 v[158:161], v[12:15], v[108:111], v[158:161]
	v_mfma_f32_16x16x32_bf16 v[166:169], v[12:15], v[116:119], v[166:169]
	v_mfma_f32_16x16x32_bf16 v[8:11], v[16:19], v[60:63], 0
	v_mfma_f32_16x16x32_bf16 v[12:15], v[24:27], v[60:63], 0
	v_mfma_f32_16x16x32_bf16 v[8:11], v[20:23], v[100:103], v[8:11]
	v_mfma_f32_16x16x32_bf16 v[12:15], v[28:31], v[100:103], v[12:15]
	v_mfma_f32_16x16x32_bf16 v[60:63], v[16:19], v[104:107], 0
	v_mfma_f32_16x16x32_bf16 v[100:103], v[24:27], v[104:107], 0
	v_mfma_f32_16x16x32_bf16 v[104:107], v[16:19], v[112:115], 0
	v_mfma_f32_16x16x32_bf16 v[16:19], v[16:19], v[120:123], 0
	v_mfma_f32_16x16x32_bf16 v[60:63], v[20:23], v[108:111], v[60:63]
	v_mfma_f32_16x16x32_bf16 v[100:103], v[28:31], v[108:111], v[100:103]
	v_mfma_f32_16x16x32_bf16 v[104:107], v[20:23], v[116:119], v[104:107]
	v_mfma_f32_16x16x32_bf16 v[108:111], v[24:27], v[112:115], 0
	v_mfma_f32_16x16x32_bf16 v[16:19], v[20:23], v[124:127], v[16:19]
	v_mfma_f32_16x16x32_bf16 v[20:23], v[24:27], v[120:123], 0
	v_mfma_f32_16x16x32_bf16 v[108:111], v[28:31], v[116:119], v[108:111]
	v_mfma_f32_16x16x32_bf16 v[20:23], v[28:31], v[124:127], v[20:23]
	s_barrier
	s_add_i32 s49, 0, 0x18000
	s_add_i32 s68, 0, 0x1c000
	v_add_u32_e32 v224, s49, v142
	v_add_u32_e32 v228, s68, v142
	ds_read_b128 v[24:27], v224
	ds_read_b128 v[28:31], v224 offset:1024
	ds_read_b128 v[112:115], v224 offset:2048
	ds_read_b128 v[116:119], v224 offset:3072
	ds_read_b128 v[120:123], v228
	ds_read_b128 v[124:127], v228 offset:1024
	ds_read_b128 v[170:173], v228 offset:2048
	ds_read_b128 v[174:177], v228 offset:3072
	s_add_u32 s64, s38, 0x10100
	s_addc_u32 s65, s39, 0
	s_mov_b32 m0, s33
	ds_read_b128 v[178:181], v145 offset:32768
	ds_read_b128 v[182:185], v145 offset:33792
	ds_read_b128 v[186:189], v145 offset:34816
	ds_read_b128 v[196:199], v145 offset:35840
	ds_read_b128 v[200:203], v145 offset:36864
	ds_read_b128 v[204:207], v145 offset:37888
	ds_read_b128 v[208:211], v145 offset:38912
	ds_read_b128 v[212:215], v145 offset:39936
	global_load_lds_dwordx4 v128, s[64:65]
	s_mov_b32 m0, s42
	s_nop 0
	global_load_lds_dwordx4 v132, s[64:65]
	s_waitcnt vmcnt(8)
	s_waitcnt lgkmcnt(0)
	s_barrier
	s_waitcnt lgkmcnt(0)
	v_mfma_f32_16x16x32_bf16 v[64:67], v[24:27], v[178:181], v[64:67]
	v_mfma_f32_16x16x32_bf16 v[68:71], v[112:115], v[178:181], v[68:71]
	v_mfma_f32_16x16x32_bf16 v[72:75], v[24:27], v[186:189], v[72:75]
	v_mfma_f32_16x16x32_bf16 v[76:79], v[112:115], v[186:189], v[76:79]
	v_mfma_f32_16x16x32_bf16 v[80:83], v[24:27], v[200:203], v[80:83]
	v_mfma_f32_16x16x32_bf16 v[84:87], v[112:115], v[200:203], v[84:87]
	v_mfma_f32_16x16x32_bf16 v[88:91], v[24:27], v[208:211], v[88:91]
	v_mfma_f32_16x16x32_bf16 v[92:95], v[112:115], v[208:211], v[92:95]
	v_mfma_f32_16x16x32_bf16 v[64:67], v[28:31], v[182:185], v[64:67]
	v_mfma_f32_16x16x32_bf16 v[68:71], v[116:119], v[182:185], v[68:71]
	v_mfma_f32_16x16x32_bf16 v[72:75], v[28:31], v[196:199], v[72:75]
	v_mfma_f32_16x16x32_bf16 v[76:79], v[116:119], v[196:199], v[76:79]
	v_mfma_f32_16x16x32_bf16 v[80:83], v[28:31], v[204:207], v[80:83]
	v_mfma_f32_16x16x32_bf16 v[84:87], v[116:119], v[204:207], v[84:87]
	v_mfma_f32_16x16x32_bf16 v[88:91], v[28:31], v[212:215], v[88:91]
	v_mfma_f32_16x16x32_bf16 v[92:95], v[116:119], v[212:215], v[92:95]
	v_mfma_f32_16x16x32_bf16 v[96:99], v[120:123], v[178:181], v[96:99]
	v_mfma_f32_16x16x32_bf16 v[32:35], v[170:173], v[178:181], v[32:35]
	v_mfma_f32_16x16x32_bf16 v[36:39], v[120:123], v[186:189], v[36:39]
	v_mfma_f32_16x16x32_bf16 v[40:43], v[170:173], v[186:189], v[40:43]
	v_mfma_f32_16x16x32_bf16 v[44:47], v[120:123], v[200:203], v[44:47]
	v_mfma_f32_16x16x32_bf16 v[48:51], v[170:173], v[200:203], v[48:51]
	v_mfma_f32_16x16x32_bf16 v[52:55], v[120:123], v[208:211], v[52:55]
	v_mfma_f32_16x16x32_bf16 v[56:59], v[170:173], v[208:211], v[56:59]
	v_mfma_f32_16x16x32_bf16 v[96:99], v[124:127], v[182:185], v[96:99]
	v_mfma_f32_16x16x32_bf16 v[32:35], v[174:177], v[182:185], v[32:35]
	v_mfma_f32_16x16x32_bf16 v[36:39], v[124:127], v[196:199], v[36:39]
	v_mfma_f32_16x16x32_bf16 v[40:43], v[174:177], v[196:199], v[40:43]
	v_mfma_f32_16x16x32_bf16 v[44:47], v[124:127], v[204:207], v[44:47]
	v_mfma_f32_16x16x32_bf16 v[48:51], v[174:177], v[204:207], v[48:51]
	v_mfma_f32_16x16x32_bf16 v[52:55], v[124:127], v[212:215], v[52:55]
	v_mfma_f32_16x16x32_bf16 v[56:59], v[174:177], v[212:215], v[56:59]
	s_barrier
; #define PG8_STAGE(bufoff, gbase, voff) do { _Pragma("unroll") for (int _i = 0; _i < 2; ++_i) \
;         __builtin_amdgcn_global_load_lds((const unsigned*)((const char*)(gbase) + (voff)[_i]), (PG8_LAS unsigned*)(lds + (bufoff) + ldsw + _i * 8192), 16, 0, 0); } while (0)
; #define PG8_LDA(dst, b, h) do { _Pragma("unroll") for (int m = 0; m < 4; ++m) _Pragma("unroll") for (int k = 0; k < 2; ++k) dst[m][k] = *(const PG8_LAS bf16x8*)(lds + PG8_SA(b, h) + aoff + m * 2048 + k * 1024); } while (0)
; #define PG8_LDB(dst, b, h) do { _Pragma("unroll") for (int n = 0; n < 2; ++n) _Pragma("unroll") for (int k = 0; k < 2; ++k) dst[n][k] = *(const PG8_LAS bf16x8*)(lds + PG8_SB(b, h) + boff + n * 2048 + k * 1024); } while (0)
; #define PG8_MMA(ai, bj, At, Bt) do { __builtin_amdgcn_s_setprio(1); _Pragma("unroll") for (int m = 0; m < 4; ++m) _Pragma("unroll") for (int n = 0; n < 2; ++n) _Pragma("unroll") for (int k = 0; k < 2; ++k) \
;         acc[ai][bj][m][n] = __builtin_amdgcn_mfma_f32_16x16x32_bf16(Bt[n][k], At[m][k], acc[ai][bj][m][n], 0, 0, 0); __builtin_amdgcn_s_setprio(0); } while (0)
; #define PG8_WAIT_V(n) asm volatile("s_waitcnt vmcnt(" #n ")" ::: "memory")
; #define PG8_WAIT_L(n) asm volatile("s_waitcnt lgkmcnt(" #n ")" ::: "memory")
; #define PG8_BAR __builtin_amdgcn_s_barrier()
; #define PG8_SCHED __builtin_amdgcn_sched_barrier(0)
; template <class Epi, class Sched, bool ALIGN_EPI = false, bool SP2 = false>
; __device__ __forceinline__ void gemm_phase(PG8_LAS unsigned char* lds, const Gemm g, const Sched& S, const Epi& E) {
;     ...
;             PG8_LDB(B0, 0, 0); PG8_LDB(B1, 0, 1); PG8_SCHED; PG8_LDA(At, 0, 0); PG8_STAGE(PG8_SA(1, 1), a1 + hstepA, voffA);
;             PG8_WAIT_V(8); PG8_WAIT_L(0); PG8_BAR; PG8_MMA(0, 0, At, B0); PG8_MMA(0, 1, At, B1); PG8_BAR; PG8_SCHED;
;     ...
;             PG8_LDA(At, 1, 1); PG8_STAGE(PG8_SB(1, 0), b3, voffB); PG8_STAGE(PG8_SB(1, 1), b3 + hstepB, voffB); PG8_STAGE(PG8_SA(1, 0), a3, voffA);
;             PG8_WAIT_V(8); PG8_WAIT_L(0); PG8_BAR; PG8_MMA(1, 0, At, B0); PG8_MMA(1, 1, At, B1); PG8_BAR; PG8_SCHED;
	s_add_i32 s64, s49, s8
	s_add_i32 s49, s64, 0x2000
	v_lshl_add_u64 v[190:191], v[190:191], 0, s[24:25]
	s_mov_b32 m0, s64
	s_add_u32 s66, s40, 0x10180
	ds_read_b128 v[178:181], v145 offset:49152
	ds_read_b128 v[182:185], v145 offset:50176
	ds_read_b128 v[186:189], v145 offset:51200
	ds_read_b128 v[196:199], v145 offset:52224
	ds_read_b128 v[200:203], v145 offset:53248
	ds_read_b128 v[204:207], v145 offset:54272
	ds_read_b128 v[208:211], v145 offset:55296
	ds_read_b128 v[212:215], v145 offset:56320
	global_load_lds_dwordx4 v[190:191], off
	v_lshl_add_u64 v[190:191], v[216:217], 0, s[24:25]
	s_mov_b32 m0, s49
	s_addc_u32 s67, s41, 0
	s_add_i32 s40, s68, s8
	global_load_lds_dwordx4 v[190:191], off
	s_mov_b32 m0, s40
	s_add_i32 s41, s40, 0x2000
	global_load_lds_dwordx4 v130, s[66:67]
	s_mov_b32 m0, s41
	s_nop 0
	global_load_lds_dwordx4 v134, s[66:67]
	v_lshl_add_u64 v[190:191], v[218:219], 0, s[24:25]
	s_mov_b32 m0, s53
	s_nop 0
	global_load_lds_dwordx4 v[190:191], off
	v_lshl_add_u64 v[190:191], v[220:221], 0, s[24:25]
	s_mov_b32 m0, s56
	s_nop 0
	global_load_lds_dwordx4 v[190:191], off
	s_waitcnt vmcnt(8)
	s_waitcnt lgkmcnt(0)
	s_barrier
	s_waitcnt lgkmcnt(0)
	v_mfma_f32_16x16x32_bf16 v[0:3], v[24:27], v[208:211], v[0:3]
	v_mfma_f32_16x16x32_bf16 v[4:7], v[112:115], v[208:211], v[4:7]
	v_mfma_f32_16x16x32_bf16 v[146:149], v[24:27], v[178:181], v[146:149]
	v_mfma_f32_16x16x32_bf16 v[150:153], v[112:115], v[178:181], v[150:153]
	v_mfma_f32_16x16x32_bf16 v[154:157], v[24:27], v[186:189], v[154:157]
	v_mfma_f32_16x16x32_bf16 v[158:161], v[112:115], v[186:189], v[158:161]
	v_mfma_f32_16x16x32_bf16 v[162:165], v[24:27], v[200:203], v[162:165]
	v_mfma_f32_16x16x32_bf16 v[166:169], v[112:115], v[200:203], v[166:169]
	v_mfma_f32_16x16x32_bf16 v[0:3], v[28:31], v[212:215], v[0:3]
	v_mfma_f32_16x16x32_bf16 v[4:7], v[116:119], v[212:215], v[4:7]
	v_mfma_f32_16x16x32_bf16 v[146:149], v[28:31], v[182:185], v[146:149]
	v_mfma_f32_16x16x32_bf16 v[150:153], v[116:119], v[182:185], v[150:153]
	v_mfma_f32_16x16x32_bf16 v[154:157], v[28:31], v[196:199], v[154:157]
	v_mfma_f32_16x16x32_bf16 v[158:161], v[116:119], v[196:199], v[158:161]
	v_mfma_f32_16x16x32_bf16 v[162:165], v[28:31], v[204:207], v[162:165]
	v_mfma_f32_16x16x32_bf16 v[166:169], v[116:119], v[204:207], v[166:169]
	v_mfma_f32_16x16x32_bf16 v[8:11], v[120:123], v[178:181], v[8:11]
	v_mfma_f32_16x16x32_bf16 v[12:15], v[170:173], v[178:181], v[12:15]
	v_mfma_f32_16x16x32_bf16 v[24:27], v[120:123], v[186:189], v[60:63]
	v_mfma_f32_16x16x32_bf16 v[28:31], v[170:173], v[186:189], v[100:103]
	v_mfma_f32_16x16x32_bf16 v[60:63], v[120:123], v[200:203], v[104:107]
	v_mfma_f32_16x16x32_bf16 v[100:103], v[170:173], v[200:203], v[108:111]
	v_mfma_f32_16x16x32_bf16 v[16:19], v[120:123], v[208:211], v[16:19]
	v_mfma_f32_16x16x32_bf16 v[20:23], v[170:173], v[208:211], v[20:23]
	v_mfma_f32_16x16x32_bf16 v[8:11], v[124:127], v[182:185], v[8:11]
	v_mfma_f32_16x16x32_bf16 v[12:15], v[174:177], v[182:185], v[12:15]
	v_mfma_f32_16x16x32_bf16 v[24:27], v[124:127], v[196:199], v[24:27]
	v_mfma_f32_16x16x32_bf16 v[28:31], v[174:177], v[196:199], v[28:31]
	v_mfma_f32_16x16x32_bf16 v[60:63], v[124:127], v[204:207], v[60:63]
	v_mfma_f32_16x16x32_bf16 v[100:103], v[174:177], v[204:207], v[100:103]
	v_mfma_f32_16x16x32_bf16 v[16:19], v[124:127], v[212:215], v[16:19]
	v_mfma_f32_16x16x32_bf16 v[20:23], v[174:177], v[212:215], v[20:23]
	s_barrier
	ds_read_b128 v[104:107], v143
	ds_read_b128 v[108:111], v143 offset:1024
	ds_read_b128 v[112:115], v143 offset:2048
	ds_read_b128 v[116:119], v143 offset:3072
	ds_read_b128 v[120:123], v144
	ds_read_b128 v[124:127], v144 offset:1024
	ds_read_b128 v[170:173], v144 offset:2048
	ds_read_b128 v[174:177], v144 offset:3072
	s_add_u32 s38, s38, 0x10180
	s_addc_u32 s39, s39, 0
	s_mov_b32 m0, s63
	ds_read_b128 v[178:181], v145
	ds_read_b128 v[182:185], v145 offset:1024
	ds_read_b128 v[186:189], v145 offset:2048
	ds_read_b128 v[196:199], v145 offset:3072
	ds_read_b128 v[200:203], v145 offset:4096
	ds_read_b128 v[204:207], v145 offset:5120
	ds_read_b128 v[208:211], v145 offset:6144
	ds_read_b128 v[212:215], v145 offset:7168
	global_load_lds_dwordx4 v128, s[38:39]
	s_mov_b32 m0, s29
	s_nop 0
	global_load_lds_dwordx4 v132, s[38:39]
	s_waitcnt vmcnt(8)
	s_waitcnt lgkmcnt(0)
	s_barrier
	s_waitcnt lgkmcnt(0)
	v_mfma_f32_16x16x32_bf16 v[64:67], v[104:107], v[178:181], v[64:67]
	v_mfma_f32_16x16x32_bf16 v[68:71], v[112:115], v[178:181], v[68:71]
	v_mfma_f32_16x16x32_bf16 v[72:75], v[104:107], v[186:189], v[72:75]
	v_mfma_f32_16x16x32_bf16 v[76:79], v[112:115], v[186:189], v[76:79]
	v_mfma_f32_16x16x32_bf16 v[80:83], v[104:107], v[200:203], v[80:83]
	v_mfma_f32_16x16x32_bf16 v[84:87], v[112:115], v[200:203], v[84:87]
	v_mfma_f32_16x16x32_bf16 v[88:91], v[104:107], v[208:211], v[88:91]
	v_mfma_f32_16x16x32_bf16 v[92:95], v[112:115], v[208:211], v[92:95]
	v_mfma_f32_16x16x32_bf16 v[64:67], v[108:111], v[182:185], v[64:67]
	v_mfma_f32_16x16x32_bf16 v[68:71], v[116:119], v[182:185], v[68:71]
	v_mfma_f32_16x16x32_bf16 v[72:75], v[108:111], v[196:199], v[72:75]
	v_mfma_f32_16x16x32_bf16 v[76:79], v[116:119], v[196:199], v[76:79]
	v_mfma_f32_16x16x32_bf16 v[80:83], v[108:111], v[204:207], v[80:83]
	v_mfma_f32_16x16x32_bf16 v[84:87], v[116:119], v[204:207], v[84:87]
	v_mfma_f32_16x16x32_bf16 v[88:91], v[108:111], v[212:215], v[88:91]
	v_mfma_f32_16x16x32_bf16 v[92:95], v[116:119], v[212:215], v[92:95]
	v_mfma_f32_16x16x32_bf16 v[32:35], v[170:173], v[178:181], v[32:35]
	v_mfma_f32_16x16x32_bf16 v[96:99], v[120:123], v[178:181], v[96:99]
	v_mfma_f32_16x16x32_bf16 v[178:181], v[174:177], v[182:185], v[32:35]
	v_mfma_f32_16x16x32_bf16 v[32:35], v[120:123], v[186:189], v[36:39]
	v_mfma_f32_16x16x32_bf16 v[216:219], v[124:127], v[182:185], v[96:99]
	v_mfma_f32_16x16x32_bf16 v[182:185], v[124:127], v[196:199], v[32:35]
	v_mfma_f32_16x16x32_bf16 v[32:35], v[170:173], v[186:189], v[40:43]
	v_mfma_f32_16x16x32_bf16 v[40:43], v[174:177], v[196:199], v[32:35]
	v_mfma_f32_16x16x32_bf16 v[32:35], v[120:123], v[200:203], v[44:47]
	v_mfma_f32_16x16x32_bf16 v[44:47], v[124:127], v[204:207], v[32:35]
	v_mfma_f32_16x16x32_bf16 v[32:35], v[170:173], v[200:203], v[48:51]
	v_mfma_f32_16x16x32_bf16 v[48:51], v[174:177], v[204:207], v[32:35]
	v_mfma_f32_16x16x32_bf16 v[32:35], v[120:123], v[208:211], v[52:55]
	v_mfma_f32_16x16x32_bf16 v[52:55], v[124:127], v[212:215], v[32:35]
	v_mfma_f32_16x16x32_bf16 v[32:35], v[170:173], v[208:211], v[56:59]
	v_mfma_f32_16x16x32_bf16 v[56:59], v[174:177], v[212:215], v[32:35]
	s_barrier
; #define PG8_STAGE(bufoff, gbase, voff) do { _Pragma("unroll") for (int _i = 0; _i < 2; ++_i) \
;         __builtin_amdgcn_global_load_lds((const unsigned*)((const char*)(gbase) + (voff)[_i]), (PG8_LAS unsigned*)(lds + (bufoff) + ldsw + _i * 8192), 16, 0, 0); } while (0)
; #define PG8_LDA(dst, b, h) do { _Pragma("unroll") for (int m = 0; m < 4; ++m) _Pragma("unroll") for (int k = 0; k < 2; ++k) dst[m][k] = *(const PG8_LAS bf16x8*)(lds + PG8_SA(b, h) + aoff + m * 2048 + k * 1024); } while (0)
; #define PG8_LDB(dst, b, h) do { _Pragma("unroll") for (int n = 0; n < 2; ++n) _Pragma("unroll") for (int k = 0; k < 2; ++k) dst[n][k] = *(const PG8_LAS bf16x8*)(lds + PG8_SB(b, h) + boff + n * 2048 + k * 1024); } while (0)
; #define PG8_MMA(ai, bj, At, Bt) do { __builtin_amdgcn_s_setprio(1); _Pragma("unroll") for (int m = 0; m < 4; ++m) _Pragma("unroll") for (int n = 0; n < 2; ++n) _Pragma("unroll") for (int k = 0; k < 2; ++k) \
;         acc[ai][bj][m][n] = __builtin_amdgcn_mfma_f32_16x16x32_bf16(Bt[n][k], At[m][k], acc[ai][bj][m][n], 0, 0, 0); __builtin_amdgcn_s_setprio(0); } while (0)
; #define PG8_WAIT_V(n) asm volatile("s_waitcnt vmcnt(" #n ")" ::: "memory")
; #define PG8_WAIT_L(n) asm volatile("s_waitcnt lgkmcnt(" #n ")" ::: "memory")
; #define PG8_BAR __builtin_amdgcn_s_barrier()
; #define PG8_SCHED __builtin_amdgcn_sched_barrier(0)
; template <class Epi, class Sched, bool ALIGN_EPI = false, bool SP2 = false>
; __device__ __forceinline__ void gemm_phase(PG8_LAS unsigned char* lds, const Gemm g, const Sched& S, const Epi& E) {
;     ...
;             PG8_LDA(At, 0, 1); PG8_STAGE(PG8_SB(0, 0), b2, voffB); PG8_STAGE(PG8_SB(0, 1), b2 + hstepB, voffB); PG8_STAGE(PG8_SA(0, 0), a2, voffA);
;             PG8_WAIT_V(8); PG8_WAIT_L(0); PG8_BAR; PG8_MMA(1, 0, At, B0); PG8_MMA(1, 1, At, B1); PG8_BAR; PG8_SCHED;
;             PG8_LDB(B0, 1, 0); PG8_LDB(B1, 1, 1); PG8_SCHED; PG8_LDA(At, 1, 0); PG8_STAGE(PG8_SA(0, 1), a2 + hstepA, voffA);
;             PG8_WAIT_V(8); PG8_WAIT_L(0); PG8_BAR; PG8_MMA(0, 0, At, B0); PG8_MMA(0, 1, At, B1); PG8_BAR; PG8_SCHED;
	s_mov_b32 m0, s48
	s_add_u32 s98, s46, s16
	s_addc_u32 s99, s47, s17
	s_add_u32 s38, s46, 0x10000
	s_nop 1
	ds_read_b128 v[32:35], v145 offset:16384
	ds_read_b128 v[36:39], v145 offset:17408
	ds_read_b128 v[96:99], v145 offset:18432
	ds_read_b128 v[186:189], v145 offset:19456
	ds_read_b128 v[196:199], v145 offset:20480
	ds_read_b128 v[200:203], v145 offset:21504
	ds_read_b128 v[204:207], v145 offset:22528
	ds_read_b128 v[208:211], v145 offset:23552
	global_load_lds_dwordx4 v130, s[46:47]
	s_mov_b32 m0, s31
	s_addc_u32 s39, s47, 0
	global_load_lds_dwordx4 v134, s[46:47]
	s_mov_b32 m0, s44
	global_load_lds_dwordx4 v130, s[38:39]
	s_mov_b32 m0, s45
	global_load_lds_dwordx4 v134, s[38:39]
	s_mov_b32 m0, s9
	s_nop 0
	s_add_u32 s100, s50, s16
	s_addc_u32 s101, s51, s17
	global_load_lds_dwordx4 v128, s[50:51]
	s_mov_b32 m0, s27
	s_nop 0
	global_load_lds_dwordx4 v132, s[50:51]
	s_waitcnt vmcnt(8)
	s_waitcnt lgkmcnt(0)
	s_barrier
	s_waitcnt lgkmcnt(0)
	v_mfma_f32_16x16x32_bf16 v[0:3], v[104:107], v[204:207], v[0:3]
	v_mfma_f32_16x16x32_bf16 v[4:7], v[112:115], v[204:207], v[4:7]
	v_mfma_f32_16x16x32_bf16 v[146:149], v[104:107], v[32:35], v[146:149]
	v_mfma_f32_16x16x32_bf16 v[150:153], v[112:115], v[32:35], v[150:153]
	v_mfma_f32_16x16x32_bf16 v[154:157], v[104:107], v[96:99], v[154:157]
	v_mfma_f32_16x16x32_bf16 v[158:161], v[112:115], v[96:99], v[158:161]
	v_mfma_f32_16x16x32_bf16 v[162:165], v[104:107], v[196:199], v[162:165]
	v_mfma_f32_16x16x32_bf16 v[166:169], v[112:115], v[196:199], v[166:169]
	v_mfma_f32_16x16x32_bf16 v[0:3], v[108:111], v[208:211], v[0:3]
	v_mfma_f32_16x16x32_bf16 v[4:7], v[116:119], v[208:211], v[4:7]
	v_mfma_f32_16x16x32_bf16 v[146:149], v[108:111], v[36:39], v[146:149]
	v_mfma_f32_16x16x32_bf16 v[150:153], v[116:119], v[36:39], v[150:153]
	v_mfma_f32_16x16x32_bf16 v[154:157], v[108:111], v[186:189], v[154:157]
	v_mfma_f32_16x16x32_bf16 v[158:161], v[116:119], v[186:189], v[158:161]
	v_mfma_f32_16x16x32_bf16 v[162:165], v[108:111], v[200:203], v[162:165]
	v_mfma_f32_16x16x32_bf16 v[166:169], v[116:119], v[200:203], v[166:169]
	v_mfma_f32_16x16x32_bf16 v[8:11], v[120:123], v[32:35], v[8:11]
	v_mfma_f32_16x16x32_bf16 v[12:15], v[170:173], v[32:35], v[12:15]
	v_mfma_f32_16x16x32_bf16 v[24:27], v[120:123], v[96:99], v[24:27]
	v_mfma_f32_16x16x32_bf16 v[28:31], v[170:173], v[96:99], v[28:31]
	v_mfma_f32_16x16x32_bf16 v[32:35], v[120:123], v[196:199], v[60:63]
	v_mfma_f32_16x16x32_bf16 v[24:27], v[124:127], v[186:189], v[24:27]
	v_mfma_f32_16x16x32_bf16 v[28:31], v[174:177], v[186:189], v[28:31]
	v_mfma_f32_16x16x32_bf16 v[186:189], v[124:127], v[200:203], v[32:35]
	v_mfma_f32_16x16x32_bf16 v[32:35], v[170:173], v[196:199], v[100:103]
	v_mfma_f32_16x16x32_bf16 v[16:19], v[120:123], v[204:207], v[16:19]
	v_mfma_f32_16x16x32_bf16 v[8:11], v[124:127], v[36:39], v[8:11]
	v_mfma_f32_16x16x32_bf16 v[12:15], v[174:177], v[36:39], v[12:15]
	v_mfma_f32_16x16x32_bf16 v[196:199], v[174:177], v[200:203], v[32:35]
	v_mfma_f32_16x16x32_bf16 v[200:203], v[124:127], v[208:211], v[16:19]
	v_mfma_f32_16x16x32_bf16 v[16:19], v[170:173], v[204:207], v[20:23]
	v_mfma_f32_16x16x32_bf16 v[170:173], v[174:177], v[208:211], v[16:19]
	s_barrier
	ds_read_b128 v[60:63], v224
	ds_read_b128 v[174:177], v224 offset:1024
	ds_read_b128 v[204:207], v224 offset:2048
	ds_read_b128 v[208:211], v224 offset:3072
	ds_read_b128 v[212:215], v228
	ds_read_b128 v[220:223], v228 offset:1024
	ds_read_b128 v[224:227], v228 offset:2048
	ds_read_b128 v[228:231], v228 offset:3072
	s_add_u32 s38, s50, 0x10000
	s_addc_u32 s39, s51, 0
	s_mov_b32 m0, s33
	ds_read_b128 v[16:19], v145 offset:32768
	ds_read_b128 v[20:23], v145 offset:33792
	ds_read_b128 v[108:111], v145 offset:34816
	ds_read_b128 v[232:235], v145 offset:35840
	ds_read_b128 v[236:239], v145 offset:36864
	ds_read_b128 v[240:243], v145 offset:37888
	ds_read_b128 v[244:247], v145 offset:38912
	ds_read_b128 v[248:251], v145 offset:39936
	global_load_lds_dwordx4 v128, s[38:39]
	s_mov_b32 m0, s42
	s_nop 0
	global_load_lds_dwordx4 v132, s[38:39]
	s_waitcnt vmcnt(8)
	s_waitcnt lgkmcnt(0)
	s_barrier
; #define PG8_STAGE(bufoff, gbase, voff) do { _Pragma("unroll") for (int _i = 0; _i < 2; ++_i) \
;         __builtin_amdgcn_global_load_lds((const unsigned*)((const char*)(gbase) + (voff)[_i]), (PG8_LAS unsigned*)(lds + (bufoff) + ldsw + _i * 8192), 16, 0, 0); } while (0)
; #define PG8_LDA(dst, b, h) do { _Pragma("unroll") for (int m = 0; m < 4; ++m) _Pragma("unroll") for (int k = 0; k < 2; ++k) dst[m][k] = *(const PG8_LAS bf16x8*)(lds + PG8_SA(b, h) + aoff + m * 2048 + k * 1024); } while (0)
; #define PG8_MMA(ai, bj, At, Bt) do { __builtin_amdgcn_s_setprio(1); _Pragma("unroll") for (int m = 0; m < 4; ++m) _Pragma("unroll") for (int n = 0; n < 2; ++n) _Pragma("unroll") for (int k = 0; k < 2; ++k) \
;         acc[ai][bj][m][n] = __builtin_amdgcn_mfma_f32_16x16x32_bf16(Bt[n][k], At[m][k], acc[ai][bj][m][n], 0, 0, 0); __builtin_amdgcn_s_setprio(0); } while (0)
; #define PG8_WAIT_V(n) asm volatile("s_waitcnt vmcnt(" #n ")" ::: "memory")
; #define PG8_WAIT_L(n) asm volatile("s_waitcnt lgkmcnt(" #n ")" ::: "memory")
; #define PG8_BAR __builtin_amdgcn_s_barrier()
; #define PG8_SCHED __builtin_amdgcn_sched_barrier(0)
; template <class Epi, class Sched, bool ALIGN_EPI = false, bool SP2 = false>
; __device__ __forceinline__ void gemm_phase(PG8_LAS unsigned char* lds, const Gemm g, const Sched& S, const Epi& E) {
;     ...
;             PG8_LDA(At, 1, 1); PG8_STAGE(PG8_SB(1, 0), b3, voffB); PG8_STAGE(PG8_SB(1, 1), b3 + hstepB, voffB); PG8_STAGE(PG8_SA(1, 0), a3, voffA);
;             PG8_WAIT_V(8); PG8_WAIT_L(0); PG8_BAR; PG8_MMA(1, 0, At, B0); PG8_MMA(1, 1, At, B1); PG8_BAR; PG8_SCHED;
;     ...
;         if constexpr (ALIGN_EPI) { if (wr == 0) PG8_BAR; }
	s_waitcnt lgkmcnt(0)
	v_mfma_f32_16x16x32_bf16 v[32:35], v[60:63], v[16:19], v[64:67]
	v_mfma_f32_16x16x32_bf16 v[112:115], v[174:177], v[20:23], v[32:35]
	v_mfma_f32_16x16x32_bf16 v[32:35], v[204:207], v[16:19], v[68:71]
	v_mfma_f32_16x16x32_bf16 v[116:119], v[208:211], v[20:23], v[32:35]
	v_mfma_f32_16x16x32_bf16 v[32:35], v[60:63], v[108:111], v[72:75]
	v_mfma_f32_16x16x32_bf16 v[96:99], v[174:177], v[232:235], v[32:35]
	v_mfma_f32_16x16x32_bf16 v[32:35], v[204:207], v[108:111], v[76:79]
	v_mfma_f32_16x16x32_bf16 v[100:103], v[208:211], v[232:235], v[32:35]
	v_mfma_f32_16x16x32_bf16 v[32:35], v[60:63], v[236:239], v[80:83]
	v_mfma_f32_16x16x32_bf16 v[64:67], v[174:177], v[240:243], v[32:35]
	v_mfma_f32_16x16x32_bf16 v[32:35], v[204:207], v[236:239], v[84:87]
	v_mfma_f32_16x16x32_bf16 v[68:71], v[208:211], v[240:243], v[32:35]
	v_mfma_f32_16x16x32_bf16 v[32:35], v[60:63], v[244:247], v[88:91]
	v_mfma_f32_16x16x32_bf16 v[36:39], v[204:207], v[244:247], v[92:95]
	v_mfma_f32_16x16x32_bf16 v[32:35], v[174:177], v[248:251], v[32:35]
	v_mfma_f32_16x16x32_bf16 v[36:39], v[208:211], v[248:251], v[36:39]
	v_mfma_f32_16x16x32_bf16 v[72:75], v[212:215], v[16:19], v[216:219]
	v_mfma_f32_16x16x32_bf16 v[16:19], v[224:227], v[16:19], v[178:181]
	v_mfma_f32_16x16x32_bf16 v[124:127], v[228:231], v[20:23], v[16:19]
	v_mfma_f32_16x16x32_bf16 v[16:19], v[212:215], v[108:111], v[182:185]
	v_mfma_f32_16x16x32_bf16 v[104:107], v[220:223], v[232:235], v[16:19]
	v_mfma_f32_16x16x32_bf16 v[16:19], v[224:227], v[108:111], v[40:43]
	v_mfma_f32_16x16x32_bf16 v[108:111], v[228:231], v[232:235], v[16:19]
	v_mfma_f32_16x16x32_bf16 v[16:19], v[212:215], v[236:239], v[44:47]
	v_mfma_f32_16x16x32_bf16 v[120:123], v[220:223], v[20:23], v[72:75]
	v_mfma_f32_16x16x32_bf16 v[72:75], v[220:223], v[240:243], v[16:19]
	v_mfma_f32_16x16x32_bf16 v[16:19], v[224:227], v[236:239], v[48:51]
	v_mfma_f32_16x16x32_bf16 v[76:79], v[228:231], v[240:243], v[16:19]
	v_mfma_f32_16x16x32_bf16 v[16:19], v[212:215], v[244:247], v[52:55]
	v_mfma_f32_16x16x32_bf16 v[40:43], v[220:223], v[248:251], v[16:19]
	v_mfma_f32_16x16x32_bf16 v[16:19], v[224:227], v[244:247], v[56:59]
	v_mfma_f32_16x16x32_bf16 v[44:47], v[228:231], v[248:251], v[16:19]
	s_barrier
	s_mov_b32 m0, s64
	s_nop 3
	s_add_u32 s38, s46, 0x10080
	ds_read_b128 v[56:59], v145 offset:49152
	ds_read_b128 v[92:95], v145 offset:50176
	ds_read_b128 v[178:181], v145 offset:51200
	ds_read_b128 v[182:185], v145 offset:52224
	ds_read_b128 v[216:219], v145 offset:53248
	ds_read_b128 v[232:235], v145 offset:54272
	ds_read_b128 v[236:239], v145 offset:55296
	ds_read_b128 v[240:243], v145 offset:56320
	global_load_lds_dwordx4 v130, s[98:99]
	s_mov_b32 m0, s49
	s_addc_u32 s39, s47, 0
	global_load_lds_dwordx4 v134, s[98:99]
	s_mov_b32 m0, s40
	s_nop 0
	global_load_lds_dwordx4 v130, s[38:39]
	s_mov_b32 m0, s41
	s_nop 0
	global_load_lds_dwordx4 v134, s[38:39]
	s_mov_b32 m0, s53
	s_nop 0
	global_load_lds_dwordx4 v128, s[100:101]
	s_mov_b32 m0, s56
	s_nop 0
	global_load_lds_dwordx4 v132, s[100:101]
	s_waitcnt vmcnt(8)
	s_waitcnt lgkmcnt(0)
	s_barrier
	s_waitcnt lgkmcnt(0)
	v_mfma_f32_16x16x32_bf16 v[16:19], v[60:63], v[56:59], v[146:149]
	v_mfma_f32_16x16x32_bf16 v[80:83], v[174:177], v[92:95], v[16:19]
	v_mfma_f32_16x16x32_bf16 v[16:19], v[204:207], v[56:59], v[150:153]
	v_mfma_f32_16x16x32_bf16 v[84:87], v[208:211], v[92:95], v[16:19]
	v_mfma_f32_16x16x32_bf16 v[16:19], v[60:63], v[178:181], v[154:157]
	v_mfma_f32_16x16x32_bf16 v[48:51], v[174:177], v[182:185], v[16:19]
	v_mfma_f32_16x16x32_bf16 v[16:19], v[204:207], v[178:181], v[158:161]
	v_mfma_f32_16x16x32_bf16 v[52:55], v[208:211], v[182:185], v[16:19]
	v_mfma_f32_16x16x32_bf16 v[16:19], v[60:63], v[216:219], v[162:165]
	v_mfma_f32_16x16x32_bf16 v[20:23], v[204:207], v[216:219], v[166:169]
	v_mfma_f32_16x16x32_bf16 v[0:3], v[60:63], v[236:239], v[0:3]
	v_mfma_f32_16x16x32_bf16 v[4:7], v[204:207], v[236:239], v[4:7]
	v_mfma_f32_16x16x32_bf16 v[16:19], v[174:177], v[232:235], v[16:19]
	v_mfma_f32_16x16x32_bf16 v[20:23], v[208:211], v[232:235], v[20:23]
	v_mfma_f32_16x16x32_bf16 v[0:3], v[174:177], v[240:243], v[0:3]
	v_mfma_f32_16x16x32_bf16 v[4:7], v[208:211], v[240:243], v[4:7]
	v_mfma_f32_16x16x32_bf16 v[8:11], v[212:215], v[56:59], v[8:11]
	v_mfma_f32_16x16x32_bf16 v[88:91], v[220:223], v[92:95], v[8:11]
	v_mfma_f32_16x16x32_bf16 v[8:11], v[224:227], v[56:59], v[12:15]
	v_mfma_f32_16x16x32_bf16 v[92:95], v[228:231], v[92:95], v[8:11]
	v_mfma_f32_16x16x32_bf16 v[8:11], v[212:215], v[178:181], v[24:27]
	v_mfma_f32_16x16x32_bf16 v[56:59], v[220:223], v[182:185], v[8:11]
	v_mfma_f32_16x16x32_bf16 v[8:11], v[224:227], v[178:181], v[28:31]
	v_mfma_f32_16x16x32_bf16 v[60:63], v[228:231], v[182:185], v[8:11]
	v_mfma_f32_16x16x32_bf16 v[8:11], v[212:215], v[216:219], v[186:189]
	v_mfma_f32_16x16x32_bf16 v[24:27], v[220:223], v[232:235], v[8:11]
	v_mfma_f32_16x16x32_bf16 v[8:11], v[224:227], v[216:219], v[196:199]
	v_mfma_f32_16x16x32_bf16 v[28:31], v[228:231], v[232:235], v[8:11]
	v_mfma_f32_16x16x32_bf16 v[8:11], v[212:215], v[236:239], v[200:203]
	v_mfma_f32_16x16x32_bf16 v[12:15], v[224:227], v[236:239], v[170:173]
	v_mfma_f32_16x16x32_bf16 v[8:11], v[220:223], v[240:243], v[8:11]
	v_mfma_f32_16x16x32_bf16 v[12:15], v[228:231], v[240:243], v[12:15]
	s_barrier
	s_andn2_b64 vcc, exec, s[18:19]
	s_cbranch_vccnz .LBB0_165
	s_barrier

; #define PG8_STAGE(bufoff, gbase, voff) do { _Pragma("unroll") for (int _i = 0; _i < 2; ++_i) \
;         __builtin_amdgcn_global_load_lds((const unsigned*)((const char*)(gbase) + (voff)[_i]), (PG8_LAS unsigned*)(lds + (bufoff) + ldsw + _i * 8192), 16, 0, 0); } while (0)
; #define PG8_LDA(dst, b, h) do { _Pragma("unroll") for (int m = 0; m < 4; ++m) _Pragma("unroll") for (int k = 0; k < 2; ++k) dst[m][k] = *(const PG8_LAS bf16x8*)(lds + PG8_SA(b, h) + aoff + m * 2048 + k * 1024); } while (0)
; #define PG8_LDB(dst, b, h) do { _Pragma("unroll") for (int n = 0; n < 2; ++n) _Pragma("unroll") for (int k = 0; k < 2; ++k) dst[n][k] = *(const PG8_LAS bf16x8*)(lds + PG8_SB(b, h) + boff + n * 2048 + k * 1024); } while (0)
; #define PG8_MMA(ai, bj, At, Bt) do { __builtin_amdgcn_s_setprio(1); _Pragma("unroll") for (int m = 0; m < 4; ++m) _Pragma("unroll") for (int n = 0; n < 2; ++n) _Pragma("unroll") for (int k = 0; k < 2; ++k) \
;         acc[ai][bj][m][n] = __builtin_amdgcn_mfma_f32_16x16x32_bf16(Bt[n][k], At[m][k], acc[ai][bj][m][n], 0, 0, 0); __builtin_amdgcn_s_setprio(0); } while (0)
; #define PG8_WAIT_V(n) asm volatile("s_waitcnt vmcnt(" #n ")" ::: "memory")
; #define PG8_WAIT_L(n) asm volatile("s_waitcnt lgkmcnt(" #n ")" ::: "memory")
; #define PG8_BAR __builtin_amdgcn_s_barrier()
; template <class Epi, class Sched, bool ALIGN_EPI = false, bool SP2 = false>
; __device__ __forceinline__ void gemm_phase(PG8_LAS unsigned char* lds, const Gemm g, const Sched& S, const Epi& E) {
;     ...
;             const char* a1 = cA + (size_t)(t + 1) * kstep;
;             const char* a2 = last ? nA : cA + (size_t)(t + 2) * kstep; const char* b2 = last ? nB : cB + (size_t)(t + 2) * kstep;
;             const char* a3 = a2 + kstep; const char* b3 = b2 + kstep;
;             if (last && has_next) S.a_ready(nxt);
;             if constexpr (SP2) {
;             PG8_LDB(B0, 0, 0); PG8_LDB(B1, 0, 1); PG8_SCHED; PG8_LDA(At, 0, 0); PG8_STAGE(PG8_SA(1, 1), a1 + hstepA, voffA);
;             PG8_WAIT_V(8); PG8_WAIT_L(0); PG8_BAR; PG8_MMA(0, 0, At, B0); PG8_MMA(0, 1, At, B1); PG8_BAR; PG8_SCHED;
;             PG8_LDA(At, 0, 1); PG8_STAGE(PG8_SB(0, 0), b2, voffB); PG8_STAGE(PG8_SB(0, 1), b2 + hstepB, voffB); PG8_STAGE(PG8_SA(0, 0), a2, voffA);
;             PG8_WAIT_V(8); PG8_WAIT_L(0); PG8_BAR; PG8_MMA(1, 0, At, B0); PG8_MMA(1, 1, At, B1); PG8_BAR; PG8_SCHED;
.LBB0_186:
	ds_read_b128 v[150:153], v147
	ds_read_b128 v[154:157], v147 offset:1024
	ds_read_b128 v[158:161], v147 offset:2048
	ds_read_b128 v[162:165], v147 offset:3072
	ds_read_b128 v[166:169], v148
	ds_read_b128 v[170:173], v148 offset:1024
	ds_read_b128 v[174:177], v148 offset:2048
	ds_read_b128 v[178:181], v148 offset:3072
	s_add_u32 s36, s34, 0xfffc0080
	s_addc_u32 s37, s35, -1
	s_cmp_eq_u32 s64, 12
	s_cselect_b32 s39, s27, s37
	s_cselect_b32 s38, s60, s36
	s_cselect_b32 s37, s25, s63
	s_cselect_b32 s36, s61, s62
	s_add_i32 m0, s8, 0xc000
	ds_read_b128 v[182:185], v149
	ds_read_b128 v[186:189], v149 offset:1024
	ds_read_b128 v[196:199], v149 offset:2048
	ds_read_b128 v[200:203], v149 offset:3072
	ds_read_b128 v[204:207], v149 offset:4096
	ds_read_b128 v[208:211], v149 offset:5120
	ds_read_b128 v[212:215], v149 offset:6144
	ds_read_b128 v[216:219], v149 offset:7168
	global_load_lds_dwordx4 v136, s[34:35]
	s_add_i32 m0, s8, 0xe000
	s_nop 0
	global_load_lds_dwordx4 v138, s[34:35]
	s_waitcnt vmcnt(8)
	s_waitcnt lgkmcnt(0)
	s_barrier
	s_waitcnt lgkmcnt(0)
	v_mfma_f32_16x16x32_bf16 v[124:127], v[150:153], v[182:185], v[124:127]
	v_mfma_f32_16x16x32_bf16 v[120:123], v[158:161], v[182:185], v[120:123]
	v_mfma_f32_16x16x32_bf16 v[116:119], v[150:153], v[196:199], v[116:119]
	v_mfma_f32_16x16x32_bf16 v[112:115], v[158:161], v[196:199], v[112:115]
	v_mfma_f32_16x16x32_bf16 v[100:103], v[150:153], v[204:207], v[100:103]
	v_mfma_f32_16x16x32_bf16 v[96:99], v[158:161], v[204:207], v[96:99]
	v_mfma_f32_16x16x32_bf16 v[84:87], v[150:153], v[212:215], v[84:87]
	v_mfma_f32_16x16x32_bf16 v[80:83], v[158:161], v[212:215], v[80:83]
	v_mfma_f32_16x16x32_bf16 v[124:127], v[154:157], v[186:189], v[124:127]
	v_mfma_f32_16x16x32_bf16 v[120:123], v[162:165], v[186:189], v[120:123]
	v_mfma_f32_16x16x32_bf16 v[116:119], v[154:157], v[200:203], v[116:119]
	v_mfma_f32_16x16x32_bf16 v[112:115], v[162:165], v[200:203], v[112:115]
	v_mfma_f32_16x16x32_bf16 v[100:103], v[154:157], v[208:211], v[100:103]
	v_mfma_f32_16x16x32_bf16 v[96:99], v[162:165], v[208:211], v[96:99]
	v_mfma_f32_16x16x32_bf16 v[84:87], v[154:157], v[216:219], v[84:87]
	v_mfma_f32_16x16x32_bf16 v[80:83], v[162:165], v[216:219], v[80:83]
	v_mfma_f32_16x16x32_bf16 v[108:111], v[166:169], v[182:185], v[108:111]
	v_mfma_f32_16x16x32_bf16 v[104:107], v[174:177], v[182:185], v[104:107]
	v_mfma_f32_16x16x32_bf16 v[92:95], v[166:169], v[196:199], v[92:95]
	v_mfma_f32_16x16x32_bf16 v[88:91], v[174:177], v[196:199], v[88:91]
	v_mfma_f32_16x16x32_bf16 v[76:79], v[166:169], v[204:207], v[76:79]
	v_mfma_f32_16x16x32_bf16 v[72:75], v[174:177], v[204:207], v[72:75]
	v_mfma_f32_16x16x32_bf16 v[68:71], v[166:169], v[212:215], v[68:71]
	v_mfma_f32_16x16x32_bf16 v[64:67], v[174:177], v[212:215], v[64:67]
	v_mfma_f32_16x16x32_bf16 v[108:111], v[170:173], v[186:189], v[108:111]
	v_mfma_f32_16x16x32_bf16 v[104:107], v[178:181], v[186:189], v[104:107]
	v_mfma_f32_16x16x32_bf16 v[92:95], v[170:173], v[200:203], v[92:95]
	v_mfma_f32_16x16x32_bf16 v[88:91], v[178:181], v[200:203], v[88:91]
	v_mfma_f32_16x16x32_bf16 v[76:79], v[170:173], v[208:211], v[76:79]
	v_mfma_f32_16x16x32_bf16 v[72:75], v[178:181], v[208:211], v[72:75]
	v_mfma_f32_16x16x32_bf16 v[68:71], v[170:173], v[216:219], v[68:71]
	v_mfma_f32_16x16x32_bf16 v[64:67], v[178:181], v[216:219], v[64:67]
	s_barrier
	s_add_i32 s44, s53, s3
	s_add_u32 s98, s36, s16
	s_addc_u32 s99, s37, s17
	s_mov_b32 m0, s44
	ds_read_b128 v[182:185], v149 offset:16384
	ds_read_b128 v[186:189], v149 offset:17408
	ds_read_b128 v[196:199], v149 offset:18432
	ds_read_b128 v[200:203], v149 offset:19456
	ds_read_b128 v[204:207], v149 offset:20480
	ds_read_b128 v[208:211], v149 offset:21504
	ds_read_b128 v[212:215], v149 offset:22528
	ds_read_b128 v[216:219], v149 offset:23552
	global_load_lds_dwordx4 v130, s[36:37]
	s_add_i32 m0, s44, 0x2000
	s_add_u32 s44, s36, 0x40000
	s_addc_u32 s45, s37, 0
	s_add_u32 s98, s36, s16
	s_addc_u32 s99, s37, s17
	s_add_i32 s48, s56, s3
	global_load_lds_dwordx4 v134, s[36:37]
	s_mov_b32 m0, s48
	v_lshl_add_u64 v[220:221], s[38:39], 0, v[132:133]
	global_load_lds_dwordx4 v130, s[44:45]
	s_add_i32 m0, s48, 0x2000
	s_nop 0
	global_load_lds_dwordx4 v134, s[44:45]
	s_add_u32 s100, s38, s16
	s_addc_u32 s101, s39, s17
	s_mov_b32 m0, s8
	s_nop 0
	global_load_lds_dwordx4 v128, s[38:39]
	s_mov_b32 m0, s9
	s_nop 0
	global_load_lds_dwordx4 v[220:221], off
	s_waitcnt vmcnt(8)
	s_waitcnt lgkmcnt(0)
	s_barrier
	s_waitcnt lgkmcnt(0)
	v_mfma_f32_16x16x32_bf16 v[60:63], v[150:153], v[182:185], v[60:63]
	v_mfma_f32_16x16x32_bf16 v[56:59], v[158:161], v[182:185], v[56:59]
	v_mfma_f32_16x16x32_bf16 v[52:55], v[150:153], v[196:199], v[52:55]
	v_mfma_f32_16x16x32_bf16 v[48:51], v[158:161], v[196:199], v[48:51]
	v_mfma_f32_16x16x32_bf16 v[36:39], v[150:153], v[204:207], v[36:39]
	v_mfma_f32_16x16x32_bf16 v[32:35], v[158:161], v[204:207], v[32:35]
	v_mfma_f32_16x16x32_bf16 v[20:23], v[150:153], v[212:215], v[20:23]
	v_mfma_f32_16x16x32_bf16 v[16:19], v[158:161], v[212:215], v[16:19]
	v_mfma_f32_16x16x32_bf16 v[60:63], v[154:157], v[186:189], v[60:63]
	v_mfma_f32_16x16x32_bf16 v[56:59], v[162:165], v[186:189], v[56:59]
	v_mfma_f32_16x16x32_bf16 v[52:55], v[154:157], v[200:203], v[52:55]
	v_mfma_f32_16x16x32_bf16 v[48:51], v[162:165], v[200:203], v[48:51]
	v_mfma_f32_16x16x32_bf16 v[36:39], v[154:157], v[208:211], v[36:39]
	v_mfma_f32_16x16x32_bf16 v[32:35], v[162:165], v[208:211], v[32:35]
	v_mfma_f32_16x16x32_bf16 v[20:23], v[154:157], v[216:219], v[20:23]
	v_mfma_f32_16x16x32_bf16 v[16:19], v[162:165], v[216:219], v[16:19]
	v_mfma_f32_16x16x32_bf16 v[44:47], v[166:169], v[182:185], v[44:47]
	v_mfma_f32_16x16x32_bf16 v[40:43], v[174:177], v[182:185], v[40:43]
	v_mfma_f32_16x16x32_bf16 v[28:31], v[166:169], v[196:199], v[28:31]
	v_mfma_f32_16x16x32_bf16 v[24:27], v[174:177], v[196:199], v[24:27]
	v_mfma_f32_16x16x32_bf16 v[12:15], v[166:169], v[204:207], v[12:15]
	v_mfma_f32_16x16x32_bf16 v[8:11], v[174:177], v[204:207], v[8:11]
	v_mfma_f32_16x16x32_bf16 v[4:7], v[166:169], v[212:215], v[4:7]
	v_mfma_f32_16x16x32_bf16 v[0:3], v[174:177], v[212:215], v[0:3]
	v_mfma_f32_16x16x32_bf16 v[44:47], v[170:173], v[186:189], v[44:47]
	v_mfma_f32_16x16x32_bf16 v[40:43], v[178:181], v[186:189], v[40:43]
	v_mfma_f32_16x16x32_bf16 v[28:31], v[170:173], v[200:203], v[28:31]
	v_mfma_f32_16x16x32_bf16 v[24:27], v[178:181], v[200:203], v[24:27]
	v_mfma_f32_16x16x32_bf16 v[12:15], v[170:173], v[208:211], v[12:15]
	v_mfma_f32_16x16x32_bf16 v[8:11], v[178:181], v[208:211], v[8:11]
	v_mfma_f32_16x16x32_bf16 v[4:7], v[170:173], v[216:219], v[4:7]
	v_mfma_f32_16x16x32_bf16 v[0:3], v[178:181], v[216:219], v[0:3]
	s_barrier
; #define PG8_STAGE(bufoff, gbase, voff) do { _Pragma("unroll") for (int _i = 0; _i < 2; ++_i) \
;         __builtin_amdgcn_global_load_lds((const unsigned*)((const char*)(gbase) + (voff)[_i]), (PG8_LAS unsigned*)(lds + (bufoff) + ldsw + _i * 8192), 16, 0, 0); } while (0)
; #define PG8_LDA(dst, b, h) do { _Pragma("unroll") for (int m = 0; m < 4; ++m) _Pragma("unroll") for (int k = 0; k < 2; ++k) dst[m][k] = *(const PG8_LAS bf16x8*)(lds + PG8_SA(b, h) + aoff + m * 2048 + k * 1024); } while (0)
; #define PG8_LDB(dst, b, h) do { _Pragma("unroll") for (int n = 0; n < 2; ++n) _Pragma("unroll") for (int k = 0; k < 2; ++k) dst[n][k] = *(const PG8_LAS bf16x8*)(lds + PG8_SB(b, h) + boff + n * 2048 + k * 1024); } while (0)
; #define PG8_MMA(ai, bj, At, Bt) do { __builtin_amdgcn_s_setprio(1); _Pragma("unroll") for (int m = 0; m < 4; ++m) _Pragma("unroll") for (int n = 0; n < 2; ++n) _Pragma("unroll") for (int k = 0; k < 2; ++k) \
;         acc[ai][bj][m][n] = __builtin_amdgcn_mfma_f32_16x16x32_bf16(Bt[n][k], At[m][k], acc[ai][bj][m][n], 0, 0, 0); __builtin_amdgcn_s_setprio(0); } while (0)
; #define PG8_WAIT_V(n) asm volatile("s_waitcnt vmcnt(" #n ")" ::: "memory")
; #define PG8_WAIT_L(n) asm volatile("s_waitcnt lgkmcnt(" #n ")" ::: "memory")
; #define PG8_BAR __builtin_amdgcn_s_barrier()
; #define PG8_SCHED __builtin_amdgcn_sched_barrier(0)
; template <class Epi, class Sched, bool ALIGN_EPI = false, bool SP2 = false>
; __device__ __forceinline__ void gemm_phase(PG8_LAS unsigned char* lds, const Gemm g, const Sched& S, const Epi& E) {
;     ...
;             PG8_LDB(B0, 1, 0); PG8_LDB(B1, 1, 1); PG8_SCHED; PG8_LDA(At, 1, 0); PG8_STAGE(PG8_SA(0, 1), a2 + hstepA, voffA);
;             PG8_WAIT_V(8); PG8_WAIT_L(0); PG8_BAR; PG8_MMA(0, 0, At, B0); PG8_MMA(0, 1, At, B1); PG8_BAR; PG8_SCHED;
;             PG8_LDA(At, 1, 1); PG8_STAGE(PG8_SB(1, 0), b3, voffB); PG8_STAGE(PG8_SB(1, 1), b3 + hstepB, voffB); PG8_STAGE(PG8_SA(1, 0), a3, voffA);
;             PG8_WAIT_V(8); PG8_WAIT_L(0); PG8_BAR; PG8_MMA(1, 0, At, B0); PG8_MMA(1, 1, At, B1); PG8_BAR; PG8_SCHED;
	s_add_i32 s44, 0, 0x18000
	s_add_i32 s45, 0, 0x1c000
	v_add_u32_e32 v162, s44, v146
	v_add_u32_e32 v178, s45, v146
	ds_read_b128 v[150:153], v162
	ds_read_b128 v[154:157], v162 offset:1024
	ds_read_b128 v[158:161], v162 offset:2048
	ds_read_b128 v[162:165], v162 offset:3072
	ds_read_b128 v[166:169], v178
	ds_read_b128 v[170:173], v178 offset:1024
	ds_read_b128 v[174:177], v178 offset:2048
	ds_read_b128 v[178:181], v178 offset:3072
	s_add_u32 s38, s38, 0x40000
	s_addc_u32 s39, s39, 0
	s_mov_b32 m0, s23
	ds_read_b128 v[182:185], v149 offset:32768
	ds_read_b128 v[186:189], v149 offset:33792
	ds_read_b128 v[196:199], v149 offset:34816
	ds_read_b128 v[200:203], v149 offset:35840
	ds_read_b128 v[204:207], v149 offset:36864
	ds_read_b128 v[208:211], v149 offset:37888
	ds_read_b128 v[212:215], v149 offset:38912
	ds_read_b128 v[216:219], v149 offset:39936
	global_load_lds_dwordx4 v128, s[38:39]
	s_mov_b32 m0, s33
	s_nop 0
	global_load_lds_dwordx4 v132, s[38:39]
	s_waitcnt vmcnt(8)
	s_waitcnt lgkmcnt(0)
	s_barrier
	s_waitcnt lgkmcnt(0)
	v_mfma_f32_16x16x32_bf16 v[124:127], v[150:153], v[182:185], v[124:127]
	v_mfma_f32_16x16x32_bf16 v[120:123], v[158:161], v[182:185], v[120:123]
	v_mfma_f32_16x16x32_bf16 v[116:119], v[150:153], v[196:199], v[116:119]
	v_mfma_f32_16x16x32_bf16 v[112:115], v[158:161], v[196:199], v[112:115]
	v_mfma_f32_16x16x32_bf16 v[100:103], v[150:153], v[204:207], v[100:103]
	v_mfma_f32_16x16x32_bf16 v[96:99], v[158:161], v[204:207], v[96:99]
	v_mfma_f32_16x16x32_bf16 v[84:87], v[150:153], v[212:215], v[84:87]
	v_mfma_f32_16x16x32_bf16 v[80:83], v[158:161], v[212:215], v[80:83]
	v_mfma_f32_16x16x32_bf16 v[124:127], v[154:157], v[186:189], v[124:127]
	v_mfma_f32_16x16x32_bf16 v[120:123], v[162:165], v[186:189], v[120:123]
	v_mfma_f32_16x16x32_bf16 v[116:119], v[154:157], v[200:203], v[116:119]
	v_mfma_f32_16x16x32_bf16 v[112:115], v[162:165], v[200:203], v[112:115]
	v_mfma_f32_16x16x32_bf16 v[100:103], v[154:157], v[208:211], v[100:103]
	v_mfma_f32_16x16x32_bf16 v[96:99], v[162:165], v[208:211], v[96:99]
	v_mfma_f32_16x16x32_bf16 v[84:87], v[154:157], v[216:219], v[84:87]
	v_mfma_f32_16x16x32_bf16 v[80:83], v[162:165], v[216:219], v[80:83]
	v_mfma_f32_16x16x32_bf16 v[108:111], v[166:169], v[182:185], v[108:111]
	v_mfma_f32_16x16x32_bf16 v[104:107], v[174:177], v[182:185], v[104:107]
	v_mfma_f32_16x16x32_bf16 v[92:95], v[166:169], v[196:199], v[92:95]
	v_mfma_f32_16x16x32_bf16 v[88:91], v[174:177], v[196:199], v[88:91]
	v_mfma_f32_16x16x32_bf16 v[76:79], v[166:169], v[204:207], v[76:79]
	v_mfma_f32_16x16x32_bf16 v[72:75], v[174:177], v[204:207], v[72:75]
	v_mfma_f32_16x16x32_bf16 v[68:71], v[166:169], v[212:215], v[68:71]
	v_mfma_f32_16x16x32_bf16 v[64:67], v[174:177], v[212:215], v[64:67]
	v_mfma_f32_16x16x32_bf16 v[108:111], v[170:173], v[186:189], v[108:111]
	v_mfma_f32_16x16x32_bf16 v[104:107], v[178:181], v[186:189], v[104:107]
	v_mfma_f32_16x16x32_bf16 v[92:95], v[170:173], v[200:203], v[92:95]
	v_mfma_f32_16x16x32_bf16 v[88:91], v[178:181], v[200:203], v[88:91]
	v_mfma_f32_16x16x32_bf16 v[76:79], v[170:173], v[208:211], v[76:79]
	v_mfma_f32_16x16x32_bf16 v[72:75], v[178:181], v[208:211], v[72:75]
	v_mfma_f32_16x16x32_bf16 v[68:71], v[170:173], v[216:219], v[68:71]
	v_mfma_f32_16x16x32_bf16 v[64:67], v[178:181], v[216:219], v[64:67]
	s_barrier
	s_add_i32 s38, s44, s3
	s_mov_b32 m0, s38
	ds_read_b128 v[182:185], v149 offset:49152
	ds_read_b128 v[186:189], v149 offset:50176
	ds_read_b128 v[196:199], v149 offset:51200
	ds_read_b128 v[200:203], v149 offset:52224
	ds_read_b128 v[204:207], v149 offset:53248
	ds_read_b128 v[208:211], v149 offset:54272
	ds_read_b128 v[212:215], v149 offset:55296
	ds_read_b128 v[216:219], v149 offset:56320
	global_load_lds_dwordx4 v130, s[98:99]
	s_add_i32 m0, s38, 0x2000
	s_add_u32 s36, s36, 0x40080
	s_addc_u32 s37, s37, 0
	s_add_i32 s38, s45, s3
	global_load_lds_dwordx4 v134, s[98:99]
	s_mov_b32 m0, s38
	s_nop 0
	global_load_lds_dwordx4 v130, s[36:37]
	s_add_i32 m0, s38, 0x2000
	s_nop 0
	global_load_lds_dwordx4 v134, s[36:37]
	s_mov_b32 m0, s43
	s_nop 0
	global_load_lds_dwordx4 v128, s[100:101]
	v_lshl_add_u64 v[190:191], v[220:221], 0, s[16:17]
	s_mov_b32 m0, s50
	s_nop 0
	global_load_lds_dwordx4 v[190:191], off
	s_waitcnt vmcnt(8)
	s_waitcnt lgkmcnt(0)
	s_barrier
	s_waitcnt lgkmcnt(0)
	v_mfma_f32_16x16x32_bf16 v[60:63], v[150:153], v[182:185], v[60:63]
	v_mfma_f32_16x16x32_bf16 v[56:59], v[158:161], v[182:185], v[56:59]
	v_mfma_f32_16x16x32_bf16 v[52:55], v[150:153], v[196:199], v[52:55]
	v_mfma_f32_16x16x32_bf16 v[48:51], v[158:161], v[196:199], v[48:51]
	v_mfma_f32_16x16x32_bf16 v[36:39], v[150:153], v[204:207], v[36:39]
	v_mfma_f32_16x16x32_bf16 v[32:35], v[158:161], v[204:207], v[32:35]
	v_mfma_f32_16x16x32_bf16 v[20:23], v[150:153], v[212:215], v[20:23]
	v_mfma_f32_16x16x32_bf16 v[16:19], v[158:161], v[212:215], v[16:19]
	v_mfma_f32_16x16x32_bf16 v[60:63], v[154:157], v[186:189], v[60:63]
	v_mfma_f32_16x16x32_bf16 v[56:59], v[162:165], v[186:189], v[56:59]
	v_mfma_f32_16x16x32_bf16 v[52:55], v[154:157], v[200:203], v[52:55]
	v_mfma_f32_16x16x32_bf16 v[48:51], v[162:165], v[200:203], v[48:51]
	v_mfma_f32_16x16x32_bf16 v[36:39], v[154:157], v[208:211], v[36:39]
	v_mfma_f32_16x16x32_bf16 v[32:35], v[162:165], v[208:211], v[32:35]
	v_mfma_f32_16x16x32_bf16 v[20:23], v[154:157], v[216:219], v[20:23]
	v_mfma_f32_16x16x32_bf16 v[16:19], v[162:165], v[216:219], v[16:19]
	v_mfma_f32_16x16x32_bf16 v[44:47], v[166:169], v[182:185], v[44:47]
	v_mfma_f32_16x16x32_bf16 v[40:43], v[174:177], v[182:185], v[40:43]
	v_mfma_f32_16x16x32_bf16 v[28:31], v[166:169], v[196:199], v[28:31]
	v_mfma_f32_16x16x32_bf16 v[24:27], v[174:177], v[196:199], v[24:27]
	v_mfma_f32_16x16x32_bf16 v[12:15], v[166:169], v[204:207], v[12:15]
	v_mfma_f32_16x16x32_bf16 v[8:11], v[174:177], v[204:207], v[8:11]
	v_mfma_f32_16x16x32_bf16 v[4:7], v[166:169], v[212:215], v[4:7]
	v_mfma_f32_16x16x32_bf16 v[0:3], v[174:177], v[212:215], v[0:3]
	v_mfma_f32_16x16x32_bf16 v[44:47], v[170:173], v[186:189], v[44:47]
	v_mfma_f32_16x16x32_bf16 v[40:43], v[178:181], v[186:189], v[40:43]
	v_mfma_f32_16x16x32_bf16 v[28:31], v[170:173], v[200:203], v[28:31]
	v_mfma_f32_16x16x32_bf16 v[24:27], v[178:181], v[200:203], v[24:27]
	v_mfma_f32_16x16x32_bf16 v[12:15], v[170:173], v[208:211], v[12:15]
	v_mfma_f32_16x16x32_bf16 v[8:11], v[178:181], v[208:211], v[8:11]
	v_mfma_f32_16x16x32_bf16 v[4:7], v[170:173], v[216:219], v[4:7]
	v_mfma_f32_16x16x32_bf16 v[0:3], v[178:181], v[216:219], v[0:3]
	s_barrier
	s_add_i32 s64, s64, 2
	s_add_u32 s34, s34, 0x100
	s_addc_u32 s35, s35, 0
	s_add_u32 s62, s62, 0x100
	s_addc_u32 s63, s63, 0
	s_cmp_gt_u32 s64, 13
	s_cbranch_scc0 .LBB0_186
	s_and_b64 vcc, exec, s[18:19]
	s_cbranch_vccz .LBB0_189
	s_barrier

; #define PG8_STAGE(bufoff, gbase, voff) do { _Pragma("unroll") for (int _i = 0; _i < 2; ++_i) \
;         __builtin_amdgcn_global_load_lds((const unsigned*)((const char*)(gbase) + (voff)[_i]), (PG8_LAS unsigned*)(lds + (bufoff) + ldsw + _i * 8192), 16, 0, 0); } while (0)
; #define PG8_LDA(dst, b, h) do { _Pragma("unroll") for (int m = 0; m < 4; ++m) _Pragma("unroll") for (int k = 0; k < 2; ++k) dst[m][k] = *(const PG8_LAS bf16x8*)(lds + PG8_SA(b, h) + aoff + m * 2048 + k * 1024); } while (0)
; #define PG8_LDB(dst, b, h) do { _Pragma("unroll") for (int n = 0; n < 2; ++n) _Pragma("unroll") for (int k = 0; k < 2; ++k) dst[n][k] = *(const PG8_LAS bf16x8*)(lds + PG8_SB(b, h) + boff + n * 2048 + k * 1024); } while (0)
; #define PG8_MMA(ai, bj, At, Bt) do { __builtin_amdgcn_s_setprio(1); _Pragma("unroll") for (int m = 0; m < 4; ++m) _Pragma("unroll") for (int n = 0; n < 2; ++n) _Pragma("unroll") for (int k = 0; k < 2; ++k) \
;         acc[ai][bj][m][n] = __builtin_amdgcn_mfma_f32_16x16x32_bf16(Bt[n][k], At[m][k], acc[ai][bj][m][n], 0, 0, 0); __builtin_amdgcn_s_setprio(0); } while (0)
; #define PG8_WAIT_V(n) asm volatile("s_waitcnt vmcnt(" #n ")" ::: "memory")
; #define PG8_WAIT_L(n) asm volatile("s_waitcnt lgkmcnt(" #n ")" ::: "memory")
; #define PG8_BAR __builtin_amdgcn_s_barrier()
; template <class Epi, class Sched, bool ALIGN_EPI = false, bool SP2 = false>
; __device__ __forceinline__ void gemm_phase(PG8_LAS unsigned char* lds, const Gemm g, const Sched& S, const Epi& E) {
;     ...
;             const char* a1 = cA + (size_t)(t + 1) * kstep;
;             const char* a2 = last ? nA : cA + (size_t)(t + 2) * kstep; const char* b2 = last ? nB : cB + (size_t)(t + 2) * kstep;
;             const char* a3 = a2 + kstep; const char* b3 = b2 + kstep;
;             if (last && has_next) S.a_ready(nxt);
;             if constexpr (SP2) {
;             PG8_LDB(B0, 0, 0); PG8_LDB(B1, 0, 1); PG8_SCHED; PG8_LDA(At, 0, 0); PG8_STAGE(PG8_SA(1, 1), a1 + hstepA, voffA);
;             PG8_WAIT_V(8); PG8_WAIT_L(0); PG8_BAR; PG8_MMA(0, 0, At, B0); PG8_MMA(0, 1, At, B1); PG8_BAR; PG8_SCHED;
;             PG8_LDA(At, 0, 1); PG8_STAGE(PG8_SB(0, 0), b2, voffB); PG8_STAGE(PG8_SB(0, 1), b2 + hstepB, voffB); PG8_STAGE(PG8_SA(0, 0), a2, voffA);
;             PG8_WAIT_V(8); PG8_WAIT_L(0); PG8_BAR; PG8_MMA(1, 0, At, B0); PG8_MMA(1, 1, At, B1); PG8_BAR; PG8_SCHED;
.LBB0_210:
	ds_read_b128 v[146:149], v143
	ds_read_b128 v[150:153], v143 offset:1024
	ds_read_b128 v[154:157], v143 offset:2048
	ds_read_b128 v[158:161], v143 offset:3072
	ds_read_b128 v[162:165], v144
	ds_read_b128 v[166:169], v144 offset:1024
	ds_read_b128 v[170:173], v144 offset:2048
	ds_read_b128 v[174:177], v144 offset:3072
	s_add_u32 s36, s34, 0xfffc0080
	s_addc_u32 s37, s35, -1
	s_cmp_eq_u32 s64, 12
	s_cselect_b32 s39, s25, s37
	s_cselect_b32 s38, s60, s36
	s_cselect_b32 s37, s23, s63
	s_cselect_b32 s36, s61, s62
	s_add_i32 m0, s31, 0xc000
	ds_read_b128 v[178:181], v145
	ds_read_b128 v[182:185], v145 offset:1024
	ds_read_b128 v[186:189], v145 offset:2048
	ds_read_b128 v[196:199], v145 offset:3072
	ds_read_b128 v[200:203], v145 offset:4096
	ds_read_b128 v[204:207], v145 offset:5120
	ds_read_b128 v[208:211], v145 offset:6144
	ds_read_b128 v[212:215], v145 offset:7168
	global_load_lds_dwordx4 v132, s[34:35]
	s_add_i32 m0, s31, 0xe000
	s_nop 0
	global_load_lds_dwordx4 v134, s[34:35]
	s_waitcnt vmcnt(8)
	s_waitcnt lgkmcnt(0)
	s_barrier
	s_waitcnt lgkmcnt(0)
	v_mfma_f32_16x16x32_bf16 v[124:127], v[146:149], v[178:181], v[124:127]
	v_mfma_f32_16x16x32_bf16 v[120:123], v[154:157], v[178:181], v[120:123]
	v_mfma_f32_16x16x32_bf16 v[108:111], v[146:149], v[186:189], v[108:111]
	v_mfma_f32_16x16x32_bf16 v[104:107], v[154:157], v[186:189], v[104:107]
	v_mfma_f32_16x16x32_bf16 v[92:95], v[146:149], v[200:203], v[92:95]
	v_mfma_f32_16x16x32_bf16 v[88:91], v[154:157], v[200:203], v[88:91]
	v_mfma_f32_16x16x32_bf16 v[76:79], v[146:149], v[208:211], v[76:79]
	v_mfma_f32_16x16x32_bf16 v[72:75], v[154:157], v[208:211], v[72:75]
	v_mfma_f32_16x16x32_bf16 v[124:127], v[150:153], v[182:185], v[124:127]
	v_mfma_f32_16x16x32_bf16 v[120:123], v[158:161], v[182:185], v[120:123]
	v_mfma_f32_16x16x32_bf16 v[108:111], v[150:153], v[196:199], v[108:111]
	v_mfma_f32_16x16x32_bf16 v[104:107], v[158:161], v[196:199], v[104:107]
	v_mfma_f32_16x16x32_bf16 v[92:95], v[150:153], v[204:207], v[92:95]
	v_mfma_f32_16x16x32_bf16 v[88:91], v[158:161], v[204:207], v[88:91]
	v_mfma_f32_16x16x32_bf16 v[76:79], v[150:153], v[212:215], v[76:79]
	v_mfma_f32_16x16x32_bf16 v[72:75], v[158:161], v[212:215], v[72:75]
	v_mfma_f32_16x16x32_bf16 v[116:119], v[162:165], v[178:181], v[116:119]
	v_mfma_f32_16x16x32_bf16 v[112:115], v[170:173], v[178:181], v[112:115]
	v_mfma_f32_16x16x32_bf16 v[100:103], v[162:165], v[186:189], v[100:103]
	v_mfma_f32_16x16x32_bf16 v[96:99], v[170:173], v[186:189], v[96:99]
	v_mfma_f32_16x16x32_bf16 v[84:87], v[162:165], v[200:203], v[84:87]
	v_mfma_f32_16x16x32_bf16 v[80:83], v[170:173], v[200:203], v[80:83]
	v_mfma_f32_16x16x32_bf16 v[68:71], v[162:165], v[208:211], v[68:71]
	v_mfma_f32_16x16x32_bf16 v[64:67], v[170:173], v[208:211], v[64:67]
	v_mfma_f32_16x16x32_bf16 v[116:119], v[166:169], v[182:185], v[116:119]
	v_mfma_f32_16x16x32_bf16 v[112:115], v[174:177], v[182:185], v[112:115]
	v_mfma_f32_16x16x32_bf16 v[100:103], v[166:169], v[196:199], v[100:103]
	v_mfma_f32_16x16x32_bf16 v[96:99], v[174:177], v[196:199], v[96:99]
	v_mfma_f32_16x16x32_bf16 v[84:87], v[166:169], v[204:207], v[84:87]
	v_mfma_f32_16x16x32_bf16 v[80:83], v[174:177], v[204:207], v[80:83]
	v_mfma_f32_16x16x32_bf16 v[68:71], v[166:169], v[212:215], v[68:71]
	v_mfma_f32_16x16x32_bf16 v[64:67], v[174:177], v[212:215], v[64:67]
	s_barrier
	s_add_i32 s44, s57, s9
	s_add_u32 s98, s36, s16
	s_addc_u32 s99, s37, s17
	s_mov_b32 m0, s44
	ds_read_b128 v[178:181], v145 offset:16384
	ds_read_b128 v[182:185], v145 offset:17408
	ds_read_b128 v[186:189], v145 offset:18432
	ds_read_b128 v[196:199], v145 offset:19456
	ds_read_b128 v[200:203], v145 offset:20480
	ds_read_b128 v[204:207], v145 offset:21504
	ds_read_b128 v[208:211], v145 offset:22528
	ds_read_b128 v[212:215], v145 offset:23552
	global_load_lds_dwordx4 v128, s[36:37]
	s_add_i32 m0, s44, 0x2000
	s_add_u32 s44, s36, 0x40000
	s_addc_u32 s45, s37, 0
	s_add_u32 s98, s36, s16
	s_addc_u32 s99, s37, s17
	s_add_i32 s48, s58, s9
	global_load_lds_dwordx4 v130, s[36:37]
	s_mov_b32 m0, s48
	v_lshl_add_u64 v[216:217], s[38:39], 0, v[130:131]
	global_load_lds_dwordx4 v128, s[44:45]
	s_add_i32 m0, s48, 0x2000
	s_nop 0
	global_load_lds_dwordx4 v130, s[44:45]
	s_add_u32 s100, s38, s16
	s_addc_u32 s101, s39, s17
	s_mov_b32 m0, s31
	s_nop 0
	global_load_lds_dwordx4 v128, s[38:39]
	s_mov_b32 m0, s33
	s_nop 0
	global_load_lds_dwordx4 v[216:217], off
	s_waitcnt vmcnt(8)
	s_waitcnt lgkmcnt(0)
	s_barrier
	s_waitcnt lgkmcnt(0)
	v_mfma_f32_16x16x32_bf16 v[60:63], v[146:149], v[178:181], v[60:63]
	v_mfma_f32_16x16x32_bf16 v[56:59], v[154:157], v[178:181], v[56:59]
	v_mfma_f32_16x16x32_bf16 v[44:47], v[146:149], v[186:189], v[44:47]
	v_mfma_f32_16x16x32_bf16 v[40:43], v[154:157], v[186:189], v[40:43]
	v_mfma_f32_16x16x32_bf16 v[28:31], v[146:149], v[200:203], v[28:31]
	v_mfma_f32_16x16x32_bf16 v[24:27], v[154:157], v[200:203], v[24:27]
	v_mfma_f32_16x16x32_bf16 v[12:15], v[146:149], v[208:211], v[12:15]
	v_mfma_f32_16x16x32_bf16 v[8:11], v[154:157], v[208:211], v[8:11]
	v_mfma_f32_16x16x32_bf16 v[60:63], v[150:153], v[182:185], v[60:63]
	v_mfma_f32_16x16x32_bf16 v[56:59], v[158:161], v[182:185], v[56:59]
	v_mfma_f32_16x16x32_bf16 v[44:47], v[150:153], v[196:199], v[44:47]
	v_mfma_f32_16x16x32_bf16 v[40:43], v[158:161], v[196:199], v[40:43]
	v_mfma_f32_16x16x32_bf16 v[28:31], v[150:153], v[204:207], v[28:31]
	v_mfma_f32_16x16x32_bf16 v[24:27], v[158:161], v[204:207], v[24:27]
	v_mfma_f32_16x16x32_bf16 v[12:15], v[150:153], v[212:215], v[12:15]
	v_mfma_f32_16x16x32_bf16 v[8:11], v[158:161], v[212:215], v[8:11]
	v_mfma_f32_16x16x32_bf16 v[52:55], v[162:165], v[178:181], v[52:55]
	v_mfma_f32_16x16x32_bf16 v[48:51], v[170:173], v[178:181], v[48:51]
	v_mfma_f32_16x16x32_bf16 v[36:39], v[162:165], v[186:189], v[36:39]
	v_mfma_f32_16x16x32_bf16 v[32:35], v[170:173], v[186:189], v[32:35]
	v_mfma_f32_16x16x32_bf16 v[20:23], v[162:165], v[200:203], v[20:23]
	v_mfma_f32_16x16x32_bf16 v[16:19], v[170:173], v[200:203], v[16:19]
	v_mfma_f32_16x16x32_bf16 v[4:7], v[162:165], v[208:211], v[4:7]
	v_mfma_f32_16x16x32_bf16 v[0:3], v[170:173], v[208:211], v[0:3]
	v_mfma_f32_16x16x32_bf16 v[52:55], v[166:169], v[182:185], v[52:55]
	v_mfma_f32_16x16x32_bf16 v[48:51], v[174:177], v[182:185], v[48:51]
	v_mfma_f32_16x16x32_bf16 v[36:39], v[166:169], v[196:199], v[36:39]
	v_mfma_f32_16x16x32_bf16 v[32:35], v[174:177], v[196:199], v[32:35]
	v_mfma_f32_16x16x32_bf16 v[20:23], v[166:169], v[204:207], v[20:23]
	v_mfma_f32_16x16x32_bf16 v[16:19], v[174:177], v[204:207], v[16:19]
	v_mfma_f32_16x16x32_bf16 v[4:7], v[166:169], v[212:215], v[4:7]
	v_mfma_f32_16x16x32_bf16 v[0:3], v[174:177], v[212:215], v[0:3]
	s_barrier
; #define PG8_STAGE(bufoff, gbase, voff) do { _Pragma("unroll") for (int _i = 0; _i < 2; ++_i) \
;         __builtin_amdgcn_global_load_lds((const unsigned*)((const char*)(gbase) + (voff)[_i]), (PG8_LAS unsigned*)(lds + (bufoff) + ldsw + _i * 8192), 16, 0, 0); } while (0)
; #define PG8_LDA(dst, b, h) do { _Pragma("unroll") for (int m = 0; m < 4; ++m) _Pragma("unroll") for (int k = 0; k < 2; ++k) dst[m][k] = *(const PG8_LAS bf16x8*)(lds + PG8_SA(b, h) + aoff + m * 2048 + k * 1024); } while (0)
; #define PG8_LDB(dst, b, h) do { _Pragma("unroll") for (int n = 0; n < 2; ++n) _Pragma("unroll") for (int k = 0; k < 2; ++k) dst[n][k] = *(const PG8_LAS bf16x8*)(lds + PG8_SB(b, h) + boff + n * 2048 + k * 1024); } while (0)
; #define PG8_MMA(ai, bj, At, Bt) do { __builtin_amdgcn_s_setprio(1); _Pragma("unroll") for (int m = 0; m < 4; ++m) _Pragma("unroll") for (int n = 0; n < 2; ++n) _Pragma("unroll") for (int k = 0; k < 2; ++k) \
;         acc[ai][bj][m][n] = __builtin_amdgcn_mfma_f32_16x16x32_bf16(Bt[n][k], At[m][k], acc[ai][bj][m][n], 0, 0, 0); __builtin_amdgcn_s_setprio(0); } while (0)
; #define PG8_WAIT_V(n) asm volatile("s_waitcnt vmcnt(" #n ")" ::: "memory")
; #define PG8_WAIT_L(n) asm volatile("s_waitcnt lgkmcnt(" #n ")" ::: "memory")
; #define PG8_BAR __builtin_amdgcn_s_barrier()
; #define PG8_SCHED __builtin_amdgcn_sched_barrier(0)
; template <class Epi, class Sched, bool ALIGN_EPI = false, bool SP2 = false>
; __device__ __forceinline__ void gemm_phase(PG8_LAS unsigned char* lds, const Gemm g, const Sched& S, const Epi& E) {
;     ...
;             PG8_LDB(B0, 1, 0); PG8_LDB(B1, 1, 1); PG8_SCHED; PG8_LDA(At, 1, 0); PG8_STAGE(PG8_SA(0, 1), a2 + hstepA, voffA);
;             PG8_WAIT_V(8); PG8_WAIT_L(0); PG8_BAR; PG8_MMA(0, 0, At, B0); PG8_MMA(0, 1, At, B1); PG8_BAR; PG8_SCHED;
;             PG8_LDA(At, 1, 1); PG8_STAGE(PG8_SB(1, 0), b3, voffB); PG8_STAGE(PG8_SB(1, 1), b3 + hstepB, voffB); PG8_STAGE(PG8_SA(1, 0), a3, voffA);
;             PG8_WAIT_V(8); PG8_WAIT_L(0); PG8_BAR; PG8_MMA(1, 0, At, B0); PG8_MMA(1, 1, At, B1); PG8_BAR; PG8_SCHED;
	s_add_i32 s44, 0, 0x18000
	s_add_i32 s45, 0, 0x1c000
	v_add_u32_e32 v158, s44, v142
	v_add_u32_e32 v174, s45, v142
	ds_read_b128 v[146:149], v158
	ds_read_b128 v[150:153], v158 offset:1024
	ds_read_b128 v[154:157], v158 offset:2048
	ds_read_b128 v[158:161], v158 offset:3072
	ds_read_b128 v[162:165], v174
	ds_read_b128 v[166:169], v174 offset:1024
	ds_read_b128 v[170:173], v174 offset:2048
	ds_read_b128 v[174:177], v174 offset:3072
	s_add_u32 s38, s38, 0x40000
	s_addc_u32 s39, s39, 0
	s_mov_b32 m0, s40
	ds_read_b128 v[178:181], v145 offset:32768
	ds_read_b128 v[182:185], v145 offset:33792
	ds_read_b128 v[186:189], v145 offset:34816
	ds_read_b128 v[196:199], v145 offset:35840
	ds_read_b128 v[200:203], v145 offset:36864
	ds_read_b128 v[204:207], v145 offset:37888
	ds_read_b128 v[208:211], v145 offset:38912
	ds_read_b128 v[212:215], v145 offset:39936
	global_load_lds_dwordx4 v128, s[38:39]
	s_mov_b32 m0, s41
	s_nop 0
	global_load_lds_dwordx4 v130, s[38:39]
	s_waitcnt vmcnt(8)
	s_waitcnt lgkmcnt(0)
	s_barrier
	s_waitcnt lgkmcnt(0)
	v_mfma_f32_16x16x32_bf16 v[124:127], v[146:149], v[178:181], v[124:127]
	v_mfma_f32_16x16x32_bf16 v[120:123], v[154:157], v[178:181], v[120:123]
	v_mfma_f32_16x16x32_bf16 v[108:111], v[146:149], v[186:189], v[108:111]
	v_mfma_f32_16x16x32_bf16 v[104:107], v[154:157], v[186:189], v[104:107]
	v_mfma_f32_16x16x32_bf16 v[92:95], v[146:149], v[200:203], v[92:95]
	v_mfma_f32_16x16x32_bf16 v[88:91], v[154:157], v[200:203], v[88:91]
	v_mfma_f32_16x16x32_bf16 v[76:79], v[146:149], v[208:211], v[76:79]
	v_mfma_f32_16x16x32_bf16 v[72:75], v[154:157], v[208:211], v[72:75]
	v_mfma_f32_16x16x32_bf16 v[124:127], v[150:153], v[182:185], v[124:127]
	v_mfma_f32_16x16x32_bf16 v[120:123], v[158:161], v[182:185], v[120:123]
	v_mfma_f32_16x16x32_bf16 v[108:111], v[150:153], v[196:199], v[108:111]
	v_mfma_f32_16x16x32_bf16 v[104:107], v[158:161], v[196:199], v[104:107]
	v_mfma_f32_16x16x32_bf16 v[92:95], v[150:153], v[204:207], v[92:95]
	v_mfma_f32_16x16x32_bf16 v[88:91], v[158:161], v[204:207], v[88:91]
	v_mfma_f32_16x16x32_bf16 v[76:79], v[150:153], v[212:215], v[76:79]
	v_mfma_f32_16x16x32_bf16 v[72:75], v[158:161], v[212:215], v[72:75]
	v_mfma_f32_16x16x32_bf16 v[116:119], v[162:165], v[178:181], v[116:119]
	v_mfma_f32_16x16x32_bf16 v[112:115], v[170:173], v[178:181], v[112:115]
	v_mfma_f32_16x16x32_bf16 v[100:103], v[162:165], v[186:189], v[100:103]
	v_mfma_f32_16x16x32_bf16 v[96:99], v[170:173], v[186:189], v[96:99]
	v_mfma_f32_16x16x32_bf16 v[84:87], v[162:165], v[200:203], v[84:87]
	v_mfma_f32_16x16x32_bf16 v[80:83], v[170:173], v[200:203], v[80:83]
	v_mfma_f32_16x16x32_bf16 v[68:71], v[162:165], v[208:211], v[68:71]
	v_mfma_f32_16x16x32_bf16 v[64:67], v[170:173], v[208:211], v[64:67]
	v_mfma_f32_16x16x32_bf16 v[116:119], v[166:169], v[182:185], v[116:119]
	v_mfma_f32_16x16x32_bf16 v[112:115], v[174:177], v[182:185], v[112:115]
	v_mfma_f32_16x16x32_bf16 v[100:103], v[166:169], v[196:199], v[100:103]
	v_mfma_f32_16x16x32_bf16 v[96:99], v[174:177], v[196:199], v[96:99]
	v_mfma_f32_16x16x32_bf16 v[84:87], v[166:169], v[204:207], v[84:87]
	v_mfma_f32_16x16x32_bf16 v[80:83], v[174:177], v[204:207], v[80:83]
	v_mfma_f32_16x16x32_bf16 v[68:71], v[166:169], v[212:215], v[68:71]
	v_mfma_f32_16x16x32_bf16 v[64:67], v[174:177], v[212:215], v[64:67]
	s_barrier
	s_add_i32 s38, s44, s9
	s_mov_b32 m0, s38
	ds_read_b128 v[178:181], v145 offset:49152
	ds_read_b128 v[182:185], v145 offset:50176
	ds_read_b128 v[186:189], v145 offset:51200
	ds_read_b128 v[196:199], v145 offset:52224
	ds_read_b128 v[200:203], v145 offset:53248
	ds_read_b128 v[204:207], v145 offset:54272
	ds_read_b128 v[208:211], v145 offset:55296
	ds_read_b128 v[212:215], v145 offset:56320
	global_load_lds_dwordx4 v128, s[98:99]
	s_add_i32 m0, s38, 0x2000
	s_add_u32 s36, s36, 0x40080
	s_addc_u32 s37, s37, 0
	s_add_i32 s38, s45, s9
	global_load_lds_dwordx4 v130, s[98:99]
	s_mov_b32 m0, s38
	s_nop 0
	global_load_lds_dwordx4 v128, s[36:37]
	s_add_i32 m0, s38, 0x2000
	s_nop 0
	global_load_lds_dwordx4 v130, s[36:37]
	s_mov_b32 m0, s50
	s_nop 0
	global_load_lds_dwordx4 v128, s[100:101]
	v_lshl_add_u64 v[190:191], v[216:217], 0, s[16:17]
	s_mov_b32 m0, s51
	s_nop 0
	global_load_lds_dwordx4 v[190:191], off
	s_waitcnt vmcnt(8)
	s_waitcnt lgkmcnt(0)
	s_barrier
	s_waitcnt lgkmcnt(0)
	v_mfma_f32_16x16x32_bf16 v[60:63], v[146:149], v[178:181], v[60:63]
	v_mfma_f32_16x16x32_bf16 v[56:59], v[154:157], v[178:181], v[56:59]
	v_mfma_f32_16x16x32_bf16 v[44:47], v[146:149], v[186:189], v[44:47]
	v_mfma_f32_16x16x32_bf16 v[40:43], v[154:157], v[186:189], v[40:43]
	v_mfma_f32_16x16x32_bf16 v[28:31], v[146:149], v[200:203], v[28:31]
	v_mfma_f32_16x16x32_bf16 v[24:27], v[154:157], v[200:203], v[24:27]
	v_mfma_f32_16x16x32_bf16 v[12:15], v[146:149], v[208:211], v[12:15]
	v_mfma_f32_16x16x32_bf16 v[8:11], v[154:157], v[208:211], v[8:11]
	v_mfma_f32_16x16x32_bf16 v[60:63], v[150:153], v[182:185], v[60:63]
	v_mfma_f32_16x16x32_bf16 v[56:59], v[158:161], v[182:185], v[56:59]
	v_mfma_f32_16x16x32_bf16 v[44:47], v[150:153], v[196:199], v[44:47]
	v_mfma_f32_16x16x32_bf16 v[40:43], v[158:161], v[196:199], v[40:43]
	v_mfma_f32_16x16x32_bf16 v[28:31], v[150:153], v[204:207], v[28:31]
	v_mfma_f32_16x16x32_bf16 v[24:27], v[158:161], v[204:207], v[24:27]
	v_mfma_f32_16x16x32_bf16 v[12:15], v[150:153], v[212:215], v[12:15]
	v_mfma_f32_16x16x32_bf16 v[8:11], v[158:161], v[212:215], v[8:11]
	v_mfma_f32_16x16x32_bf16 v[52:55], v[162:165], v[178:181], v[52:55]
	v_mfma_f32_16x16x32_bf16 v[48:51], v[170:173], v[178:181], v[48:51]
	v_mfma_f32_16x16x32_bf16 v[36:39], v[162:165], v[186:189], v[36:39]
	v_mfma_f32_16x16x32_bf16 v[32:35], v[170:173], v[186:189], v[32:35]
	v_mfma_f32_16x16x32_bf16 v[20:23], v[162:165], v[200:203], v[20:23]
	v_mfma_f32_16x16x32_bf16 v[16:19], v[170:173], v[200:203], v[16:19]
	v_mfma_f32_16x16x32_bf16 v[4:7], v[162:165], v[208:211], v[4:7]
	v_mfma_f32_16x16x32_bf16 v[0:3], v[170:173], v[208:211], v[0:3]
	v_mfma_f32_16x16x32_bf16 v[52:55], v[166:169], v[182:185], v[52:55]
	v_mfma_f32_16x16x32_bf16 v[48:51], v[174:177], v[182:185], v[48:51]
	v_mfma_f32_16x16x32_bf16 v[36:39], v[166:169], v[196:199], v[36:39]
	v_mfma_f32_16x16x32_bf16 v[32:35], v[174:177], v[196:199], v[32:35]
	v_mfma_f32_16x16x32_bf16 v[20:23], v[166:169], v[204:207], v[20:23]
	v_mfma_f32_16x16x32_bf16 v[16:19], v[174:177], v[204:207], v[16:19]
	v_mfma_f32_16x16x32_bf16 v[4:7], v[166:169], v[212:215], v[4:7]
	v_mfma_f32_16x16x32_bf16 v[0:3], v[174:177], v[212:215], v[0:3]
	s_barrier
	s_add_i32 s64, s64, 2
	s_add_u32 s34, s34, 0x100
	s_addc_u32 s35, s35, 0
	s_add_u32 s62, s62, 0x100
	s_addc_u32 s63, s63, 0
	s_cmp_gt_u32 s64, 13
	s_cbranch_scc0 .LBB0_210
	s_and_b64 vcc, exec, s[18:19]
	s_cbranch_vccz .LBB0_213
	s_barrier

; #define PG8_STAGE(bufoff, gbase, voff) do { _Pragma("unroll") for (int _i = 0; _i < 2; ++_i) \
;         __builtin_amdgcn_global_load_lds((const unsigned*)((const char*)(gbase) + (voff)[_i]), (PG8_LAS unsigned*)(lds + (bufoff) + ldsw + _i * 8192), 16, 0, 0); } while (0)
; #define PG8_LDA(dst, b, h) do { _Pragma("unroll") for (int m = 0; m < 4; ++m) _Pragma("unroll") for (int k = 0; k < 2; ++k) dst[m][k] = *(const PG8_LAS bf16x8*)(lds + PG8_SA(b, h) + aoff + m * 2048 + k * 1024); } while (0)
; #define PG8_LDB(dst, b, h) do { _Pragma("unroll") for (int n = 0; n < 2; ++n) _Pragma("unroll") for (int k = 0; k < 2; ++k) dst[n][k] = *(const PG8_LAS bf16x8*)(lds + PG8_SB(b, h) + boff + n * 2048 + k * 1024); } while (0)
; #define PG8_MMA(ai, bj, At, Bt) do { __builtin_amdgcn_s_setprio(1); _Pragma("unroll") for (int m = 0; m < 4; ++m) _Pragma("unroll") for (int n = 0; n < 2; ++n) _Pragma("unroll") for (int k = 0; k < 2; ++k) \
;         acc[ai][bj][m][n] = __builtin_amdgcn_mfma_f32_16x16x32_bf16(Bt[n][k], At[m][k], acc[ai][bj][m][n], 0, 0, 0); __builtin_amdgcn_s_setprio(0); } while (0)
; #define PG8_WAIT_V(n) asm volatile("s_waitcnt vmcnt(" #n ")" ::: "memory")
; template <class Epi, class Sched, bool ALIGN_EPI = false, bool SP2 = false>
; __device__ __forceinline__ void gemm_phase(PG8_LAS unsigned char* lds, const Gemm g, const Sched& S, const Epi& E) {
;     ...
;         const char* nA = has_next ? (const char*)g.A + (size_t)nxt.pm * tstepA : cA; const char* nB = has_next ? (const char*)g.Bt + (size_t)nxt.pn * tstepB : cB;
;         for (int t = 0; t < nt; t += 2) {
;             const bool last = (t == nt - 2);
;             const char* a1 = cA + (size_t)(t + 1) * kstep;
;             const char* a2 = last ? nA : cA + (size_t)(t + 2) * kstep; const char* b2 = last ? nB : cB + (size_t)(t + 2) * kstep;
;             const char* a3 = a2 + kstep; const char* b3 = b2 + kstep;
;             if (last && has_next) S.a_ready(nxt);
;             if constexpr (SP2) {
;             PG8_LDB(B0, 0, 0); PG8_LDB(B1, 0, 1); PG8_SCHED; PG8_LDA(At, 0, 0); PG8_STAGE(PG8_SA(1, 1), a1 + hstepA, voffA);
;             PG8_WAIT_V(8); PG8_WAIT_L(0); PG8_BAR; PG8_MMA(0, 0, At, B0); PG8_MMA(0, 1, At, B1); PG8_BAR; PG8_SCHED;
;             PG8_LDA(At, 0, 1); PG8_STAGE(PG8_SB(0, 0), b2, voffB); PG8_STAGE(PG8_SB(0, 1), b2 + hstepB, voffB); PG8_STAGE(PG8_SA(0, 0), a2, voffA);
.LBB0_234:
	ds_read_b128 v[0:3], v143
	ds_read_b128 v[4:7], v143 offset:1024
	ds_read_b128 v[8:11], v143 offset:2048
	ds_read_b128 v[12:15], v143 offset:3072
	ds_read_b128 v[16:19], v144
	ds_read_b128 v[20:23], v144 offset:1024
	ds_read_b128 v[24:27], v144 offset:2048
	ds_read_b128 v[28:31], v144 offset:3072
	s_ashr_i32 s31, s30, 31
	s_lshl_b64 s[34:35], s[30:31], 17
	s_add_u32 s34, s54, s34
	s_addc_u32 s35, s55, s35
	s_and_b64 s[36:37], s[4:5], exec
	s_cselect_b32 s53, s35, s39
	s_cselect_b32 s52, s34, s38
	s_ashr_i32 s29, s28, 31
	s_lshl_b64 s[36:37], s[28:29], 17
	s_add_u32 s36, s2, s36
	s_addc_u32 s37, s3, s37
	s_and_b64 s[44:45], s[4:5], exec
	s_cselect_b32 s51, s37, s41
	s_cselect_b32 s50, s36, s40
	s_add_u32 s44, s38, 0x10080
	s_addc_u32 s45, s39, 0
	s_add_i32 s62, s9, 0xc000
	s_mov_b32 m0, s62
	s_add_i32 s29, s9, 0xe000
	ds_read_b128 v[32:35], v145
	ds_read_b128 v[36:39], v145 offset:1024
	ds_read_b128 v[40:43], v145 offset:2048
	ds_read_b128 v[44:47], v145 offset:3072
	ds_read_b128 v[48:51], v145 offset:4096
	ds_read_b128 v[52:55], v145 offset:5120
	ds_read_b128 v[56:59], v145 offset:6144
	ds_read_b128 v[60:63], v145 offset:7168
	global_load_lds_dwordx4 v128, s[44:45]
	s_mov_b32 m0, s29
	s_nop 0
	global_load_lds_dwordx4 v132, s[44:45]
	s_waitcnt vmcnt(8)
	s_waitcnt lgkmcnt(0)
	s_barrier
	s_waitcnt lgkmcnt(0)
	v_mfma_f32_16x16x32_bf16 v[64:67], v[0:3], v[32:35], 0
	v_mfma_f32_16x16x32_bf16 v[68:71], v[8:11], v[32:35], 0
	v_mfma_f32_16x16x32_bf16 v[72:75], v[0:3], v[40:43], 0
	v_mfma_f32_16x16x32_bf16 v[76:79], v[8:11], v[40:43], 0
	v_mfma_f32_16x16x32_bf16 v[80:83], v[0:3], v[48:51], 0
	v_mfma_f32_16x16x32_bf16 v[84:87], v[8:11], v[48:51], 0
	v_mfma_f32_16x16x32_bf16 v[88:91], v[0:3], v[56:59], 0
	v_mfma_f32_16x16x32_bf16 v[92:95], v[8:11], v[56:59], 0
	v_mfma_f32_16x16x32_bf16 v[64:67], v[4:7], v[36:39], v[64:67]
	v_mfma_f32_16x16x32_bf16 v[68:71], v[12:15], v[36:39], v[68:71]
	v_mfma_f32_16x16x32_bf16 v[72:75], v[4:7], v[44:47], v[72:75]
	v_mfma_f32_16x16x32_bf16 v[76:79], v[12:15], v[44:47], v[76:79]
	v_mfma_f32_16x16x32_bf16 v[80:83], v[4:7], v[52:55], v[80:83]
	v_mfma_f32_16x16x32_bf16 v[84:87], v[12:15], v[52:55], v[84:87]
	v_mfma_f32_16x16x32_bf16 v[88:91], v[4:7], v[60:63], v[88:91]
	v_mfma_f32_16x16x32_bf16 v[92:95], v[12:15], v[60:63], v[92:95]
	v_mfma_f32_16x16x32_bf16 v[96:99], v[16:19], v[32:35], 0
	v_mfma_f32_16x16x32_bf16 v[32:35], v[24:27], v[32:35], 0
	v_mfma_f32_16x16x32_bf16 v[96:99], v[20:23], v[36:39], v[96:99]
	v_mfma_f32_16x16x32_bf16 v[32:35], v[28:31], v[36:39], v[32:35]
	v_mfma_f32_16x16x32_bf16 v[36:39], v[16:19], v[40:43], 0
	v_mfma_f32_16x16x32_bf16 v[40:43], v[24:27], v[40:43], 0
	v_mfma_f32_16x16x32_bf16 v[36:39], v[20:23], v[44:47], v[36:39]
	v_mfma_f32_16x16x32_bf16 v[40:43], v[28:31], v[44:47], v[40:43]
	v_mfma_f32_16x16x32_bf16 v[44:47], v[16:19], v[48:51], 0
	v_mfma_f32_16x16x32_bf16 v[48:51], v[24:27], v[48:51], 0
	v_mfma_f32_16x16x32_bf16 v[44:47], v[20:23], v[52:55], v[44:47]
	v_mfma_f32_16x16x32_bf16 v[48:51], v[28:31], v[52:55], v[48:51]
	v_mfma_f32_16x16x32_bf16 v[52:55], v[16:19], v[56:59], 0
	v_mfma_f32_16x16x32_bf16 v[56:59], v[24:27], v[56:59], 0
	v_mfma_f32_16x16x32_bf16 v[52:55], v[20:23], v[60:63], v[52:55]
	v_mfma_f32_16x16x32_bf16 v[56:59], v[28:31], v[60:63], v[56:59]
	s_barrier
	s_add_i32 s48, s59, s8
	v_lshl_add_u64 v[190:191], s[40:41], 0, v[130:131]
	s_add_i32 s31, s48, 0x2000
	v_lshl_add_u64 v[146:147], v[190:191], 0, s[22:23]
	s_mov_b32 m0, s48
	v_lshl_add_u64 v[192:193], s[40:41], 0, v[134:135]
	s_add_u32 s64, s40, 0x10100
	ds_read_b128 v[60:63], v145 offset:16384
	ds_read_b128 v[100:103], v145 offset:17408
	ds_read_b128 v[104:107], v145 offset:18432
	ds_read_b128 v[108:111], v145 offset:19456
	ds_read_b128 v[112:115], v145 offset:20480
	ds_read_b128 v[116:119], v145 offset:21504
	ds_read_b128 v[120:123], v145 offset:22528
	ds_read_b128 v[124:127], v145 offset:23552
	global_load_lds_dwordx4 v[146:147], off
	v_lshl_add_u64 v[146:147], v[192:193], 0, s[22:23]
	s_mov_b32 m0, s31
	s_addc_u32 s65, s41, 0
	s_add_i32 s44, s60, s8
	global_load_lds_dwordx4 v[146:147], off
	s_mov_b32 m0, s44
	s_add_i32 s45, s44, 0x2000
	global_load_lds_dwordx4 v130, s[64:65]
	s_mov_b32 m0, s45
	v_lshl_add_u64 v[194:195], s[38:39], 0, v[128:129]
	global_load_lds_dwordx4 v134, s[64:65]
	v_lshl_add_u64 v[146:147], v[194:195], 0, s[22:23]
	s_mov_b32 m0, s9
	v_lshl_add_u64 v[216:217], s[38:39], 0, v[132:133]
	global_load_lds_dwordx4 v[146:147], off
	v_lshl_add_u64 v[146:147], v[216:217], 0, s[22:23]
	s_mov_b32 m0, s10
	s_nop 0
	global_load_lds_dwordx4 v[146:147], off
	s_waitcnt vmcnt(8)
	s_waitcnt lgkmcnt(0)
	s_barrier
; #define PG8_STAGE(bufoff, gbase, voff) do { _Pragma("unroll") for (int _i = 0; _i < 2; ++_i) \
;         __builtin_amdgcn_global_load_lds((const unsigned*)((const char*)(gbase) + (voff)[_i]), (PG8_LAS unsigned*)(lds + (bufoff) + ldsw + _i * 8192), 16, 0, 0); } while (0)
; #define PG8_LDA(dst, b, h) do { _Pragma("unroll") for (int m = 0; m < 4; ++m) _Pragma("unroll") for (int k = 0; k < 2; ++k) dst[m][k] = *(const PG8_LAS bf16x8*)(lds + PG8_SA(b, h) + aoff + m * 2048 + k * 1024); } while (0)
; #define PG8_LDB(dst, b, h) do { _Pragma("unroll") for (int n = 0; n < 2; ++n) _Pragma("unroll") for (int k = 0; k < 2; ++k) dst[n][k] = *(const PG8_LAS bf16x8*)(lds + PG8_SB(b, h) + boff + n * 2048 + k * 1024); } while (0)
; #define PG8_MMA(ai, bj, At, Bt) do { __builtin_amdgcn_s_setprio(1); _Pragma("unroll") for (int m = 0; m < 4; ++m) _Pragma("unroll") for (int n = 0; n < 2; ++n) _Pragma("unroll") for (int k = 0; k < 2; ++k) \
;         acc[ai][bj][m][n] = __builtin_amdgcn_mfma_f32_16x16x32_bf16(Bt[n][k], At[m][k], acc[ai][bj][m][n], 0, 0, 0); __builtin_amdgcn_s_setprio(0); } while (0)
; #define PG8_WAIT_V(n) asm volatile("s_waitcnt vmcnt(" #n ")" ::: "memory")
; #define PG8_WAIT_L(n) asm volatile("s_waitcnt lgkmcnt(" #n ")" ::: "memory")
; #define PG8_BAR __builtin_amdgcn_s_barrier()
; #define PG8_SCHED __builtin_amdgcn_sched_barrier(0)
; template <class Epi, class Sched, bool ALIGN_EPI = false, bool SP2 = false>
; __device__ __forceinline__ void gemm_phase(PG8_LAS unsigned char* lds, const Gemm g, const Sched& S, const Epi& E) {
;     ...
;             PG8_WAIT_V(8); PG8_WAIT_L(0); PG8_BAR; PG8_MMA(1, 0, At, B0); PG8_MMA(1, 1, At, B1); PG8_BAR; PG8_SCHED;
;             PG8_LDB(B0, 1, 0); PG8_LDB(B1, 1, 1); PG8_SCHED; PG8_LDA(At, 1, 0); PG8_STAGE(PG8_SA(0, 1), a2 + hstepA, voffA);
;             PG8_WAIT_V(8); PG8_WAIT_L(0); PG8_BAR; PG8_MMA(0, 0, At, B0); PG8_MMA(0, 1, At, B1); PG8_BAR; PG8_SCHED;
	s_waitcnt lgkmcnt(0)
	v_mfma_f32_16x16x32_bf16 v[146:149], v[0:3], v[60:63], 0
	v_mfma_f32_16x16x32_bf16 v[154:157], v[0:3], v[104:107], 0
	v_mfma_f32_16x16x32_bf16 v[162:165], v[0:3], v[112:115], 0
	v_mfma_f32_16x16x32_bf16 v[0:3], v[0:3], v[120:123], 0
	v_mfma_f32_16x16x32_bf16 v[146:149], v[4:7], v[100:103], v[146:149]
	v_mfma_f32_16x16x32_bf16 v[154:157], v[4:7], v[108:111], v[154:157]
	v_mfma_f32_16x16x32_bf16 v[162:165], v[4:7], v[116:119], v[162:165]
	v_mfma_f32_16x16x32_bf16 v[0:3], v[4:7], v[124:127], v[0:3]
	v_mfma_f32_16x16x32_bf16 v[4:7], v[8:11], v[120:123], 0
	v_mfma_f32_16x16x32_bf16 v[150:153], v[8:11], v[60:63], 0
	v_mfma_f32_16x16x32_bf16 v[158:161], v[8:11], v[104:107], 0
	v_mfma_f32_16x16x32_bf16 v[166:169], v[8:11], v[112:115], 0
	v_mfma_f32_16x16x32_bf16 v[4:7], v[12:15], v[124:127], v[4:7]
	v_mfma_f32_16x16x32_bf16 v[150:153], v[12:15], v[100:103], v[150:153]
	v_mfma_f32_16x16x32_bf16 v[158:161], v[12:15], v[108:111], v[158:161]
	v_mfma_f32_16x16x32_bf16 v[166:169], v[12:15], v[116:119], v[166:169]
	v_mfma_f32_16x16x32_bf16 v[8:11], v[16:19], v[60:63], 0
	v_mfma_f32_16x16x32_bf16 v[12:15], v[24:27], v[60:63], 0
	v_mfma_f32_16x16x32_bf16 v[8:11], v[20:23], v[100:103], v[8:11]
	v_mfma_f32_16x16x32_bf16 v[12:15], v[28:31], v[100:103], v[12:15]
	v_mfma_f32_16x16x32_bf16 v[60:63], v[16:19], v[104:107], 0
	v_mfma_f32_16x16x32_bf16 v[100:103], v[24:27], v[104:107], 0
	v_mfma_f32_16x16x32_bf16 v[104:107], v[16:19], v[112:115], 0
	v_mfma_f32_16x16x32_bf16 v[16:19], v[16:19], v[120:123], 0
	v_mfma_f32_16x16x32_bf16 v[60:63], v[20:23], v[108:111], v[60:63]
	v_mfma_f32_16x16x32_bf16 v[100:103], v[28:31], v[108:111], v[100:103]
	v_mfma_f32_16x16x32_bf16 v[104:107], v[20:23], v[116:119], v[104:107]
	v_mfma_f32_16x16x32_bf16 v[108:111], v[24:27], v[112:115], 0
	v_mfma_f32_16x16x32_bf16 v[16:19], v[20:23], v[124:127], v[16:19]
	v_mfma_f32_16x16x32_bf16 v[20:23], v[24:27], v[120:123], 0
	v_mfma_f32_16x16x32_bf16 v[108:111], v[28:31], v[116:119], v[108:111]
	v_mfma_f32_16x16x32_bf16 v[20:23], v[28:31], v[124:127], v[20:23]
	s_barrier
	s_add_i32 s63, 0, 0x18000
	s_add_i32 s66, 0, 0x1c000
	v_add_u32_e32 v220, s63, v142
	v_add_u32_e32 v228, s66, v142
	ds_read_b128 v[24:27], v220
	ds_read_b128 v[28:31], v220 offset:1024
	ds_read_b128 v[112:115], v220 offset:2048
	ds_read_b128 v[116:119], v220 offset:3072
	ds_read_b128 v[120:123], v228
	ds_read_b128 v[124:127], v228 offset:1024
	ds_read_b128 v[170:173], v228 offset:2048
	ds_read_b128 v[174:177], v228 offset:3072
	s_add_u32 s64, s38, 0x10100
	s_addc_u32 s65, s39, 0
	s_mov_b32 m0, s11
	ds_read_b128 v[178:181], v145 offset:32768
	ds_read_b128 v[182:185], v145 offset:33792
	ds_read_b128 v[186:189], v145 offset:34816
	ds_read_b128 v[196:199], v145 offset:35840
	ds_read_b128 v[200:203], v145 offset:36864
	ds_read_b128 v[204:207], v145 offset:37888
	ds_read_b128 v[208:211], v145 offset:38912
	ds_read_b128 v[212:215], v145 offset:39936
	global_load_lds_dwordx4 v128, s[64:65]
	s_mov_b32 m0, s27
	s_nop 0
	global_load_lds_dwordx4 v132, s[64:65]
	s_waitcnt vmcnt(8)
	s_waitcnt lgkmcnt(0)
	s_barrier
	s_waitcnt lgkmcnt(0)
	v_mfma_f32_16x16x32_bf16 v[64:67], v[24:27], v[178:181], v[64:67]
	v_mfma_f32_16x16x32_bf16 v[68:71], v[112:115], v[178:181], v[68:71]
	v_mfma_f32_16x16x32_bf16 v[72:75], v[24:27], v[186:189], v[72:75]
	v_mfma_f32_16x16x32_bf16 v[76:79], v[112:115], v[186:189], v[76:79]
	v_mfma_f32_16x16x32_bf16 v[80:83], v[24:27], v[200:203], v[80:83]
	v_mfma_f32_16x16x32_bf16 v[84:87], v[112:115], v[200:203], v[84:87]
	v_mfma_f32_16x16x32_bf16 v[88:91], v[24:27], v[208:211], v[88:91]
	v_mfma_f32_16x16x32_bf16 v[92:95], v[112:115], v[208:211], v[92:95]
	v_mfma_f32_16x16x32_bf16 v[64:67], v[28:31], v[182:185], v[64:67]
	v_mfma_f32_16x16x32_bf16 v[68:71], v[116:119], v[182:185], v[68:71]
	v_mfma_f32_16x16x32_bf16 v[72:75], v[28:31], v[196:199], v[72:75]
	v_mfma_f32_16x16x32_bf16 v[76:79], v[116:119], v[196:199], v[76:79]
	v_mfma_f32_16x16x32_bf16 v[80:83], v[28:31], v[204:207], v[80:83]
	v_mfma_f32_16x16x32_bf16 v[84:87], v[116:119], v[204:207], v[84:87]
	v_mfma_f32_16x16x32_bf16 v[88:91], v[28:31], v[212:215], v[88:91]
	v_mfma_f32_16x16x32_bf16 v[92:95], v[116:119], v[212:215], v[92:95]
	v_mfma_f32_16x16x32_bf16 v[96:99], v[120:123], v[178:181], v[96:99]
	v_mfma_f32_16x16x32_bf16 v[32:35], v[170:173], v[178:181], v[32:35]
	v_mfma_f32_16x16x32_bf16 v[36:39], v[120:123], v[186:189], v[36:39]
	v_mfma_f32_16x16x32_bf16 v[40:43], v[170:173], v[186:189], v[40:43]
	v_mfma_f32_16x16x32_bf16 v[44:47], v[120:123], v[200:203], v[44:47]
	v_mfma_f32_16x16x32_bf16 v[48:51], v[170:173], v[200:203], v[48:51]
	v_mfma_f32_16x16x32_bf16 v[52:55], v[120:123], v[208:211], v[52:55]
	v_mfma_f32_16x16x32_bf16 v[56:59], v[170:173], v[208:211], v[56:59]
	v_mfma_f32_16x16x32_bf16 v[96:99], v[124:127], v[182:185], v[96:99]
	v_mfma_f32_16x16x32_bf16 v[32:35], v[174:177], v[182:185], v[32:35]
	v_mfma_f32_16x16x32_bf16 v[36:39], v[124:127], v[196:199], v[36:39]
	v_mfma_f32_16x16x32_bf16 v[40:43], v[174:177], v[196:199], v[40:43]
	v_mfma_f32_16x16x32_bf16 v[44:47], v[124:127], v[204:207], v[44:47]
	v_mfma_f32_16x16x32_bf16 v[48:51], v[174:177], v[204:207], v[48:51]
	v_mfma_f32_16x16x32_bf16 v[52:55], v[124:127], v[212:215], v[52:55]
	v_mfma_f32_16x16x32_bf16 v[56:59], v[174:177], v[212:215], v[56:59]
	s_barrier
; #define PG8_STAGE(bufoff, gbase, voff) do { _Pragma("unroll") for (int _i = 0; _i < 2; ++_i) \
;         __builtin_amdgcn_global_load_lds((const unsigned*)((const char*)(gbase) + (voff)[_i]), (PG8_LAS unsigned*)(lds + (bufoff) + ldsw + _i * 8192), 16, 0, 0); } while (0)
; #define PG8_LDA(dst, b, h) do { _Pragma("unroll") for (int m = 0; m < 4; ++m) _Pragma("unroll") for (int k = 0; k < 2; ++k) dst[m][k] = *(const PG8_LAS bf16x8*)(lds + PG8_SA(b, h) + aoff + m * 2048 + k * 1024); } while (0)
; #define PG8_LDB(dst, b, h) do { _Pragma("unroll") for (int n = 0; n < 2; ++n) _Pragma("unroll") for (int k = 0; k < 2; ++k) dst[n][k] = *(const PG8_LAS bf16x8*)(lds + PG8_SB(b, h) + boff + n * 2048 + k * 1024); } while (0)
; #define PG8_MMA(ai, bj, At, Bt) do { __builtin_amdgcn_s_setprio(1); _Pragma("unroll") for (int m = 0; m < 4; ++m) _Pragma("unroll") for (int n = 0; n < 2; ++n) _Pragma("unroll") for (int k = 0; k < 2; ++k) \
;         acc[ai][bj][m][n] = __builtin_amdgcn_mfma_f32_16x16x32_bf16(Bt[n][k], At[m][k], acc[ai][bj][m][n], 0, 0, 0); __builtin_amdgcn_s_setprio(0); } while (0)
; #define PG8_WAIT_V(n) asm volatile("s_waitcnt vmcnt(" #n ")" ::: "memory")
; #define PG8_WAIT_L(n) asm volatile("s_waitcnt lgkmcnt(" #n ")" ::: "memory")
; #define PG8_BAR __builtin_amdgcn_s_barrier()
; #define PG8_SCHED __builtin_amdgcn_sched_barrier(0)
; template <class Epi, class Sched, bool ALIGN_EPI = false, bool SP2 = false>
; __device__ __forceinline__ void gemm_phase(PG8_LAS unsigned char* lds, const Gemm g, const Sched& S, const Epi& E) {
;     ...
;             PG8_LDB(B0, 0, 0); PG8_LDB(B1, 0, 1); PG8_SCHED; PG8_LDA(At, 0, 0); PG8_STAGE(PG8_SA(1, 1), a1 + hstepA, voffA);
;             PG8_WAIT_V(8); PG8_WAIT_L(0); PG8_BAR; PG8_MMA(0, 0, At, B0); PG8_MMA(0, 1, At, B1); PG8_BAR; PG8_SCHED;
;     ...
;             PG8_LDA(At, 1, 1); PG8_STAGE(PG8_SB(1, 0), b3, voffB); PG8_STAGE(PG8_SB(1, 1), b3 + hstepB, voffB); PG8_STAGE(PG8_SA(1, 0), a3, voffA);
;             PG8_WAIT_V(8); PG8_WAIT_L(0); PG8_BAR; PG8_MMA(1, 0, At, B0); PG8_MMA(1, 1, At, B1); PG8_BAR; PG8_SCHED;
	s_add_i32 s63, s63, s8
	s_add_i32 s49, s63, 0x2000
	v_lshl_add_u64 v[190:191], v[190:191], 0, s[24:25]
	s_mov_b32 m0, s63
	s_add_u32 s64, s40, 0x10180
	ds_read_b128 v[178:181], v145 offset:49152
	ds_read_b128 v[182:185], v145 offset:50176
	ds_read_b128 v[186:189], v145 offset:51200
	ds_read_b128 v[196:199], v145 offset:52224
	ds_read_b128 v[200:203], v145 offset:53248
	ds_read_b128 v[204:207], v145 offset:54272
	ds_read_b128 v[208:211], v145 offset:55296
	ds_read_b128 v[212:215], v145 offset:56320
	global_load_lds_dwordx4 v[190:191], off
	v_lshl_add_u64 v[190:191], v[192:193], 0, s[24:25]
	s_mov_b32 m0, s49
	s_addc_u32 s65, s41, 0
	s_add_i32 s40, s66, s8
	global_load_lds_dwordx4 v[190:191], off
	s_mov_b32 m0, s40
	s_add_i32 s41, s40, 0x2000
	global_load_lds_dwordx4 v130, s[64:65]
	s_mov_b32 m0, s41
	s_nop 0
	global_load_lds_dwordx4 v134, s[64:65]
	v_lshl_add_u64 v[190:191], v[194:195], 0, s[24:25]
	s_mov_b32 m0, s43
	s_nop 0
	global_load_lds_dwordx4 v[190:191], off
	v_lshl_add_u64 v[190:191], v[216:217], 0, s[24:25]
	s_mov_b32 m0, s56
	s_nop 0
	global_load_lds_dwordx4 v[190:191], off
	s_waitcnt vmcnt(8)
	s_waitcnt lgkmcnt(0)
	s_barrier
	s_waitcnt lgkmcnt(0)
	v_mfma_f32_16x16x32_bf16 v[0:3], v[24:27], v[208:211], v[0:3]
	v_mfma_f32_16x16x32_bf16 v[4:7], v[112:115], v[208:211], v[4:7]
	v_mfma_f32_16x16x32_bf16 v[146:149], v[24:27], v[178:181], v[146:149]
	v_mfma_f32_16x16x32_bf16 v[150:153], v[112:115], v[178:181], v[150:153]
	v_mfma_f32_16x16x32_bf16 v[154:157], v[24:27], v[186:189], v[154:157]
	v_mfma_f32_16x16x32_bf16 v[158:161], v[112:115], v[186:189], v[158:161]
	v_mfma_f32_16x16x32_bf16 v[162:165], v[24:27], v[200:203], v[162:165]
	v_mfma_f32_16x16x32_bf16 v[166:169], v[112:115], v[200:203], v[166:169]
	v_mfma_f32_16x16x32_bf16 v[0:3], v[28:31], v[212:215], v[0:3]
	v_mfma_f32_16x16x32_bf16 v[4:7], v[116:119], v[212:215], v[4:7]
	v_mfma_f32_16x16x32_bf16 v[146:149], v[28:31], v[182:185], v[146:149]
	v_mfma_f32_16x16x32_bf16 v[150:153], v[116:119], v[182:185], v[150:153]
	v_mfma_f32_16x16x32_bf16 v[154:157], v[28:31], v[196:199], v[154:157]
	v_mfma_f32_16x16x32_bf16 v[158:161], v[116:119], v[196:199], v[158:161]
	v_mfma_f32_16x16x32_bf16 v[162:165], v[28:31], v[204:207], v[162:165]
	v_mfma_f32_16x16x32_bf16 v[166:169], v[116:119], v[204:207], v[166:169]
	v_mfma_f32_16x16x32_bf16 v[8:11], v[120:123], v[178:181], v[8:11]
	v_mfma_f32_16x16x32_bf16 v[12:15], v[170:173], v[178:181], v[12:15]
	v_mfma_f32_16x16x32_bf16 v[24:27], v[120:123], v[186:189], v[60:63]
	v_mfma_f32_16x16x32_bf16 v[28:31], v[170:173], v[186:189], v[100:103]
	v_mfma_f32_16x16x32_bf16 v[60:63], v[120:123], v[200:203], v[104:107]
	v_mfma_f32_16x16x32_bf16 v[100:103], v[170:173], v[200:203], v[108:111]
	v_mfma_f32_16x16x32_bf16 v[16:19], v[120:123], v[208:211], v[16:19]
	v_mfma_f32_16x16x32_bf16 v[20:23], v[170:173], v[208:211], v[20:23]
	v_mfma_f32_16x16x32_bf16 v[8:11], v[124:127], v[182:185], v[8:11]
	v_mfma_f32_16x16x32_bf16 v[12:15], v[174:177], v[182:185], v[12:15]
	v_mfma_f32_16x16x32_bf16 v[24:27], v[124:127], v[196:199], v[24:27]
	v_mfma_f32_16x16x32_bf16 v[28:31], v[174:177], v[196:199], v[28:31]
	v_mfma_f32_16x16x32_bf16 v[60:63], v[124:127], v[204:207], v[60:63]
	v_mfma_f32_16x16x32_bf16 v[100:103], v[174:177], v[204:207], v[100:103]
	v_mfma_f32_16x16x32_bf16 v[16:19], v[124:127], v[212:215], v[16:19]
	v_mfma_f32_16x16x32_bf16 v[20:23], v[174:177], v[212:215], v[20:23]
	s_barrier
	ds_read_b128 v[104:107], v143
	ds_read_b128 v[108:111], v143 offset:1024
	ds_read_b128 v[112:115], v143 offset:2048
	ds_read_b128 v[116:119], v143 offset:3072
	ds_read_b128 v[120:123], v144
	ds_read_b128 v[124:127], v144 offset:1024
	ds_read_b128 v[170:173], v144 offset:2048
	ds_read_b128 v[174:177], v144 offset:3072
	s_add_u32 s38, s38, 0x10180
	s_addc_u32 s39, s39, 0
	s_mov_b32 m0, s62
	ds_read_b128 v[178:181], v145
	ds_read_b128 v[182:185], v145 offset:1024
	ds_read_b128 v[186:189], v145 offset:2048
	ds_read_b128 v[196:199], v145 offset:3072
	ds_read_b128 v[200:203], v145 offset:4096
	ds_read_b128 v[204:207], v145 offset:5120
	ds_read_b128 v[208:211], v145 offset:6144
	ds_read_b128 v[212:215], v145 offset:7168
	global_load_lds_dwordx4 v128, s[38:39]
	s_mov_b32 m0, s29
	s_nop 0
	global_load_lds_dwordx4 v132, s[38:39]
	s_waitcnt vmcnt(8)
	s_waitcnt lgkmcnt(0)
	s_barrier
	s_waitcnt lgkmcnt(0)
	v_mfma_f32_16x16x32_bf16 v[64:67], v[104:107], v[178:181], v[64:67]
	v_mfma_f32_16x16x32_bf16 v[68:71], v[112:115], v[178:181], v[68:71]
	v_mfma_f32_16x16x32_bf16 v[72:75], v[104:107], v[186:189], v[72:75]
	v_mfma_f32_16x16x32_bf16 v[76:79], v[112:115], v[186:189], v[76:79]
	v_mfma_f32_16x16x32_bf16 v[80:83], v[104:107], v[200:203], v[80:83]
	v_mfma_f32_16x16x32_bf16 v[84:87], v[112:115], v[200:203], v[84:87]
	v_mfma_f32_16x16x32_bf16 v[88:91], v[104:107], v[208:211], v[88:91]
	v_mfma_f32_16x16x32_bf16 v[92:95], v[112:115], v[208:211], v[92:95]
	v_mfma_f32_16x16x32_bf16 v[64:67], v[108:111], v[182:185], v[64:67]
	v_mfma_f32_16x16x32_bf16 v[68:71], v[116:119], v[182:185], v[68:71]
	v_mfma_f32_16x16x32_bf16 v[72:75], v[108:111], v[196:199], v[72:75]
	v_mfma_f32_16x16x32_bf16 v[76:79], v[116:119], v[196:199], v[76:79]
	v_mfma_f32_16x16x32_bf16 v[80:83], v[108:111], v[204:207], v[80:83]
	v_mfma_f32_16x16x32_bf16 v[84:87], v[116:119], v[204:207], v[84:87]
	v_mfma_f32_16x16x32_bf16 v[88:91], v[108:111], v[212:215], v[88:91]
	v_mfma_f32_16x16x32_bf16 v[92:95], v[116:119], v[212:215], v[92:95]
	v_mfma_f32_16x16x32_bf16 v[32:35], v[170:173], v[178:181], v[32:35]
	v_mfma_f32_16x16x32_bf16 v[96:99], v[120:123], v[178:181], v[96:99]
	v_mfma_f32_16x16x32_bf16 v[178:181], v[174:177], v[182:185], v[32:35]
	v_mfma_f32_16x16x32_bf16 v[32:35], v[120:123], v[186:189], v[36:39]
	v_mfma_f32_16x16x32_bf16 v[216:219], v[124:127], v[182:185], v[96:99]
	v_mfma_f32_16x16x32_bf16 v[182:185], v[124:127], v[196:199], v[32:35]
	v_mfma_f32_16x16x32_bf16 v[32:35], v[170:173], v[186:189], v[40:43]
	v_mfma_f32_16x16x32_bf16 v[40:43], v[174:177], v[196:199], v[32:35]
	v_mfma_f32_16x16x32_bf16 v[32:35], v[120:123], v[200:203], v[44:47]
	v_mfma_f32_16x16x32_bf16 v[44:47], v[124:127], v[204:207], v[32:35]
	v_mfma_f32_16x16x32_bf16 v[32:35], v[170:173], v[200:203], v[48:51]
	v_mfma_f32_16x16x32_bf16 v[48:51], v[174:177], v[204:207], v[32:35]
	v_mfma_f32_16x16x32_bf16 v[32:35], v[120:123], v[208:211], v[52:55]
	v_mfma_f32_16x16x32_bf16 v[52:55], v[124:127], v[212:215], v[32:35]
	v_mfma_f32_16x16x32_bf16 v[32:35], v[170:173], v[208:211], v[56:59]
	v_mfma_f32_16x16x32_bf16 v[56:59], v[174:177], v[212:215], v[32:35]
	s_barrier
; #define PG8_STAGE(bufoff, gbase, voff) do { _Pragma("unroll") for (int _i = 0; _i < 2; ++_i) \
;         __builtin_amdgcn_global_load_lds((const unsigned*)((const char*)(gbase) + (voff)[_i]), (PG8_LAS unsigned*)(lds + (bufoff) + ldsw + _i * 8192), 16, 0, 0); } while (0)
; #define PG8_LDA(dst, b, h) do { _Pragma("unroll") for (int m = 0; m < 4; ++m) _Pragma("unroll") for (int k = 0; k < 2; ++k) dst[m][k] = *(const PG8_LAS bf16x8*)(lds + PG8_SA(b, h) + aoff + m * 2048 + k * 1024); } while (0)
; #define PG8_LDB(dst, b, h) do { _Pragma("unroll") for (int n = 0; n < 2; ++n) _Pragma("unroll") for (int k = 0; k < 2; ++k) dst[n][k] = *(const PG8_LAS bf16x8*)(lds + PG8_SB(b, h) + boff + n * 2048 + k * 1024); } while (0)
; #define PG8_MMA(ai, bj, At, Bt) do { __builtin_amdgcn_s_setprio(1); _Pragma("unroll") for (int m = 0; m < 4; ++m) _Pragma("unroll") for (int n = 0; n < 2; ++n) _Pragma("unroll") for (int k = 0; k < 2; ++k) \
;         acc[ai][bj][m][n] = __builtin_amdgcn_mfma_f32_16x16x32_bf16(Bt[n][k], At[m][k], acc[ai][bj][m][n], 0, 0, 0); __builtin_amdgcn_s_setprio(0); } while (0)
; #define PG8_WAIT_V(n) asm volatile("s_waitcnt vmcnt(" #n ")" ::: "memory")
; #define PG8_WAIT_L(n) asm volatile("s_waitcnt lgkmcnt(" #n ")" ::: "memory")
; #define PG8_BAR __builtin_amdgcn_s_barrier()
; #define PG8_SCHED __builtin_amdgcn_sched_barrier(0)
; template <class Epi, class Sched, bool ALIGN_EPI = false, bool SP2 = false>
; __device__ __forceinline__ void gemm_phase(PG8_LAS unsigned char* lds, const Gemm g, const Sched& S, const Epi& E) {
;     ...
;             PG8_LDA(At, 0, 1); PG8_STAGE(PG8_SB(0, 0), b2, voffB); PG8_STAGE(PG8_SB(0, 1), b2 + hstepB, voffB); PG8_STAGE(PG8_SA(0, 0), a2, voffA);
;             PG8_WAIT_V(8); PG8_WAIT_L(0); PG8_BAR; PG8_MMA(1, 0, At, B0); PG8_MMA(1, 1, At, B1); PG8_BAR; PG8_SCHED;
;             PG8_LDB(B0, 1, 0); PG8_LDB(B1, 1, 1); PG8_SCHED; PG8_LDA(At, 1, 0); PG8_STAGE(PG8_SA(0, 1), a2 + hstepA, voffA);
;             PG8_WAIT_V(8); PG8_WAIT_L(0); PG8_BAR; PG8_MMA(0, 0, At, B0); PG8_MMA(0, 1, At, B1); PG8_BAR; PG8_SCHED;
	s_mov_b32 m0, s48
	s_add_u32 s98, s50, s16
	s_addc_u32 s99, s51, s17
	s_add_u32 s38, s50, 0x10000
	s_nop 1
	ds_read_b128 v[32:35], v145 offset:16384
	ds_read_b128 v[36:39], v145 offset:17408
	ds_read_b128 v[96:99], v145 offset:18432
	ds_read_b128 v[186:189], v145 offset:19456
	ds_read_b128 v[196:199], v145 offset:20480
	ds_read_b128 v[200:203], v145 offset:21504
	ds_read_b128 v[204:207], v145 offset:22528
	ds_read_b128 v[208:211], v145 offset:23552
	global_load_lds_dwordx4 v130, s[50:51]
	s_mov_b32 m0, s31
	s_addc_u32 s39, s51, 0
	global_load_lds_dwordx4 v134, s[50:51]
	s_mov_b32 m0, s44
	global_load_lds_dwordx4 v130, s[38:39]
	s_mov_b32 m0, s45
	s_nop 0
	global_load_lds_dwordx4 v134, s[38:39]
	s_mov_b32 m0, s9
	s_nop 0
	s_add_u32 s100, s52, s16
	s_addc_u32 s101, s53, s17
	global_load_lds_dwordx4 v128, s[52:53]
	s_mov_b32 m0, s10
	s_nop 0
	global_load_lds_dwordx4 v132, s[52:53]
	s_waitcnt vmcnt(8)
	s_waitcnt lgkmcnt(0)
	s_barrier
	s_waitcnt lgkmcnt(0)
	v_mfma_f32_16x16x32_bf16 v[0:3], v[104:107], v[204:207], v[0:3]
	v_mfma_f32_16x16x32_bf16 v[4:7], v[112:115], v[204:207], v[4:7]
	v_mfma_f32_16x16x32_bf16 v[146:149], v[104:107], v[32:35], v[146:149]
	v_mfma_f32_16x16x32_bf16 v[150:153], v[112:115], v[32:35], v[150:153]
	v_mfma_f32_16x16x32_bf16 v[154:157], v[104:107], v[96:99], v[154:157]
	v_mfma_f32_16x16x32_bf16 v[158:161], v[112:115], v[96:99], v[158:161]
	v_mfma_f32_16x16x32_bf16 v[162:165], v[104:107], v[196:199], v[162:165]
	v_mfma_f32_16x16x32_bf16 v[166:169], v[112:115], v[196:199], v[166:169]
	v_mfma_f32_16x16x32_bf16 v[0:3], v[108:111], v[208:211], v[0:3]
	v_mfma_f32_16x16x32_bf16 v[4:7], v[116:119], v[208:211], v[4:7]
	v_mfma_f32_16x16x32_bf16 v[146:149], v[108:111], v[36:39], v[146:149]
	v_mfma_f32_16x16x32_bf16 v[150:153], v[116:119], v[36:39], v[150:153]
	v_mfma_f32_16x16x32_bf16 v[154:157], v[108:111], v[186:189], v[154:157]
	v_mfma_f32_16x16x32_bf16 v[158:161], v[116:119], v[186:189], v[158:161]
	v_mfma_f32_16x16x32_bf16 v[162:165], v[108:111], v[200:203], v[162:165]
	v_mfma_f32_16x16x32_bf16 v[166:169], v[116:119], v[200:203], v[166:169]
	v_mfma_f32_16x16x32_bf16 v[8:11], v[120:123], v[32:35], v[8:11]
	v_mfma_f32_16x16x32_bf16 v[12:15], v[170:173], v[32:35], v[12:15]
	v_mfma_f32_16x16x32_bf16 v[24:27], v[120:123], v[96:99], v[24:27]
	v_mfma_f32_16x16x32_bf16 v[28:31], v[170:173], v[96:99], v[28:31]
	v_mfma_f32_16x16x32_bf16 v[32:35], v[120:123], v[196:199], v[60:63]
	v_mfma_f32_16x16x32_bf16 v[24:27], v[124:127], v[186:189], v[24:27]
	v_mfma_f32_16x16x32_bf16 v[28:31], v[174:177], v[186:189], v[28:31]
	v_mfma_f32_16x16x32_bf16 v[186:189], v[124:127], v[200:203], v[32:35]
	v_mfma_f32_16x16x32_bf16 v[32:35], v[170:173], v[196:199], v[100:103]
	v_mfma_f32_16x16x32_bf16 v[16:19], v[120:123], v[204:207], v[16:19]
	v_mfma_f32_16x16x32_bf16 v[8:11], v[124:127], v[36:39], v[8:11]
	v_mfma_f32_16x16x32_bf16 v[12:15], v[174:177], v[36:39], v[12:15]
	v_mfma_f32_16x16x32_bf16 v[196:199], v[174:177], v[200:203], v[32:35]
	v_mfma_f32_16x16x32_bf16 v[200:203], v[124:127], v[208:211], v[16:19]
	v_mfma_f32_16x16x32_bf16 v[16:19], v[170:173], v[204:207], v[20:23]
	v_mfma_f32_16x16x32_bf16 v[170:173], v[174:177], v[208:211], v[16:19]
	s_barrier
	ds_read_b128 v[60:63], v220
	ds_read_b128 v[174:177], v220 offset:1024
	ds_read_b128 v[204:207], v220 offset:2048
	ds_read_b128 v[208:211], v220 offset:3072
	ds_read_b128 v[212:215], v228
	ds_read_b128 v[220:223], v228 offset:1024
	ds_read_b128 v[224:227], v228 offset:2048
	ds_read_b128 v[228:231], v228 offset:3072
	s_add_u32 s38, s52, 0x10000
	s_addc_u32 s39, s53, 0
	s_mov_b32 m0, s11
	ds_read_b128 v[16:19], v145 offset:32768
	ds_read_b128 v[20:23], v145 offset:33792
	ds_read_b128 v[108:111], v145 offset:34816
	ds_read_b128 v[232:235], v145 offset:35840
	ds_read_b128 v[236:239], v145 offset:36864
	ds_read_b128 v[240:243], v145 offset:37888
	ds_read_b128 v[244:247], v145 offset:38912
	ds_read_b128 v[248:251], v145 offset:39936
	global_load_lds_dwordx4 v128, s[38:39]
	s_mov_b32 m0, s27
	s_nop 0
	global_load_lds_dwordx4 v132, s[38:39]
	s_waitcnt vmcnt(8)
	s_waitcnt lgkmcnt(0)
	s_barrier
; #define PG8_STAGE(bufoff, gbase, voff) do { _Pragma("unroll") for (int _i = 0; _i < 2; ++_i) \
;         __builtin_amdgcn_global_load_lds((const unsigned*)((const char*)(gbase) + (voff)[_i]), (PG8_LAS unsigned*)(lds + (bufoff) + ldsw + _i * 8192), 16, 0, 0); } while (0)
; #define PG8_LDA(dst, b, h) do { _Pragma("unroll") for (int m = 0; m < 4; ++m) _Pragma("unroll") for (int k = 0; k < 2; ++k) dst[m][k] = *(const PG8_LAS bf16x8*)(lds + PG8_SA(b, h) + aoff + m * 2048 + k * 1024); } while (0)
; #define PG8_MMA(ai, bj, At, Bt) do { __builtin_amdgcn_s_setprio(1); _Pragma("unroll") for (int m = 0; m < 4; ++m) _Pragma("unroll") for (int n = 0; n < 2; ++n) _Pragma("unroll") for (int k = 0; k < 2; ++k) \
;         acc[ai][bj][m][n] = __builtin_amdgcn_mfma_f32_16x16x32_bf16(Bt[n][k], At[m][k], acc[ai][bj][m][n], 0, 0, 0); __builtin_amdgcn_s_setprio(0); } while (0)
; #define PG8_WAIT_V(n) asm volatile("s_waitcnt vmcnt(" #n ")" ::: "memory")
; #define PG8_WAIT_L(n) asm volatile("s_waitcnt lgkmcnt(" #n ")" ::: "memory")
; #define PG8_BAR __builtin_amdgcn_s_barrier()
; #define PG8_SCHED __builtin_amdgcn_sched_barrier(0)
; template <class Epi, class Sched, bool ALIGN_EPI = false, bool SP2 = false>
; __device__ __forceinline__ void gemm_phase(PG8_LAS unsigned char* lds, const Gemm g, const Sched& S, const Epi& E) {
;     ...
;             PG8_LDA(At, 1, 1); PG8_STAGE(PG8_SB(1, 0), b3, voffB); PG8_STAGE(PG8_SB(1, 1), b3 + hstepB, voffB); PG8_STAGE(PG8_SA(1, 0), a3, voffA);
;             PG8_WAIT_V(8); PG8_WAIT_L(0); PG8_BAR; PG8_MMA(1, 0, At, B0); PG8_MMA(1, 1, At, B1); PG8_BAR; PG8_SCHED;
;     ...
;         if constexpr (ALIGN_EPI) { if (wr == 0) PG8_BAR; }
	s_waitcnt lgkmcnt(0)
	v_mfma_f32_16x16x32_bf16 v[32:35], v[60:63], v[16:19], v[64:67]
	v_mfma_f32_16x16x32_bf16 v[112:115], v[174:177], v[20:23], v[32:35]
	v_mfma_f32_16x16x32_bf16 v[32:35], v[204:207], v[16:19], v[68:71]
	v_mfma_f32_16x16x32_bf16 v[116:119], v[208:211], v[20:23], v[32:35]
	v_mfma_f32_16x16x32_bf16 v[32:35], v[60:63], v[108:111], v[72:75]
	v_mfma_f32_16x16x32_bf16 v[96:99], v[174:177], v[232:235], v[32:35]
	v_mfma_f32_16x16x32_bf16 v[32:35], v[204:207], v[108:111], v[76:79]
	v_mfma_f32_16x16x32_bf16 v[100:103], v[208:211], v[232:235], v[32:35]
	v_mfma_f32_16x16x32_bf16 v[32:35], v[60:63], v[236:239], v[80:83]
	v_mfma_f32_16x16x32_bf16 v[64:67], v[174:177], v[240:243], v[32:35]
	v_mfma_f32_16x16x32_bf16 v[32:35], v[204:207], v[236:239], v[84:87]
	v_mfma_f32_16x16x32_bf16 v[68:71], v[208:211], v[240:243], v[32:35]
	v_mfma_f32_16x16x32_bf16 v[32:35], v[60:63], v[244:247], v[88:91]
	v_mfma_f32_16x16x32_bf16 v[36:39], v[204:207], v[244:247], v[92:95]
	v_mfma_f32_16x16x32_bf16 v[32:35], v[174:177], v[248:251], v[32:35]
	v_mfma_f32_16x16x32_bf16 v[36:39], v[208:211], v[248:251], v[36:39]
	v_mfma_f32_16x16x32_bf16 v[72:75], v[212:215], v[16:19], v[216:219]
	v_mfma_f32_16x16x32_bf16 v[16:19], v[224:227], v[16:19], v[178:181]
	v_mfma_f32_16x16x32_bf16 v[124:127], v[228:231], v[20:23], v[16:19]
	v_mfma_f32_16x16x32_bf16 v[16:19], v[212:215], v[108:111], v[182:185]
	v_mfma_f32_16x16x32_bf16 v[104:107], v[220:223], v[232:235], v[16:19]
	v_mfma_f32_16x16x32_bf16 v[16:19], v[224:227], v[108:111], v[40:43]
	v_mfma_f32_16x16x32_bf16 v[108:111], v[228:231], v[232:235], v[16:19]
	v_mfma_f32_16x16x32_bf16 v[16:19], v[212:215], v[236:239], v[44:47]
	v_mfma_f32_16x16x32_bf16 v[120:123], v[220:223], v[20:23], v[72:75]
	v_mfma_f32_16x16x32_bf16 v[72:75], v[220:223], v[240:243], v[16:19]
	v_mfma_f32_16x16x32_bf16 v[16:19], v[224:227], v[236:239], v[48:51]
	v_mfma_f32_16x16x32_bf16 v[76:79], v[228:231], v[240:243], v[16:19]
	v_mfma_f32_16x16x32_bf16 v[16:19], v[212:215], v[244:247], v[52:55]
	v_mfma_f32_16x16x32_bf16 v[40:43], v[220:223], v[248:251], v[16:19]
	v_mfma_f32_16x16x32_bf16 v[16:19], v[224:227], v[244:247], v[56:59]
	v_mfma_f32_16x16x32_bf16 v[44:47], v[228:231], v[248:251], v[16:19]
	s_barrier
	s_mov_b32 m0, s63
	s_nop 3
	s_add_u32 s38, s50, 0x10080
	ds_read_b128 v[56:59], v145 offset:49152
	ds_read_b128 v[92:95], v145 offset:50176
	ds_read_b128 v[178:181], v145 offset:51200
	ds_read_b128 v[182:185], v145 offset:52224
	ds_read_b128 v[216:219], v145 offset:53248
	ds_read_b128 v[232:235], v145 offset:54272
	ds_read_b128 v[236:239], v145 offset:55296
	ds_read_b128 v[240:243], v145 offset:56320
	global_load_lds_dwordx4 v130, s[98:99]
	s_mov_b32 m0, s49
	s_addc_u32 s39, s51, 0
	global_load_lds_dwordx4 v134, s[98:99]
	s_mov_b32 m0, s40
	s_nop 0
	global_load_lds_dwordx4 v130, s[38:39]
	s_mov_b32 m0, s41
	s_nop 0
	global_load_lds_dwordx4 v134, s[38:39]
	s_mov_b32 m0, s43
	s_nop 0
	global_load_lds_dwordx4 v128, s[100:101]
	s_mov_b32 m0, s56
	s_nop 0
	global_load_lds_dwordx4 v132, s[100:101]
	s_waitcnt vmcnt(8)
	s_waitcnt lgkmcnt(0)
	s_barrier
	s_waitcnt lgkmcnt(0)
	v_mfma_f32_16x16x32_bf16 v[16:19], v[60:63], v[56:59], v[146:149]
	v_mfma_f32_16x16x32_bf16 v[80:83], v[174:177], v[92:95], v[16:19]
	v_mfma_f32_16x16x32_bf16 v[16:19], v[204:207], v[56:59], v[150:153]
	v_mfma_f32_16x16x32_bf16 v[84:87], v[208:211], v[92:95], v[16:19]
	v_mfma_f32_16x16x32_bf16 v[16:19], v[60:63], v[178:181], v[154:157]
	v_mfma_f32_16x16x32_bf16 v[48:51], v[174:177], v[182:185], v[16:19]
	v_mfma_f32_16x16x32_bf16 v[16:19], v[204:207], v[178:181], v[158:161]
	v_mfma_f32_16x16x32_bf16 v[52:55], v[208:211], v[182:185], v[16:19]
	v_mfma_f32_16x16x32_bf16 v[16:19], v[60:63], v[216:219], v[162:165]
	v_mfma_f32_16x16x32_bf16 v[20:23], v[204:207], v[216:219], v[166:169]
	v_mfma_f32_16x16x32_bf16 v[0:3], v[60:63], v[236:239], v[0:3]
	v_mfma_f32_16x16x32_bf16 v[4:7], v[204:207], v[236:239], v[4:7]
	v_mfma_f32_16x16x32_bf16 v[16:19], v[174:177], v[232:235], v[16:19]
	v_mfma_f32_16x16x32_bf16 v[20:23], v[208:211], v[232:235], v[20:23]
	v_mfma_f32_16x16x32_bf16 v[0:3], v[174:177], v[240:243], v[0:3]
	v_mfma_f32_16x16x32_bf16 v[4:7], v[208:211], v[240:243], v[4:7]
	v_mfma_f32_16x16x32_bf16 v[8:11], v[212:215], v[56:59], v[8:11]
	v_mfma_f32_16x16x32_bf16 v[88:91], v[220:223], v[92:95], v[8:11]
	v_mfma_f32_16x16x32_bf16 v[8:11], v[224:227], v[56:59], v[12:15]
	v_mfma_f32_16x16x32_bf16 v[92:95], v[228:231], v[92:95], v[8:11]
	v_mfma_f32_16x16x32_bf16 v[8:11], v[212:215], v[178:181], v[24:27]
	v_mfma_f32_16x16x32_bf16 v[56:59], v[220:223], v[182:185], v[8:11]
	v_mfma_f32_16x16x32_bf16 v[8:11], v[224:227], v[178:181], v[28:31]
	v_mfma_f32_16x16x32_bf16 v[60:63], v[228:231], v[182:185], v[8:11]
	v_mfma_f32_16x16x32_bf16 v[8:11], v[212:215], v[216:219], v[186:189]
	v_mfma_f32_16x16x32_bf16 v[24:27], v[220:223], v[232:235], v[8:11]
	v_mfma_f32_16x16x32_bf16 v[8:11], v[224:227], v[216:219], v[196:199]
	v_mfma_f32_16x16x32_bf16 v[28:31], v[228:231], v[232:235], v[8:11]
	v_mfma_f32_16x16x32_bf16 v[8:11], v[212:215], v[236:239], v[200:203]
	v_mfma_f32_16x16x32_bf16 v[12:15], v[224:227], v[236:239], v[170:173]
	v_mfma_f32_16x16x32_bf16 v[8:11], v[220:223], v[240:243], v[8:11]
	v_mfma_f32_16x16x32_bf16 v[12:15], v[228:231], v[240:243], v[12:15]
	s_barrier
	s_andn2_b64 vcc, exec, s[18:19]
	s_cbranch_vccnz .LBB0_236
	s_barrier

; #define PG8_STAGE(bufoff, gbase, voff) do { _Pragma("unroll") for (int _i = 0; _i < 2; ++_i) \
;         __builtin_amdgcn_global_load_lds((const unsigned*)((const char*)(gbase) + (voff)[_i]), (PG8_LAS unsigned*)(lds + (bufoff) + ldsw + _i * 8192), 16, 0, 0); } while (0)
; #define PG8_LDA(dst, b, h) do { _Pragma("unroll") for (int m = 0; m < 4; ++m) _Pragma("unroll") for (int k = 0; k < 2; ++k) dst[m][k] = *(const PG8_LAS bf16x8*)(lds + PG8_SA(b, h) + aoff + m * 2048 + k * 1024); } while (0)
; #define PG8_LDB(dst, b, h) do { _Pragma("unroll") for (int n = 0; n < 2; ++n) _Pragma("unroll") for (int k = 0; k < 2; ++k) dst[n][k] = *(const PG8_LAS bf16x8*)(lds + PG8_SB(b, h) + boff + n * 2048 + k * 1024); } while (0)
; #define PG8_MMA(ai, bj, At, Bt) do { __builtin_amdgcn_s_setprio(1); _Pragma("unroll") for (int m = 0; m < 4; ++m) _Pragma("unroll") for (int n = 0; n < 2; ++n) _Pragma("unroll") for (int k = 0; k < 2; ++k) \
;         acc[ai][bj][m][n] = __builtin_amdgcn_mfma_f32_16x16x32_bf16(Bt[n][k], At[m][k], acc[ai][bj][m][n], 0, 0, 0); __builtin_amdgcn_s_setprio(0); } while (0)
; #define PG8_WAIT_V(n) asm volatile("s_waitcnt vmcnt(" #n ")" ::: "memory")
; #define PG8_WAIT_L(n) asm volatile("s_waitcnt lgkmcnt(" #n ")" ::: "memory")
; #define PG8_BAR __builtin_amdgcn_s_barrier()
; template <class Epi, class Sched, bool ALIGN_EPI = false, bool SP2 = false>
; __device__ __forceinline__ void gemm_phase(PG8_LAS unsigned char* lds, const Gemm g, const Sched& S, const Epi& E) {
;     ...
;             const char* a1 = cA + (size_t)(t + 1) * kstep;
;             const char* a2 = last ? nA : cA + (size_t)(t + 2) * kstep; const char* b2 = last ? nB : cB + (size_t)(t + 2) * kstep;
;             const char* a3 = a2 + kstep; const char* b3 = b2 + kstep;
;             if (last && has_next) S.a_ready(nxt);
;             if constexpr (SP2) {
;             PG8_LDB(B0, 0, 0); PG8_LDB(B1, 0, 1); PG8_SCHED; PG8_LDA(At, 0, 0); PG8_STAGE(PG8_SA(1, 1), a1 + hstepA, voffA);
;             PG8_WAIT_V(8); PG8_WAIT_L(0); PG8_BAR; PG8_MMA(0, 0, At, B0); PG8_MMA(0, 1, At, B1); PG8_BAR; PG8_SCHED;
;             PG8_LDA(At, 0, 1); PG8_STAGE(PG8_SB(0, 0), b2, voffB); PG8_STAGE(PG8_SB(0, 1), b2 + hstepB, voffB); PG8_STAGE(PG8_SA(0, 0), a2, voffA);
;             PG8_WAIT_V(8); PG8_WAIT_L(0); PG8_BAR; PG8_MMA(1, 0, At, B0); PG8_MMA(1, 1, At, B1); PG8_BAR; PG8_SCHED;
.LBB0_303:
	ds_read_b128 v[150:153], v147
	ds_read_b128 v[154:157], v147 offset:1024
	ds_read_b128 v[158:161], v147 offset:2048
	ds_read_b128 v[162:165], v147 offset:3072
	ds_read_b128 v[166:169], v148
	ds_read_b128 v[170:173], v148 offset:1024
	ds_read_b128 v[174:177], v148 offset:2048
	ds_read_b128 v[178:181], v148 offset:3072
	s_add_u32 s28, s0, 0xfff80080
	s_addc_u32 s29, s1, -1
	s_cmp_eq_u32 s53, 2
	s_cselect_b32 s31, s23, s29
	s_cselect_b32 s30, s50, s28
	s_cselect_b32 s29, s25, s52
	s_cselect_b32 s28, s24, s51
	s_add_i32 m0, s8, 0xc000
	ds_read_b128 v[182:185], v149
	ds_read_b128 v[186:189], v149 offset:1024
	ds_read_b128 v[196:199], v149 offset:2048
	ds_read_b128 v[200:203], v149 offset:3072
	ds_read_b128 v[204:207], v149 offset:4096
	ds_read_b128 v[208:211], v149 offset:5120
	ds_read_b128 v[212:215], v149 offset:6144
	ds_read_b128 v[216:219], v149 offset:7168
	global_load_lds_dwordx4 v136, s[0:1]
	s_add_i32 m0, s8, 0xe000
	s_nop 0
	global_load_lds_dwordx4 v138, s[0:1]
	s_waitcnt vmcnt(8)
	s_waitcnt lgkmcnt(0)
	s_barrier
	s_waitcnt lgkmcnt(0)
	v_mfma_f32_16x16x32_bf16 v[124:127], v[150:153], v[182:185], v[124:127]
	v_mfma_f32_16x16x32_bf16 v[120:123], v[158:161], v[182:185], v[120:123]
	v_mfma_f32_16x16x32_bf16 v[116:119], v[150:153], v[196:199], v[116:119]
	v_mfma_f32_16x16x32_bf16 v[112:115], v[158:161], v[196:199], v[112:115]
	v_mfma_f32_16x16x32_bf16 v[100:103], v[150:153], v[204:207], v[100:103]
	v_mfma_f32_16x16x32_bf16 v[96:99], v[158:161], v[204:207], v[96:99]
	v_mfma_f32_16x16x32_bf16 v[84:87], v[150:153], v[212:215], v[84:87]
	v_mfma_f32_16x16x32_bf16 v[80:83], v[158:161], v[212:215], v[80:83]
	v_mfma_f32_16x16x32_bf16 v[124:127], v[154:157], v[186:189], v[124:127]
	v_mfma_f32_16x16x32_bf16 v[120:123], v[162:165], v[186:189], v[120:123]
	v_mfma_f32_16x16x32_bf16 v[116:119], v[154:157], v[200:203], v[116:119]
	v_mfma_f32_16x16x32_bf16 v[112:115], v[162:165], v[200:203], v[112:115]
	v_mfma_f32_16x16x32_bf16 v[100:103], v[154:157], v[208:211], v[100:103]
	v_mfma_f32_16x16x32_bf16 v[96:99], v[162:165], v[208:211], v[96:99]
	v_mfma_f32_16x16x32_bf16 v[84:87], v[154:157], v[216:219], v[84:87]
	v_mfma_f32_16x16x32_bf16 v[80:83], v[162:165], v[216:219], v[80:83]
	v_mfma_f32_16x16x32_bf16 v[108:111], v[166:169], v[182:185], v[108:111]
	v_mfma_f32_16x16x32_bf16 v[104:107], v[174:177], v[182:185], v[104:107]
	v_mfma_f32_16x16x32_bf16 v[92:95], v[166:169], v[196:199], v[92:95]
	v_mfma_f32_16x16x32_bf16 v[88:91], v[174:177], v[196:199], v[88:91]
	v_mfma_f32_16x16x32_bf16 v[76:79], v[166:169], v[204:207], v[76:79]
	v_mfma_f32_16x16x32_bf16 v[72:75], v[174:177], v[204:207], v[72:75]
	v_mfma_f32_16x16x32_bf16 v[68:71], v[166:169], v[212:215], v[68:71]
	v_mfma_f32_16x16x32_bf16 v[64:67], v[174:177], v[212:215], v[64:67]
	v_mfma_f32_16x16x32_bf16 v[108:111], v[170:173], v[186:189], v[108:111]
	v_mfma_f32_16x16x32_bf16 v[104:107], v[178:181], v[186:189], v[104:107]
	v_mfma_f32_16x16x32_bf16 v[92:95], v[170:173], v[200:203], v[92:95]
	v_mfma_f32_16x16x32_bf16 v[88:91], v[178:181], v[200:203], v[88:91]
	v_mfma_f32_16x16x32_bf16 v[76:79], v[170:173], v[208:211], v[76:79]
	v_mfma_f32_16x16x32_bf16 v[72:75], v[178:181], v[208:211], v[72:75]
	v_mfma_f32_16x16x32_bf16 v[68:71], v[170:173], v[216:219], v[68:71]
	v_mfma_f32_16x16x32_bf16 v[64:67], v[178:181], v[216:219], v[64:67]
	s_barrier
	s_add_i32 s44, s39, s2
	s_add_u32 s98, s28, s16
	s_addc_u32 s99, s29, s17
	s_mov_b32 m0, s44
	ds_read_b128 v[182:185], v149 offset:16384
	ds_read_b128 v[186:189], v149 offset:17408
	ds_read_b128 v[196:199], v149 offset:18432
	ds_read_b128 v[200:203], v149 offset:19456
	ds_read_b128 v[204:207], v149 offset:20480
	ds_read_b128 v[208:211], v149 offset:21504
	ds_read_b128 v[212:215], v149 offset:22528
	ds_read_b128 v[216:219], v149 offset:23552
	global_load_lds_dwordx4 v132, s[28:29]
	s_add_i32 m0, s44, 0x2000
	s_add_u32 s44, s28, 0x18000
	s_addc_u32 s45, s29, 0
	s_add_u32 s98, s28, s16
	s_addc_u32 s99, s29, s17
	s_add_i32 s48, s40, s2
	global_load_lds_dwordx4 v128, s[28:29]
	s_mov_b32 m0, s48
	v_lshl_add_u64 v[220:221], s[30:31], 0, v[130:131]
	global_load_lds_dwordx4 v132, s[44:45]
	s_add_i32 m0, s48, 0x2000
	s_nop 0
	global_load_lds_dwordx4 v128, s[44:45]
	s_add_u32 s100, s30, s16
	s_addc_u32 s101, s31, s17
	s_mov_b32 m0, s8
	s_nop 0
	global_load_lds_dwordx4 v134, s[30:31]
	s_mov_b32 m0, s9
	s_nop 0
	global_load_lds_dwordx4 v[220:221], off
	s_waitcnt vmcnt(8)
	s_waitcnt lgkmcnt(0)
	s_barrier
	s_waitcnt lgkmcnt(0)
	v_mfma_f32_16x16x32_bf16 v[60:63], v[150:153], v[182:185], v[60:63]
	v_mfma_f32_16x16x32_bf16 v[56:59], v[158:161], v[182:185], v[56:59]
	v_mfma_f32_16x16x32_bf16 v[52:55], v[150:153], v[196:199], v[52:55]
	v_mfma_f32_16x16x32_bf16 v[48:51], v[158:161], v[196:199], v[48:51]
	v_mfma_f32_16x16x32_bf16 v[36:39], v[150:153], v[204:207], v[36:39]
	v_mfma_f32_16x16x32_bf16 v[32:35], v[158:161], v[204:207], v[32:35]
	v_mfma_f32_16x16x32_bf16 v[20:23], v[150:153], v[212:215], v[20:23]
	v_mfma_f32_16x16x32_bf16 v[16:19], v[158:161], v[212:215], v[16:19]
	v_mfma_f32_16x16x32_bf16 v[60:63], v[154:157], v[186:189], v[60:63]
	v_mfma_f32_16x16x32_bf16 v[56:59], v[162:165], v[186:189], v[56:59]
	v_mfma_f32_16x16x32_bf16 v[52:55], v[154:157], v[200:203], v[52:55]
	v_mfma_f32_16x16x32_bf16 v[48:51], v[162:165], v[200:203], v[48:51]
	v_mfma_f32_16x16x32_bf16 v[36:39], v[154:157], v[208:211], v[36:39]
	v_mfma_f32_16x16x32_bf16 v[32:35], v[162:165], v[208:211], v[32:35]
	v_mfma_f32_16x16x32_bf16 v[20:23], v[154:157], v[216:219], v[20:23]
	v_mfma_f32_16x16x32_bf16 v[16:19], v[162:165], v[216:219], v[16:19]
	v_mfma_f32_16x16x32_bf16 v[44:47], v[166:169], v[182:185], v[44:47]
	v_mfma_f32_16x16x32_bf16 v[40:43], v[174:177], v[182:185], v[40:43]
	v_mfma_f32_16x16x32_bf16 v[28:31], v[166:169], v[196:199], v[28:31]
	v_mfma_f32_16x16x32_bf16 v[24:27], v[174:177], v[196:199], v[24:27]
	v_mfma_f32_16x16x32_bf16 v[12:15], v[166:169], v[204:207], v[12:15]
	v_mfma_f32_16x16x32_bf16 v[8:11], v[174:177], v[204:207], v[8:11]
	v_mfma_f32_16x16x32_bf16 v[4:7], v[166:169], v[212:215], v[4:7]
	v_mfma_f32_16x16x32_bf16 v[0:3], v[174:177], v[212:215], v[0:3]
	v_mfma_f32_16x16x32_bf16 v[44:47], v[170:173], v[186:189], v[44:47]
	v_mfma_f32_16x16x32_bf16 v[40:43], v[178:181], v[186:189], v[40:43]
	v_mfma_f32_16x16x32_bf16 v[28:31], v[170:173], v[200:203], v[28:31]
	v_mfma_f32_16x16x32_bf16 v[24:27], v[178:181], v[200:203], v[24:27]
	v_mfma_f32_16x16x32_bf16 v[12:15], v[170:173], v[208:211], v[12:15]
	v_mfma_f32_16x16x32_bf16 v[8:11], v[178:181], v[208:211], v[8:11]
	v_mfma_f32_16x16x32_bf16 v[4:7], v[170:173], v[216:219], v[4:7]
	v_mfma_f32_16x16x32_bf16 v[0:3], v[178:181], v[216:219], v[0:3]
	s_barrier
; #define PG8_STAGE(bufoff, gbase, voff) do { _Pragma("unroll") for (int _i = 0; _i < 2; ++_i) \
;         __builtin_amdgcn_global_load_lds((const unsigned*)((const char*)(gbase) + (voff)[_i]), (PG8_LAS unsigned*)(lds + (bufoff) + ldsw + _i * 8192), 16, 0, 0); } while (0)
; #define PG8_LDA(dst, b, h) do { _Pragma("unroll") for (int m = 0; m < 4; ++m) _Pragma("unroll") for (int k = 0; k < 2; ++k) dst[m][k] = *(const PG8_LAS bf16x8*)(lds + PG8_SA(b, h) + aoff + m * 2048 + k * 1024); } while (0)
; #define PG8_LDB(dst, b, h) do { _Pragma("unroll") for (int n = 0; n < 2; ++n) _Pragma("unroll") for (int k = 0; k < 2; ++k) dst[n][k] = *(const PG8_LAS bf16x8*)(lds + PG8_SB(b, h) + boff + n * 2048 + k * 1024); } while (0)
; #define PG8_MMA(ai, bj, At, Bt) do { __builtin_amdgcn_s_setprio(1); _Pragma("unroll") for (int m = 0; m < 4; ++m) _Pragma("unroll") for (int n = 0; n < 2; ++n) _Pragma("unroll") for (int k = 0; k < 2; ++k) \
;         acc[ai][bj][m][n] = __builtin_amdgcn_mfma_f32_16x16x32_bf16(Bt[n][k], At[m][k], acc[ai][bj][m][n], 0, 0, 0); __builtin_amdgcn_s_setprio(0); } while (0)
; #define PG8_WAIT_V(n) asm volatile("s_waitcnt vmcnt(" #n ")" ::: "memory")
; #define PG8_WAIT_L(n) asm volatile("s_waitcnt lgkmcnt(" #n ")" ::: "memory")
; #define PG8_BAR __builtin_amdgcn_s_barrier()
; #define PG8_SCHED __builtin_amdgcn_sched_barrier(0)
; template <class Epi, class Sched, bool ALIGN_EPI = false, bool SP2 = false>
; __device__ __forceinline__ void gemm_phase(PG8_LAS unsigned char* lds, const Gemm g, const Sched& S, const Epi& E) {
;     ...
;             PG8_LDB(B0, 1, 0); PG8_LDB(B1, 1, 1); PG8_SCHED; PG8_LDA(At, 1, 0); PG8_STAGE(PG8_SA(0, 1), a2 + hstepA, voffA);
;             PG8_WAIT_V(8); PG8_WAIT_L(0); PG8_BAR; PG8_MMA(0, 0, At, B0); PG8_MMA(0, 1, At, B1); PG8_BAR; PG8_SCHED;
;             PG8_LDA(At, 1, 1); PG8_STAGE(PG8_SB(1, 0), b3, voffB); PG8_STAGE(PG8_SB(1, 1), b3 + hstepB, voffB); PG8_STAGE(PG8_SA(1, 0), a3, voffA);
;             PG8_WAIT_V(8); PG8_WAIT_L(0); PG8_BAR; PG8_MMA(1, 0, At, B0); PG8_MMA(1, 1, At, B1); PG8_BAR; PG8_SCHED;
	s_add_i32 s44, 0, 0x18000
	s_add_i32 s45, 0, 0x1c000
	v_add_u32_e32 v162, s44, v146
	v_add_u32_e32 v178, s45, v146
	ds_read_b128 v[150:153], v162
	ds_read_b128 v[154:157], v162 offset:1024
	ds_read_b128 v[158:161], v162 offset:2048
	ds_read_b128 v[162:165], v162 offset:3072
	ds_read_b128 v[166:169], v178
	ds_read_b128 v[170:173], v178 offset:1024
	ds_read_b128 v[174:177], v178 offset:2048
	ds_read_b128 v[178:181], v178 offset:3072
	s_add_u32 s30, s30, 0x80000
	s_addc_u32 s31, s31, 0
	s_mov_b32 m0, s10
	ds_read_b128 v[182:185], v149 offset:32768
	ds_read_b128 v[186:189], v149 offset:33792
	ds_read_b128 v[196:199], v149 offset:34816
	ds_read_b128 v[200:203], v149 offset:35840
	ds_read_b128 v[204:207], v149 offset:36864
	ds_read_b128 v[208:211], v149 offset:37888
	ds_read_b128 v[212:215], v149 offset:38912
	ds_read_b128 v[216:219], v149 offset:39936
	global_load_lds_dwordx4 v134, s[30:31]
	s_mov_b32 m0, s11
	s_nop 0
	global_load_lds_dwordx4 v130, s[30:31]
	s_waitcnt vmcnt(8)
	s_waitcnt lgkmcnt(0)
	s_barrier
	s_waitcnt lgkmcnt(0)
	v_mfma_f32_16x16x32_bf16 v[124:127], v[150:153], v[182:185], v[124:127]
	v_mfma_f32_16x16x32_bf16 v[120:123], v[158:161], v[182:185], v[120:123]
	v_mfma_f32_16x16x32_bf16 v[116:119], v[150:153], v[196:199], v[116:119]
	v_mfma_f32_16x16x32_bf16 v[112:115], v[158:161], v[196:199], v[112:115]
	v_mfma_f32_16x16x32_bf16 v[100:103], v[150:153], v[204:207], v[100:103]
	v_mfma_f32_16x16x32_bf16 v[96:99], v[158:161], v[204:207], v[96:99]
	v_mfma_f32_16x16x32_bf16 v[84:87], v[150:153], v[212:215], v[84:87]
	v_mfma_f32_16x16x32_bf16 v[80:83], v[158:161], v[212:215], v[80:83]
	v_mfma_f32_16x16x32_bf16 v[124:127], v[154:157], v[186:189], v[124:127]
	v_mfma_f32_16x16x32_bf16 v[120:123], v[162:165], v[186:189], v[120:123]
	v_mfma_f32_16x16x32_bf16 v[116:119], v[154:157], v[200:203], v[116:119]
	v_mfma_f32_16x16x32_bf16 v[112:115], v[162:165], v[200:203], v[112:115]
	v_mfma_f32_16x16x32_bf16 v[100:103], v[154:157], v[208:211], v[100:103]
	v_mfma_f32_16x16x32_bf16 v[96:99], v[162:165], v[208:211], v[96:99]
	v_mfma_f32_16x16x32_bf16 v[84:87], v[154:157], v[216:219], v[84:87]
	v_mfma_f32_16x16x32_bf16 v[80:83], v[162:165], v[216:219], v[80:83]
	v_mfma_f32_16x16x32_bf16 v[108:111], v[166:169], v[182:185], v[108:111]
	v_mfma_f32_16x16x32_bf16 v[104:107], v[174:177], v[182:185], v[104:107]
	v_mfma_f32_16x16x32_bf16 v[92:95], v[166:169], v[196:199], v[92:95]
	v_mfma_f32_16x16x32_bf16 v[88:91], v[174:177], v[196:199], v[88:91]
	v_mfma_f32_16x16x32_bf16 v[76:79], v[166:169], v[204:207], v[76:79]
	v_mfma_f32_16x16x32_bf16 v[72:75], v[174:177], v[204:207], v[72:75]
	v_mfma_f32_16x16x32_bf16 v[68:71], v[166:169], v[212:215], v[68:71]
	v_mfma_f32_16x16x32_bf16 v[64:67], v[174:177], v[212:215], v[64:67]
	v_mfma_f32_16x16x32_bf16 v[108:111], v[170:173], v[186:189], v[108:111]
	v_mfma_f32_16x16x32_bf16 v[104:107], v[178:181], v[186:189], v[104:107]
	v_mfma_f32_16x16x32_bf16 v[92:95], v[170:173], v[200:203], v[92:95]
	v_mfma_f32_16x16x32_bf16 v[88:91], v[178:181], v[200:203], v[88:91]
	v_mfma_f32_16x16x32_bf16 v[76:79], v[170:173], v[208:211], v[76:79]
	v_mfma_f32_16x16x32_bf16 v[72:75], v[178:181], v[208:211], v[72:75]
	v_mfma_f32_16x16x32_bf16 v[68:71], v[170:173], v[216:219], v[68:71]
	v_mfma_f32_16x16x32_bf16 v[64:67], v[178:181], v[216:219], v[64:67]
	s_barrier
	s_add_i32 s30, s44, s2
	s_mov_b32 m0, s30
	ds_read_b128 v[182:185], v149 offset:49152
	ds_read_b128 v[186:189], v149 offset:50176
	ds_read_b128 v[196:199], v149 offset:51200
	ds_read_b128 v[200:203], v149 offset:52224
	ds_read_b128 v[204:207], v149 offset:53248
	ds_read_b128 v[208:211], v149 offset:54272
	ds_read_b128 v[212:215], v149 offset:55296
	ds_read_b128 v[216:219], v149 offset:56320
	global_load_lds_dwordx4 v132, s[98:99]
	s_add_i32 m0, s30, 0x2000
	s_add_u32 s28, s28, 0x18080
	s_addc_u32 s29, s29, 0
	s_add_i32 s30, s45, s2
	global_load_lds_dwordx4 v128, s[98:99]
	s_mov_b32 m0, s30
	s_nop 0
	global_load_lds_dwordx4 v132, s[28:29]
	s_add_i32 m0, s30, 0x2000
	s_nop 0
	global_load_lds_dwordx4 v128, s[28:29]
	s_mov_b32 m0, s35
	s_nop 0
	global_load_lds_dwordx4 v134, s[100:101]
	v_lshl_add_u64 v[190:191], v[220:221], 0, s[16:17]
	s_mov_b32 m0, s36
	s_nop 0
	global_load_lds_dwordx4 v[190:191], off
	s_waitcnt vmcnt(8)
	s_waitcnt lgkmcnt(0)
	s_barrier
	s_waitcnt lgkmcnt(0)
	v_mfma_f32_16x16x32_bf16 v[60:63], v[150:153], v[182:185], v[60:63]
	v_mfma_f32_16x16x32_bf16 v[56:59], v[158:161], v[182:185], v[56:59]
	v_mfma_f32_16x16x32_bf16 v[52:55], v[150:153], v[196:199], v[52:55]
	v_mfma_f32_16x16x32_bf16 v[48:51], v[158:161], v[196:199], v[48:51]
	v_mfma_f32_16x16x32_bf16 v[36:39], v[150:153], v[204:207], v[36:39]
	v_mfma_f32_16x16x32_bf16 v[32:35], v[158:161], v[204:207], v[32:35]
	v_mfma_f32_16x16x32_bf16 v[20:23], v[150:153], v[212:215], v[20:23]
	v_mfma_f32_16x16x32_bf16 v[16:19], v[158:161], v[212:215], v[16:19]
	v_mfma_f32_16x16x32_bf16 v[60:63], v[154:157], v[186:189], v[60:63]
	v_mfma_f32_16x16x32_bf16 v[56:59], v[162:165], v[186:189], v[56:59]
	v_mfma_f32_16x16x32_bf16 v[52:55], v[154:157], v[200:203], v[52:55]
	v_mfma_f32_16x16x32_bf16 v[48:51], v[162:165], v[200:203], v[48:51]
	v_mfma_f32_16x16x32_bf16 v[36:39], v[154:157], v[208:211], v[36:39]
	v_mfma_f32_16x16x32_bf16 v[32:35], v[162:165], v[208:211], v[32:35]
	v_mfma_f32_16x16x32_bf16 v[20:23], v[154:157], v[216:219], v[20:23]
	v_mfma_f32_16x16x32_bf16 v[16:19], v[162:165], v[216:219], v[16:19]
	v_mfma_f32_16x16x32_bf16 v[44:47], v[166:169], v[182:185], v[44:47]
	v_mfma_f32_16x16x32_bf16 v[40:43], v[174:177], v[182:185], v[40:43]
	v_mfma_f32_16x16x32_bf16 v[28:31], v[166:169], v[196:199], v[28:31]
	v_mfma_f32_16x16x32_bf16 v[24:27], v[174:177], v[196:199], v[24:27]
	v_mfma_f32_16x16x32_bf16 v[12:15], v[166:169], v[204:207], v[12:15]
	v_mfma_f32_16x16x32_bf16 v[8:11], v[174:177], v[204:207], v[8:11]
	v_mfma_f32_16x16x32_bf16 v[4:7], v[166:169], v[212:215], v[4:7]
	v_mfma_f32_16x16x32_bf16 v[0:3], v[174:177], v[212:215], v[0:3]
	v_mfma_f32_16x16x32_bf16 v[44:47], v[170:173], v[186:189], v[44:47]
	v_mfma_f32_16x16x32_bf16 v[40:43], v[178:181], v[186:189], v[40:43]
	v_mfma_f32_16x16x32_bf16 v[28:31], v[170:173], v[200:203], v[28:31]
	v_mfma_f32_16x16x32_bf16 v[24:27], v[178:181], v[200:203], v[24:27]
	v_mfma_f32_16x16x32_bf16 v[12:15], v[170:173], v[208:211], v[12:15]
	v_mfma_f32_16x16x32_bf16 v[8:11], v[178:181], v[208:211], v[8:11]
	v_mfma_f32_16x16x32_bf16 v[4:7], v[170:173], v[216:219], v[4:7]
	v_mfma_f32_16x16x32_bf16 v[0:3], v[178:181], v[216:219], v[0:3]
	s_barrier
	s_add_i32 s53, s53, 2
	s_add_u32 s0, s0, 0x100
	s_addc_u32 s1, s1, 0
	s_add_u32 s51, s51, 0x100
	s_addc_u32 s52, s52, 0
	s_cmp_gt_u32 s53, 3
	s_cbranch_scc0 .LBB0_303
	s_and_b64 vcc, exec, s[18:19]
	s_cbranch_vccz .LBB0_306
	s_barrier

; #define PG8_STAGE(bufoff, gbase, voff) do { _Pragma("unroll") for (int _i = 0; _i < 2; ++_i) \
;         __builtin_amdgcn_global_load_lds((const unsigned*)((const char*)(gbase) + (voff)[_i]), (PG8_LAS unsigned*)(lds + (bufoff) + ldsw + _i * 8192), 16, 0, 0); } while (0)
; #define PG8_LDA(dst, b, h) do { _Pragma("unroll") for (int m = 0; m < 4; ++m) _Pragma("unroll") for (int k = 0; k < 2; ++k) dst[m][k] = *(const PG8_LAS bf16x8*)(lds + PG8_SA(b, h) + aoff + m * 2048 + k * 1024); } while (0)
; #define PG8_LDB(dst, b, h) do { _Pragma("unroll") for (int n = 0; n < 2; ++n) _Pragma("unroll") for (int k = 0; k < 2; ++k) dst[n][k] = *(const PG8_LAS bf16x8*)(lds + PG8_SB(b, h) + boff + n * 2048 + k * 1024); } while (0)
; #define PG8_MMA(ai, bj, At, Bt) do { __builtin_amdgcn_s_setprio(1); _Pragma("unroll") for (int m = 0; m < 4; ++m) _Pragma("unroll") for (int n = 0; n < 2; ++n) _Pragma("unroll") for (int k = 0; k < 2; ++k) \
;         acc[ai][bj][m][n] = __builtin_amdgcn_mfma_f32_16x16x32_bf16(Bt[n][k], At[m][k], acc[ai][bj][m][n], 0, 0, 0); __builtin_amdgcn_s_setprio(0); } while (0)
; #define PG8_WAIT_V(n) asm volatile("s_waitcnt vmcnt(" #n ")" ::: "memory")
; #define PG8_WAIT_L(n) asm volatile("s_waitcnt lgkmcnt(" #n ")" ::: "memory")
; #define PG8_BAR __builtin_amdgcn_s_barrier()
; template <class Epi, class Sched, bool ALIGN_EPI = false, bool SP2 = false>
; __device__ __forceinline__ void gemm_phase(PG8_LAS unsigned char* lds, const Gemm g, const Sched& S, const Epi& E) {
;     ...
;             const char* a1 = cA + (size_t)(t + 1) * kstep;
;             const char* a2 = last ? nA : cA + (size_t)(t + 2) * kstep; const char* b2 = last ? nB : cB + (size_t)(t + 2) * kstep;
;             const char* a3 = a2 + kstep; const char* b3 = b2 + kstep;
;             if (last && has_next) S.a_ready(nxt);
;             if constexpr (SP2) {
;             PG8_LDB(B0, 0, 0); PG8_LDB(B1, 0, 1); PG8_SCHED; PG8_LDA(At, 0, 0); PG8_STAGE(PG8_SA(1, 1), a1 + hstepA, voffA);
;             PG8_WAIT_V(8); PG8_WAIT_L(0); PG8_BAR; PG8_MMA(0, 0, At, B0); PG8_MMA(0, 1, At, B1); PG8_BAR; PG8_SCHED;
;             PG8_LDA(At, 0, 1); PG8_STAGE(PG8_SB(0, 0), b2, voffB); PG8_STAGE(PG8_SB(0, 1), b2 + hstepB, voffB); PG8_STAGE(PG8_SA(0, 0), a2, voffA);
;             PG8_WAIT_V(8); PG8_WAIT_L(0); PG8_BAR; PG8_MMA(1, 0, At, B0); PG8_MMA(1, 1, At, B1); PG8_BAR; PG8_SCHED;
.LBB0_632:
	ds_read_b128 v[144:147], v151
	ds_read_b128 v[156:159], v151 offset:1024
	ds_read_b128 v[160:163], v151 offset:2048
	ds_read_b128 v[164:167], v151 offset:3072
	ds_read_b128 v[168:171], v152
	ds_read_b128 v[172:175], v152 offset:1024
	ds_read_b128 v[176:179], v152 offset:2048
	ds_read_b128 v[180:183], v152 offset:3072
	s_add_u32 s28, s26, 0xfffc0080
	s_addc_u32 s29, s27, -1
	s_cmp_eq_u32 s50, 12
	s_cselect_b32 s31, s17, s29
	s_cselect_b32 s30, s23, s28
	s_cselect_b32 s29, s15, s49
	s_cselect_b32 s28, s43, s48
	s_add_i32 m0, s9, 0xc000
	ds_read_b128 v[184:187], v153
	ds_read_b128 v[188:191], v153 offset:1024
	ds_read_b128 v[194:197], v153 offset:2048
	ds_read_b128 v[198:201], v153 offset:3072
	ds_read_b128 v[202:205], v153 offset:4096
	ds_read_b128 v[206:209], v153 offset:5120
	ds_read_b128 v[210:213], v153 offset:6144
	ds_read_b128 v[214:217], v153 offset:7168
	global_load_lds_dwordx4 v136, s[26:27]
	s_add_i32 m0, s9, 0xe000
	s_nop 0
	global_load_lds_dwordx4 v138, s[26:27]
	s_waitcnt vmcnt(8)
	s_waitcnt lgkmcnt(0)
	s_barrier
	s_waitcnt lgkmcnt(0)
	v_mfma_f32_16x16x32_bf16 v[124:127], v[144:147], v[184:187], v[124:127]
	v_mfma_f32_16x16x32_bf16 v[120:123], v[160:163], v[184:187], v[120:123]
	v_mfma_f32_16x16x32_bf16 v[108:111], v[144:147], v[194:197], v[108:111]
	v_mfma_f32_16x16x32_bf16 v[104:107], v[160:163], v[194:197], v[104:107]
	v_mfma_f32_16x16x32_bf16 v[92:95], v[144:147], v[202:205], v[92:95]
	v_mfma_f32_16x16x32_bf16 v[88:91], v[160:163], v[202:205], v[88:91]
	v_mfma_f32_16x16x32_bf16 v[76:79], v[144:147], v[210:213], v[76:79]
	v_mfma_f32_16x16x32_bf16 v[72:75], v[160:163], v[210:213], v[72:75]
	v_mfma_f32_16x16x32_bf16 v[124:127], v[156:159], v[188:191], v[124:127]
	v_mfma_f32_16x16x32_bf16 v[120:123], v[164:167], v[188:191], v[120:123]
	v_mfma_f32_16x16x32_bf16 v[108:111], v[156:159], v[198:201], v[108:111]
	v_mfma_f32_16x16x32_bf16 v[104:107], v[164:167], v[198:201], v[104:107]
	v_mfma_f32_16x16x32_bf16 v[92:95], v[156:159], v[206:209], v[92:95]
	v_mfma_f32_16x16x32_bf16 v[88:91], v[164:167], v[206:209], v[88:91]
	v_mfma_f32_16x16x32_bf16 v[76:79], v[156:159], v[214:217], v[76:79]
	v_mfma_f32_16x16x32_bf16 v[72:75], v[164:167], v[214:217], v[72:75]
	v_mfma_f32_16x16x32_bf16 v[116:119], v[168:171], v[184:187], v[116:119]
	v_mfma_f32_16x16x32_bf16 v[112:115], v[176:179], v[184:187], v[112:115]
	v_mfma_f32_16x16x32_bf16 v[100:103], v[168:171], v[194:197], v[100:103]
	v_mfma_f32_16x16x32_bf16 v[96:99], v[176:179], v[194:197], v[96:99]
	v_mfma_f32_16x16x32_bf16 v[84:87], v[168:171], v[202:205], v[84:87]
	v_mfma_f32_16x16x32_bf16 v[80:83], v[176:179], v[202:205], v[80:83]
	v_mfma_f32_16x16x32_bf16 v[68:71], v[168:171], v[210:213], v[68:71]
	v_mfma_f32_16x16x32_bf16 v[64:67], v[176:179], v[210:213], v[64:67]
	v_mfma_f32_16x16x32_bf16 v[116:119], v[172:175], v[188:191], v[116:119]
	v_mfma_f32_16x16x32_bf16 v[112:115], v[180:183], v[188:191], v[112:115]
	v_mfma_f32_16x16x32_bf16 v[100:103], v[172:175], v[198:201], v[100:103]
	v_mfma_f32_16x16x32_bf16 v[96:99], v[180:183], v[198:201], v[96:99]
	v_mfma_f32_16x16x32_bf16 v[84:87], v[172:175], v[206:209], v[84:87]
	v_mfma_f32_16x16x32_bf16 v[80:83], v[180:183], v[206:209], v[80:83]
	v_mfma_f32_16x16x32_bf16 v[68:71], v[172:175], v[214:217], v[68:71]
	v_mfma_f32_16x16x32_bf16 v[64:67], v[180:183], v[214:217], v[64:67]
	s_barrier
	s_add_i32 s44, s41, s8
	s_add_u32 s98, s28, s6
	s_addc_u32 s99, s29, s7
	s_mov_b32 m0, s44
	ds_read_b128 v[184:187], v153 offset:16384
	ds_read_b128 v[188:191], v153 offset:17408
	ds_read_b128 v[194:197], v153 offset:18432
	ds_read_b128 v[198:201], v153 offset:19456
	ds_read_b128 v[202:205], v153 offset:20480
	ds_read_b128 v[206:209], v153 offset:21504
	ds_read_b128 v[210:213], v153 offset:22528
	ds_read_b128 v[214:217], v153 offset:23552
	global_load_lds_dwordx4 v130, s[28:29]
	s_add_i32 m0, s44, 0x2000
	s_add_u32 s44, s28, 0x40000
	s_addc_u32 s45, s29, 0
	s_add_u32 s98, s28, s6
	s_addc_u32 s99, s29, s7
	s_add_i32 s51, s42, s8
	global_load_lds_dwordx4 v134, s[28:29]
	s_mov_b32 m0, s51
	v_lshl_add_u64 v[222:223], s[30:31], 0, v[132:133]
	global_load_lds_dwordx4 v130, s[44:45]
	s_add_i32 m0, s51, 0x2000
	s_nop 0
	global_load_lds_dwordx4 v134, s[44:45]
	s_add_u32 s100, s30, s6
	s_addc_u32 s101, s31, s7
	s_mov_b32 m0, s9
	s_nop 0
	global_load_lds_dwordx4 v128, s[30:31]
	s_mov_b32 m0, s10
	s_nop 0
	global_load_lds_dwordx4 v[222:223], off
	s_waitcnt vmcnt(8)
	s_waitcnt lgkmcnt(0)
	s_barrier
	s_waitcnt lgkmcnt(0)
	v_mfma_f32_16x16x32_bf16 v[60:63], v[144:147], v[184:187], v[60:63]
	v_mfma_f32_16x16x32_bf16 v[56:59], v[160:163], v[184:187], v[56:59]
	v_mfma_f32_16x16x32_bf16 v[44:47], v[144:147], v[194:197], v[44:47]
	v_mfma_f32_16x16x32_bf16 v[40:43], v[160:163], v[194:197], v[40:43]
	v_mfma_f32_16x16x32_bf16 v[28:31], v[144:147], v[202:205], v[28:31]
	v_mfma_f32_16x16x32_bf16 v[24:27], v[160:163], v[202:205], v[24:27]
	v_mfma_f32_16x16x32_bf16 v[12:15], v[144:147], v[210:213], v[12:15]
	v_mfma_f32_16x16x32_bf16 v[8:11], v[160:163], v[210:213], v[8:11]
	v_mfma_f32_16x16x32_bf16 v[60:63], v[156:159], v[188:191], v[60:63]
	v_mfma_f32_16x16x32_bf16 v[56:59], v[164:167], v[188:191], v[56:59]
	v_mfma_f32_16x16x32_bf16 v[44:47], v[156:159], v[198:201], v[44:47]
	v_mfma_f32_16x16x32_bf16 v[40:43], v[164:167], v[198:201], v[40:43]
	v_mfma_f32_16x16x32_bf16 v[28:31], v[156:159], v[206:209], v[28:31]
	v_mfma_f32_16x16x32_bf16 v[24:27], v[164:167], v[206:209], v[24:27]
	v_mfma_f32_16x16x32_bf16 v[12:15], v[156:159], v[214:217], v[12:15]
	v_mfma_f32_16x16x32_bf16 v[8:11], v[164:167], v[214:217], v[8:11]
	v_mfma_f32_16x16x32_bf16 v[52:55], v[168:171], v[184:187], v[52:55]
	v_mfma_f32_16x16x32_bf16 v[48:51], v[176:179], v[184:187], v[48:51]
	v_mfma_f32_16x16x32_bf16 v[36:39], v[168:171], v[194:197], v[36:39]
	v_mfma_f32_16x16x32_bf16 v[32:35], v[176:179], v[194:197], v[32:35]
	v_mfma_f32_16x16x32_bf16 v[20:23], v[168:171], v[202:205], v[20:23]
	v_mfma_f32_16x16x32_bf16 v[16:19], v[176:179], v[202:205], v[16:19]
	v_mfma_f32_16x16x32_bf16 v[4:7], v[168:171], v[210:213], v[4:7]
	v_mfma_f32_16x16x32_bf16 v[0:3], v[176:179], v[210:213], v[0:3]
	v_mfma_f32_16x16x32_bf16 v[52:55], v[172:175], v[188:191], v[52:55]
	v_mfma_f32_16x16x32_bf16 v[48:51], v[180:183], v[188:191], v[48:51]
	v_mfma_f32_16x16x32_bf16 v[36:39], v[172:175], v[198:201], v[36:39]
	v_mfma_f32_16x16x32_bf16 v[32:35], v[180:183], v[198:201], v[32:35]
	v_mfma_f32_16x16x32_bf16 v[20:23], v[172:175], v[206:209], v[20:23]
	v_mfma_f32_16x16x32_bf16 v[16:19], v[180:183], v[206:209], v[16:19]
	v_mfma_f32_16x16x32_bf16 v[4:7], v[172:175], v[214:217], v[4:7]
	v_mfma_f32_16x16x32_bf16 v[0:3], v[180:183], v[214:217], v[0:3]
	s_barrier
; #define PG8_STAGE(bufoff, gbase, voff) do { _Pragma("unroll") for (int _i = 0; _i < 2; ++_i) \
;         __builtin_amdgcn_global_load_lds((const unsigned*)((const char*)(gbase) + (voff)[_i]), (PG8_LAS unsigned*)(lds + (bufoff) + ldsw + _i * 8192), 16, 0, 0); } while (0)
; #define PG8_LDA(dst, b, h) do { _Pragma("unroll") for (int m = 0; m < 4; ++m) _Pragma("unroll") for (int k = 0; k < 2; ++k) dst[m][k] = *(const PG8_LAS bf16x8*)(lds + PG8_SA(b, h) + aoff + m * 2048 + k * 1024); } while (0)
; #define PG8_LDB(dst, b, h) do { _Pragma("unroll") for (int n = 0; n < 2; ++n) _Pragma("unroll") for (int k = 0; k < 2; ++k) dst[n][k] = *(const PG8_LAS bf16x8*)(lds + PG8_SB(b, h) + boff + n * 2048 + k * 1024); } while (0)
; #define PG8_MMA(ai, bj, At, Bt) do { __builtin_amdgcn_s_setprio(1); _Pragma("unroll") for (int m = 0; m < 4; ++m) _Pragma("unroll") for (int n = 0; n < 2; ++n) _Pragma("unroll") for (int k = 0; k < 2; ++k) \
;         acc[ai][bj][m][n] = __builtin_amdgcn_mfma_f32_16x16x32_bf16(Bt[n][k], At[m][k], acc[ai][bj][m][n], 0, 0, 0); __builtin_amdgcn_s_setprio(0); } while (0)
; #define PG8_WAIT_V(n) asm volatile("s_waitcnt vmcnt(" #n ")" ::: "memory")
; #define PG8_WAIT_L(n) asm volatile("s_waitcnt lgkmcnt(" #n ")" ::: "memory")
; #define PG8_BAR __builtin_amdgcn_s_barrier()
; #define PG8_SCHED __builtin_amdgcn_sched_barrier(0)
; template <class Epi, class Sched, bool ALIGN_EPI = false, bool SP2 = false>
; __device__ __forceinline__ void gemm_phase(PG8_LAS unsigned char* lds, const Gemm g, const Sched& S, const Epi& E) {
;     ...
;             PG8_LDB(B0, 1, 0); PG8_LDB(B1, 1, 1); PG8_SCHED; PG8_LDA(At, 1, 0); PG8_STAGE(PG8_SA(0, 1), a2 + hstepA, voffA);
;             PG8_WAIT_V(8); PG8_WAIT_L(0); PG8_BAR; PG8_MMA(0, 0, At, B0); PG8_MMA(0, 1, At, B1); PG8_BAR; PG8_SCHED;
;             PG8_LDA(At, 1, 1); PG8_STAGE(PG8_SB(1, 0), b3, voffB); PG8_STAGE(PG8_SB(1, 1), b3 + hstepB, voffB); PG8_STAGE(PG8_SA(1, 0), a3, voffA);
;             PG8_WAIT_V(8); PG8_WAIT_L(0); PG8_BAR; PG8_MMA(1, 0, At, B0); PG8_MMA(1, 1, At, B1); PG8_BAR; PG8_SCHED;
	s_add_i32 s44, 0, 0x18000
	v_add_u32_e32 v155, s44, v150
	s_add_i32 s45, 0, 0x1c000
	ds_read_b128 v[144:147], v155
	ds_read_b128 v[156:159], v155 offset:1024
	ds_read_b128 v[160:163], v155 offset:2048
	ds_read_b128 v[164:167], v155 offset:3072
	v_add_u32_e32 v155, s45, v150
	ds_read_b128 v[168:171], v155
	ds_read_b128 v[172:175], v155 offset:1024
	ds_read_b128 v[176:179], v155 offset:2048
	ds_read_b128 v[180:183], v155 offset:3072
	s_add_u32 s30, s30, 0x40000
	s_addc_u32 s31, s31, 0
	s_mov_b32 m0, s11
	ds_read_b128 v[184:187], v153 offset:32768
	ds_read_b128 v[188:191], v153 offset:33792
	ds_read_b128 v[194:197], v153 offset:34816
	ds_read_b128 v[198:201], v153 offset:35840
	ds_read_b128 v[202:205], v153 offset:36864
	ds_read_b128 v[206:209], v153 offset:37888
	ds_read_b128 v[210:213], v153 offset:38912
	ds_read_b128 v[214:217], v153 offset:39936
	global_load_lds_dwordx4 v128, s[30:31]
	s_mov_b32 m0, s25
	s_nop 0
	global_load_lds_dwordx4 v132, s[30:31]
	s_waitcnt vmcnt(8)
	s_waitcnt lgkmcnt(0)
	s_barrier
	s_waitcnt lgkmcnt(0)
	v_mfma_f32_16x16x32_bf16 v[124:127], v[144:147], v[184:187], v[124:127]
	v_mfma_f32_16x16x32_bf16 v[120:123], v[160:163], v[184:187], v[120:123]
	v_mfma_f32_16x16x32_bf16 v[108:111], v[144:147], v[194:197], v[108:111]
	v_mfma_f32_16x16x32_bf16 v[104:107], v[160:163], v[194:197], v[104:107]
	v_mfma_f32_16x16x32_bf16 v[92:95], v[144:147], v[202:205], v[92:95]
	v_mfma_f32_16x16x32_bf16 v[88:91], v[160:163], v[202:205], v[88:91]
	v_mfma_f32_16x16x32_bf16 v[76:79], v[144:147], v[210:213], v[76:79]
	v_mfma_f32_16x16x32_bf16 v[72:75], v[160:163], v[210:213], v[72:75]
	v_mfma_f32_16x16x32_bf16 v[124:127], v[156:159], v[188:191], v[124:127]
	v_mfma_f32_16x16x32_bf16 v[120:123], v[164:167], v[188:191], v[120:123]
	v_mfma_f32_16x16x32_bf16 v[108:111], v[156:159], v[198:201], v[108:111]
	v_mfma_f32_16x16x32_bf16 v[104:107], v[164:167], v[198:201], v[104:107]
	v_mfma_f32_16x16x32_bf16 v[92:95], v[156:159], v[206:209], v[92:95]
	v_mfma_f32_16x16x32_bf16 v[88:91], v[164:167], v[206:209], v[88:91]
	v_mfma_f32_16x16x32_bf16 v[76:79], v[156:159], v[214:217], v[76:79]
	v_mfma_f32_16x16x32_bf16 v[72:75], v[164:167], v[214:217], v[72:75]
	v_mfma_f32_16x16x32_bf16 v[116:119], v[168:171], v[184:187], v[116:119]
	v_mfma_f32_16x16x32_bf16 v[112:115], v[176:179], v[184:187], v[112:115]
	v_mfma_f32_16x16x32_bf16 v[100:103], v[168:171], v[194:197], v[100:103]
	v_mfma_f32_16x16x32_bf16 v[96:99], v[176:179], v[194:197], v[96:99]
	v_mfma_f32_16x16x32_bf16 v[84:87], v[168:171], v[202:205], v[84:87]
	v_mfma_f32_16x16x32_bf16 v[80:83], v[176:179], v[202:205], v[80:83]
	v_mfma_f32_16x16x32_bf16 v[68:71], v[168:171], v[210:213], v[68:71]
	v_mfma_f32_16x16x32_bf16 v[64:67], v[176:179], v[210:213], v[64:67]
	v_mfma_f32_16x16x32_bf16 v[116:119], v[172:175], v[188:191], v[116:119]
	v_mfma_f32_16x16x32_bf16 v[112:115], v[180:183], v[188:191], v[112:115]
	v_mfma_f32_16x16x32_bf16 v[100:103], v[172:175], v[198:201], v[100:103]
	v_mfma_f32_16x16x32_bf16 v[96:99], v[180:183], v[198:201], v[96:99]
	v_mfma_f32_16x16x32_bf16 v[84:87], v[172:175], v[206:209], v[84:87]
	v_mfma_f32_16x16x32_bf16 v[80:83], v[180:183], v[206:209], v[80:83]
	v_mfma_f32_16x16x32_bf16 v[68:71], v[172:175], v[214:217], v[68:71]
	v_mfma_f32_16x16x32_bf16 v[64:67], v[180:183], v[214:217], v[64:67]
	s_barrier
	s_add_i32 s30, s44, s8
	s_mov_b32 m0, s30
	ds_read_b128 v[184:187], v153 offset:49152
	ds_read_b128 v[188:191], v153 offset:50176
	ds_read_b128 v[194:197], v153 offset:51200
	ds_read_b128 v[198:201], v153 offset:52224
	ds_read_b128 v[202:205], v153 offset:53248
	ds_read_b128 v[206:209], v153 offset:54272
	ds_read_b128 v[210:213], v153 offset:55296
	ds_read_b128 v[214:217], v153 offset:56320
	global_load_lds_dwordx4 v130, s[98:99]
	s_add_i32 m0, s30, 0x2000
	s_add_u32 s28, s28, 0x40080
	s_addc_u32 s29, s29, 0
	s_add_i32 s30, s45, s8
	global_load_lds_dwordx4 v134, s[98:99]
	s_mov_b32 m0, s30
	s_nop 0
	global_load_lds_dwordx4 v130, s[28:29]
	s_add_i32 m0, s30, 0x2000
	s_nop 0
	global_load_lds_dwordx4 v134, s[28:29]
	s_mov_b32 m0, s36
	s_nop 0
	global_load_lds_dwordx4 v128, s[100:101]
	v_lshl_add_u64 v[192:193], v[222:223], 0, s[6:7]
	s_mov_b32 m0, s37
	s_nop 0
	global_load_lds_dwordx4 v[192:193], off
	s_waitcnt vmcnt(8)
	s_waitcnt lgkmcnt(0)
	s_barrier
	s_waitcnt lgkmcnt(0)
	v_mfma_f32_16x16x32_bf16 v[60:63], v[144:147], v[184:187], v[60:63]
	v_mfma_f32_16x16x32_bf16 v[56:59], v[160:163], v[184:187], v[56:59]
	v_mfma_f32_16x16x32_bf16 v[44:47], v[144:147], v[194:197], v[44:47]
	v_mfma_f32_16x16x32_bf16 v[40:43], v[160:163], v[194:197], v[40:43]
	v_mfma_f32_16x16x32_bf16 v[28:31], v[144:147], v[202:205], v[28:31]
	v_mfma_f32_16x16x32_bf16 v[24:27], v[160:163], v[202:205], v[24:27]
	v_mfma_f32_16x16x32_bf16 v[12:15], v[144:147], v[210:213], v[12:15]
	v_mfma_f32_16x16x32_bf16 v[8:11], v[160:163], v[210:213], v[8:11]
	v_mfma_f32_16x16x32_bf16 v[60:63], v[156:159], v[188:191], v[60:63]
	v_mfma_f32_16x16x32_bf16 v[56:59], v[164:167], v[188:191], v[56:59]
	v_mfma_f32_16x16x32_bf16 v[44:47], v[156:159], v[198:201], v[44:47]
	v_mfma_f32_16x16x32_bf16 v[40:43], v[164:167], v[198:201], v[40:43]
	v_mfma_f32_16x16x32_bf16 v[28:31], v[156:159], v[206:209], v[28:31]
	v_mfma_f32_16x16x32_bf16 v[24:27], v[164:167], v[206:209], v[24:27]
	v_mfma_f32_16x16x32_bf16 v[12:15], v[156:159], v[214:217], v[12:15]
	v_mfma_f32_16x16x32_bf16 v[8:11], v[164:167], v[214:217], v[8:11]
	v_mfma_f32_16x16x32_bf16 v[52:55], v[168:171], v[184:187], v[52:55]
	v_mfma_f32_16x16x32_bf16 v[48:51], v[176:179], v[184:187], v[48:51]
	v_mfma_f32_16x16x32_bf16 v[36:39], v[168:171], v[194:197], v[36:39]
	v_mfma_f32_16x16x32_bf16 v[32:35], v[176:179], v[194:197], v[32:35]
	v_mfma_f32_16x16x32_bf16 v[20:23], v[168:171], v[202:205], v[20:23]
	v_mfma_f32_16x16x32_bf16 v[16:19], v[176:179], v[202:205], v[16:19]
	v_mfma_f32_16x16x32_bf16 v[4:7], v[168:171], v[210:213], v[4:7]
	v_mfma_f32_16x16x32_bf16 v[0:3], v[176:179], v[210:213], v[0:3]
	v_mfma_f32_16x16x32_bf16 v[52:55], v[172:175], v[188:191], v[52:55]
	v_mfma_f32_16x16x32_bf16 v[48:51], v[180:183], v[188:191], v[48:51]
	v_mfma_f32_16x16x32_bf16 v[36:39], v[172:175], v[198:201], v[36:39]
	v_mfma_f32_16x16x32_bf16 v[32:35], v[180:183], v[198:201], v[32:35]
	v_mfma_f32_16x16x32_bf16 v[20:23], v[172:175], v[206:209], v[20:23]
	v_mfma_f32_16x16x32_bf16 v[16:19], v[180:183], v[206:209], v[16:19]
	v_mfma_f32_16x16x32_bf16 v[4:7], v[172:175], v[214:217], v[4:7]
	v_mfma_f32_16x16x32_bf16 v[0:3], v[180:183], v[214:217], v[0:3]
	s_barrier
	s_add_i32 s50, s50, 2
	s_add_u32 s26, s26, 0x100
	s_addc_u32 s27, s27, 0
	s_add_u32 s48, s48, 0x100
	s_addc_u32 s49, s49, 0
	s_cmp_gt_u32 s50, 13
	s_cbranch_scc0 .LBB0_632
	s_and_b64 vcc, exec, s[12:13]
	s_cbranch_vccz .LBB0_635
	s_barrier

; #define PG8_STAGE(bufoff, gbase, voff) do { _Pragma("unroll") for (int _i = 0; _i < 2; ++_i) \
;         __builtin_amdgcn_global_load_lds((const unsigned*)((const char*)(gbase) + (voff)[_i]), (PG8_LAS unsigned*)(lds + (bufoff) + ldsw + _i * 8192), 16, 0, 0); } while (0)
; #define PG8_LDA(dst, b, h) do { _Pragma("unroll") for (int m = 0; m < 4; ++m) _Pragma("unroll") for (int k = 0; k < 2; ++k) dst[m][k] = *(const PG8_LAS bf16x8*)(lds + PG8_SA(b, h) + aoff + m * 2048 + k * 1024); } while (0)
; #define PG8_LDB(dst, b, h) do { _Pragma("unroll") for (int n = 0; n < 2; ++n) _Pragma("unroll") for (int k = 0; k < 2; ++k) dst[n][k] = *(const PG8_LAS bf16x8*)(lds + PG8_SB(b, h) + boff + n * 2048 + k * 1024); } while (0)
; #define PG8_MMA(ai, bj, At, Bt) do { __builtin_amdgcn_s_setprio(1); _Pragma("unroll") for (int m = 0; m < 4; ++m) _Pragma("unroll") for (int n = 0; n < 2; ++n) _Pragma("unroll") for (int k = 0; k < 2; ++k) \
;         acc[ai][bj][m][n] = __builtin_amdgcn_mfma_f32_16x16x32_bf16(Bt[n][k], At[m][k], acc[ai][bj][m][n], 0, 0, 0); __builtin_amdgcn_s_setprio(0); } while (0)
; #define PG8_WAIT_V(n) asm volatile("s_waitcnt vmcnt(" #n ")" ::: "memory")
; #define PG8_WAIT_L(n) asm volatile("s_waitcnt lgkmcnt(" #n ")" ::: "memory")
; #define PG8_BAR __builtin_amdgcn_s_barrier()
; template <class Epi, class Sched, bool ALIGN_EPI = false, bool SP2 = false>
; __device__ __forceinline__ void gemm_phase(PG8_LAS unsigned char* lds, const Gemm g, const Sched& S, const Epi& E) {
;     ...
;             const char* a1 = cA + (size_t)(t + 1) * kstep;
;             const char* a2 = last ? nA : cA + (size_t)(t + 2) * kstep; const char* b2 = last ? nB : cB + (size_t)(t + 2) * kstep;
;             const char* a3 = a2 + kstep; const char* b3 = b2 + kstep;
;             if (last && has_next) S.a_ready(nxt);
;             if constexpr (SP2) {
;             PG8_LDB(B0, 0, 0); PG8_LDB(B1, 0, 1); PG8_SCHED; PG8_LDA(At, 0, 0); PG8_STAGE(PG8_SA(1, 1), a1 + hstepA, voffA);
;             PG8_WAIT_V(8); PG8_WAIT_L(0); PG8_BAR; PG8_MMA(0, 0, At, B0); PG8_MMA(0, 1, At, B1); PG8_BAR; PG8_SCHED;
;             PG8_LDA(At, 0, 1); PG8_STAGE(PG8_SB(0, 0), b2, voffB); PG8_STAGE(PG8_SB(0, 1), b2 + hstepB, voffB); PG8_STAGE(PG8_SA(0, 0), a2, voffA);
;             PG8_WAIT_V(8); PG8_WAIT_L(0); PG8_BAR; PG8_MMA(1, 0, At, B0); PG8_MMA(1, 1, At, B1); PG8_BAR; PG8_SCHED;
.LBB0_724:
	ds_read_b128 v[144:147], v151
	ds_read_b128 v[156:159], v151 offset:1024
	ds_read_b128 v[160:163], v151 offset:2048
	ds_read_b128 v[164:167], v151 offset:3072
	ds_read_b128 v[168:171], v152
	ds_read_b128 v[172:175], v152 offset:1024
	ds_read_b128 v[176:179], v152 offset:2048
	ds_read_b128 v[180:183], v152 offset:3072
	s_add_u32 s44, s40, 0xfffc0080
	s_addc_u32 s45, s41, -1
	s_cmp_eq_u32 s63, 12
	s_cselect_b32 s49, s8, s45
	s_cselect_b32 s48, s9, s44
	s_cselect_b32 s45, s29, s62
	s_cselect_b32 s44, s31, s42
	s_add_i32 m0, s39, 0xc000
	ds_read_b128 v[184:187], v153
	ds_read_b128 v[188:191], v153 offset:1024
	ds_read_b128 v[194:197], v153 offset:2048
	ds_read_b128 v[198:201], v153 offset:3072
	ds_read_b128 v[202:205], v153 offset:4096
	ds_read_b128 v[206:209], v153 offset:5120
	ds_read_b128 v[210:213], v153 offset:6144
	ds_read_b128 v[214:217], v153 offset:7168
	global_load_lds_dwordx4 v136, s[40:41]
	s_add_i32 m0, s39, 0xe000
	s_nop 0
	global_load_lds_dwordx4 v138, s[40:41]
	s_waitcnt vmcnt(8)
	s_waitcnt lgkmcnt(0)
	s_barrier
	s_waitcnt lgkmcnt(0)
	v_mfma_f32_16x16x32_bf16 v[124:127], v[144:147], v[184:187], v[124:127]
	v_mfma_f32_16x16x32_bf16 v[120:123], v[160:163], v[184:187], v[120:123]
	v_mfma_f32_16x16x32_bf16 v[108:111], v[144:147], v[194:197], v[108:111]
	v_mfma_f32_16x16x32_bf16 v[104:107], v[160:163], v[194:197], v[104:107]
	v_mfma_f32_16x16x32_bf16 v[92:95], v[144:147], v[202:205], v[92:95]
	v_mfma_f32_16x16x32_bf16 v[88:91], v[160:163], v[202:205], v[88:91]
	v_mfma_f32_16x16x32_bf16 v[76:79], v[144:147], v[210:213], v[76:79]
	v_mfma_f32_16x16x32_bf16 v[72:75], v[160:163], v[210:213], v[72:75]
	v_mfma_f32_16x16x32_bf16 v[124:127], v[156:159], v[188:191], v[124:127]
	v_mfma_f32_16x16x32_bf16 v[120:123], v[164:167], v[188:191], v[120:123]
	v_mfma_f32_16x16x32_bf16 v[108:111], v[156:159], v[198:201], v[108:111]
	v_mfma_f32_16x16x32_bf16 v[104:107], v[164:167], v[198:201], v[104:107]
	v_mfma_f32_16x16x32_bf16 v[92:95], v[156:159], v[206:209], v[92:95]
	v_mfma_f32_16x16x32_bf16 v[88:91], v[164:167], v[206:209], v[88:91]
	v_mfma_f32_16x16x32_bf16 v[76:79], v[156:159], v[214:217], v[76:79]
	v_mfma_f32_16x16x32_bf16 v[72:75], v[164:167], v[214:217], v[72:75]
	v_mfma_f32_16x16x32_bf16 v[116:119], v[168:171], v[184:187], v[116:119]
	v_mfma_f32_16x16x32_bf16 v[112:115], v[176:179], v[184:187], v[112:115]
	v_mfma_f32_16x16x32_bf16 v[100:103], v[168:171], v[194:197], v[100:103]
	v_mfma_f32_16x16x32_bf16 v[96:99], v[176:179], v[194:197], v[96:99]
	v_mfma_f32_16x16x32_bf16 v[84:87], v[168:171], v[202:205], v[84:87]
	v_mfma_f32_16x16x32_bf16 v[80:83], v[176:179], v[202:205], v[80:83]
	v_mfma_f32_16x16x32_bf16 v[68:71], v[168:171], v[210:213], v[68:71]
	v_mfma_f32_16x16x32_bf16 v[64:67], v[176:179], v[210:213], v[64:67]
	v_mfma_f32_16x16x32_bf16 v[116:119], v[172:175], v[188:191], v[116:119]
	v_mfma_f32_16x16x32_bf16 v[112:115], v[180:183], v[188:191], v[112:115]
	v_mfma_f32_16x16x32_bf16 v[100:103], v[172:175], v[198:201], v[100:103]
	v_mfma_f32_16x16x32_bf16 v[96:99], v[180:183], v[198:201], v[96:99]
	v_mfma_f32_16x16x32_bf16 v[84:87], v[172:175], v[206:209], v[84:87]
	v_mfma_f32_16x16x32_bf16 v[80:83], v[180:183], v[206:209], v[80:83]
	v_mfma_f32_16x16x32_bf16 v[68:71], v[172:175], v[214:217], v[68:71]
	v_mfma_f32_16x16x32_bf16 v[64:67], v[180:183], v[214:217], v[64:67]
	s_barrier
	s_add_i32 s64, s60, s50
	s_add_u32 s98, s44, s10
	s_addc_u32 s99, s45, s11
	s_mov_b32 m0, s64
	ds_read_b128 v[184:187], v153 offset:16384
	ds_read_b128 v[188:191], v153 offset:17408
	ds_read_b128 v[194:197], v153 offset:18432
	ds_read_b128 v[198:201], v153 offset:19456
	ds_read_b128 v[202:205], v153 offset:20480
	ds_read_b128 v[206:209], v153 offset:21504
	ds_read_b128 v[210:213], v153 offset:22528
	ds_read_b128 v[214:217], v153 offset:23552
	global_load_lds_dwordx4 v130, s[44:45]
	s_add_i32 m0, s64, 0x2000
	s_add_u32 s64, s44, 0x40000
	s_addc_u32 s65, s45, 0
	s_add_u32 s98, s44, s10
	s_addc_u32 s99, s45, s11
	s_add_i32 s66, s61, s50
	global_load_lds_dwordx4 v134, s[44:45]
	s_mov_b32 m0, s66
	s_add_u32 s100, s48, s10
	s_addc_u32 s101, s49, s11
	global_load_lds_dwordx4 v130, s[64:65]
	s_add_i32 m0, s66, 0x2000
	s_nop 0
	global_load_lds_dwordx4 v134, s[64:65]
	s_add_u32 s100, s48, s10
	s_addc_u32 s101, s49, s11
	s_mov_b32 m0, s39
	s_nop 0
	global_load_lds_dwordx4 v128, s[48:49]
	s_mov_b32 m0, s51
	s_nop 0
	global_load_lds_dwordx4 v132, s[48:49]
	s_waitcnt vmcnt(8)
	s_waitcnt lgkmcnt(0)
	s_barrier
	s_waitcnt lgkmcnt(0)
	v_mfma_f32_16x16x32_bf16 v[60:63], v[144:147], v[184:187], v[60:63]
	v_mfma_f32_16x16x32_bf16 v[56:59], v[160:163], v[184:187], v[56:59]
	v_mfma_f32_16x16x32_bf16 v[44:47], v[144:147], v[194:197], v[44:47]
	v_mfma_f32_16x16x32_bf16 v[40:43], v[160:163], v[194:197], v[40:43]
	v_mfma_f32_16x16x32_bf16 v[28:31], v[144:147], v[202:205], v[28:31]
	v_mfma_f32_16x16x32_bf16 v[24:27], v[160:163], v[202:205], v[24:27]
	v_mfma_f32_16x16x32_bf16 v[12:15], v[144:147], v[210:213], v[12:15]
	v_mfma_f32_16x16x32_bf16 v[8:11], v[160:163], v[210:213], v[8:11]
	v_mfma_f32_16x16x32_bf16 v[60:63], v[156:159], v[188:191], v[60:63]
	v_mfma_f32_16x16x32_bf16 v[56:59], v[164:167], v[188:191], v[56:59]
	v_mfma_f32_16x16x32_bf16 v[44:47], v[156:159], v[198:201], v[44:47]
	v_mfma_f32_16x16x32_bf16 v[40:43], v[164:167], v[198:201], v[40:43]
	v_mfma_f32_16x16x32_bf16 v[28:31], v[156:159], v[206:209], v[28:31]
	v_mfma_f32_16x16x32_bf16 v[24:27], v[164:167], v[206:209], v[24:27]
	v_mfma_f32_16x16x32_bf16 v[12:15], v[156:159], v[214:217], v[12:15]
	v_mfma_f32_16x16x32_bf16 v[8:11], v[164:167], v[214:217], v[8:11]
	v_mfma_f32_16x16x32_bf16 v[52:55], v[168:171], v[184:187], v[52:55]
	v_mfma_f32_16x16x32_bf16 v[48:51], v[176:179], v[184:187], v[48:51]
	v_mfma_f32_16x16x32_bf16 v[36:39], v[168:171], v[194:197], v[36:39]
	v_mfma_f32_16x16x32_bf16 v[32:35], v[176:179], v[194:197], v[32:35]
	v_mfma_f32_16x16x32_bf16 v[20:23], v[168:171], v[202:205], v[20:23]
	v_mfma_f32_16x16x32_bf16 v[16:19], v[176:179], v[202:205], v[16:19]
	v_mfma_f32_16x16x32_bf16 v[4:7], v[168:171], v[210:213], v[4:7]
	v_mfma_f32_16x16x32_bf16 v[0:3], v[176:179], v[210:213], v[0:3]
	v_mfma_f32_16x16x32_bf16 v[52:55], v[172:175], v[188:191], v[52:55]
	v_mfma_f32_16x16x32_bf16 v[48:51], v[180:183], v[188:191], v[48:51]
	v_mfma_f32_16x16x32_bf16 v[36:39], v[172:175], v[198:201], v[36:39]
	v_mfma_f32_16x16x32_bf16 v[32:35], v[180:183], v[198:201], v[32:35]
	v_mfma_f32_16x16x32_bf16 v[20:23], v[172:175], v[206:209], v[20:23]
	v_mfma_f32_16x16x32_bf16 v[16:19], v[180:183], v[206:209], v[16:19]
	v_mfma_f32_16x16x32_bf16 v[4:7], v[172:175], v[214:217], v[4:7]
	v_mfma_f32_16x16x32_bf16 v[0:3], v[180:183], v[214:217], v[0:3]
	s_barrier
; #define PG8_STAGE(bufoff, gbase, voff) do { _Pragma("unroll") for (int _i = 0; _i < 2; ++_i) \
;         __builtin_amdgcn_global_load_lds((const unsigned*)((const char*)(gbase) + (voff)[_i]), (PG8_LAS unsigned*)(lds + (bufoff) + ldsw + _i * 8192), 16, 0, 0); } while (0)
; #define PG8_LDA(dst, b, h) do { _Pragma("unroll") for (int m = 0; m < 4; ++m) _Pragma("unroll") for (int k = 0; k < 2; ++k) dst[m][k] = *(const PG8_LAS bf16x8*)(lds + PG8_SA(b, h) + aoff + m * 2048 + k * 1024); } while (0)
; #define PG8_LDB(dst, b, h) do { _Pragma("unroll") for (int n = 0; n < 2; ++n) _Pragma("unroll") for (int k = 0; k < 2; ++k) dst[n][k] = *(const PG8_LAS bf16x8*)(lds + PG8_SB(b, h) + boff + n * 2048 + k * 1024); } while (0)
; #define PG8_MMA(ai, bj, At, Bt) do { __builtin_amdgcn_s_setprio(1); _Pragma("unroll") for (int m = 0; m < 4; ++m) _Pragma("unroll") for (int n = 0; n < 2; ++n) _Pragma("unroll") for (int k = 0; k < 2; ++k) \
;         acc[ai][bj][m][n] = __builtin_amdgcn_mfma_f32_16x16x32_bf16(Bt[n][k], At[m][k], acc[ai][bj][m][n], 0, 0, 0); __builtin_amdgcn_s_setprio(0); } while (0)
; #define PG8_WAIT_V(n) asm volatile("s_waitcnt vmcnt(" #n ")" ::: "memory")
; #define PG8_WAIT_L(n) asm volatile("s_waitcnt lgkmcnt(" #n ")" ::: "memory")
; #define PG8_BAR __builtin_amdgcn_s_barrier()
; #define PG8_SCHED __builtin_amdgcn_sched_barrier(0)
; template <class Epi, class Sched, bool ALIGN_EPI = false, bool SP2 = false>
; __device__ __forceinline__ void gemm_phase(PG8_LAS unsigned char* lds, const Gemm g, const Sched& S, const Epi& E) {
;     ...
;             PG8_LDB(B0, 1, 0); PG8_LDB(B1, 1, 1); PG8_SCHED; PG8_LDA(At, 1, 0); PG8_STAGE(PG8_SA(0, 1), a2 + hstepA, voffA);
;             PG8_WAIT_V(8); PG8_WAIT_L(0); PG8_BAR; PG8_MMA(0, 0, At, B0); PG8_MMA(0, 1, At, B1); PG8_BAR; PG8_SCHED;
;             PG8_LDA(At, 1, 1); PG8_STAGE(PG8_SB(1, 0), b3, voffB); PG8_STAGE(PG8_SB(1, 1), b3 + hstepB, voffB); PG8_STAGE(PG8_SA(1, 0), a3, voffA);
;             PG8_WAIT_V(8); PG8_WAIT_L(0); PG8_BAR; PG8_MMA(1, 0, At, B0); PG8_MMA(1, 1, At, B1); PG8_BAR; PG8_SCHED;
	s_add_i32 s64, 0, 0x18000
	v_add_u32_e32 v155, s64, v150
	s_add_i32 s65, 0, 0x1c000
	ds_read_b128 v[144:147], v155
	ds_read_b128 v[156:159], v155 offset:1024
	ds_read_b128 v[160:163], v155 offset:2048
	ds_read_b128 v[164:167], v155 offset:3072
	v_add_u32_e32 v155, s65, v150
	ds_read_b128 v[168:171], v155
	ds_read_b128 v[172:175], v155 offset:1024
	ds_read_b128 v[176:179], v155 offset:2048
	ds_read_b128 v[180:183], v155 offset:3072
	s_add_u32 s48, s48, 0x40000
	s_addc_u32 s49, s49, 0
	s_mov_b32 m0, s52
	ds_read_b128 v[184:187], v153 offset:32768
	ds_read_b128 v[188:191], v153 offset:33792
	ds_read_b128 v[194:197], v153 offset:34816
	ds_read_b128 v[198:201], v153 offset:35840
	ds_read_b128 v[202:205], v153 offset:36864
	ds_read_b128 v[206:209], v153 offset:37888
	ds_read_b128 v[210:213], v153 offset:38912
	ds_read_b128 v[214:217], v153 offset:39936
	global_load_lds_dwordx4 v128, s[48:49]
	s_mov_b32 m0, s53
	s_nop 0
	global_load_lds_dwordx4 v132, s[48:49]
	s_waitcnt vmcnt(8)
	s_waitcnt lgkmcnt(0)
	s_barrier
	s_waitcnt lgkmcnt(0)
	v_mfma_f32_16x16x32_bf16 v[124:127], v[144:147], v[184:187], v[124:127]
	v_mfma_f32_16x16x32_bf16 v[120:123], v[160:163], v[184:187], v[120:123]
	v_mfma_f32_16x16x32_bf16 v[108:111], v[144:147], v[194:197], v[108:111]
	v_mfma_f32_16x16x32_bf16 v[104:107], v[160:163], v[194:197], v[104:107]
	v_mfma_f32_16x16x32_bf16 v[92:95], v[144:147], v[202:205], v[92:95]
	v_mfma_f32_16x16x32_bf16 v[88:91], v[160:163], v[202:205], v[88:91]
	v_mfma_f32_16x16x32_bf16 v[76:79], v[144:147], v[210:213], v[76:79]
	v_mfma_f32_16x16x32_bf16 v[72:75], v[160:163], v[210:213], v[72:75]
	v_mfma_f32_16x16x32_bf16 v[124:127], v[156:159], v[188:191], v[124:127]
	v_mfma_f32_16x16x32_bf16 v[120:123], v[164:167], v[188:191], v[120:123]
	v_mfma_f32_16x16x32_bf16 v[108:111], v[156:159], v[198:201], v[108:111]
	v_mfma_f32_16x16x32_bf16 v[104:107], v[164:167], v[198:201], v[104:107]
	v_mfma_f32_16x16x32_bf16 v[92:95], v[156:159], v[206:209], v[92:95]
	v_mfma_f32_16x16x32_bf16 v[88:91], v[164:167], v[206:209], v[88:91]
	v_mfma_f32_16x16x32_bf16 v[76:79], v[156:159], v[214:217], v[76:79]
	v_mfma_f32_16x16x32_bf16 v[72:75], v[164:167], v[214:217], v[72:75]
	v_mfma_f32_16x16x32_bf16 v[116:119], v[168:171], v[184:187], v[116:119]
	v_mfma_f32_16x16x32_bf16 v[112:115], v[176:179], v[184:187], v[112:115]
	v_mfma_f32_16x16x32_bf16 v[100:103], v[168:171], v[194:197], v[100:103]
	v_mfma_f32_16x16x32_bf16 v[96:99], v[176:179], v[194:197], v[96:99]
	v_mfma_f32_16x16x32_bf16 v[84:87], v[168:171], v[202:205], v[84:87]
	v_mfma_f32_16x16x32_bf16 v[80:83], v[176:179], v[202:205], v[80:83]
	v_mfma_f32_16x16x32_bf16 v[68:71], v[168:171], v[210:213], v[68:71]
	v_mfma_f32_16x16x32_bf16 v[64:67], v[176:179], v[210:213], v[64:67]
	v_mfma_f32_16x16x32_bf16 v[116:119], v[172:175], v[188:191], v[116:119]
	v_mfma_f32_16x16x32_bf16 v[112:115], v[180:183], v[188:191], v[112:115]
	v_mfma_f32_16x16x32_bf16 v[100:103], v[172:175], v[198:201], v[100:103]
	v_mfma_f32_16x16x32_bf16 v[96:99], v[180:183], v[198:201], v[96:99]
	v_mfma_f32_16x16x32_bf16 v[84:87], v[172:175], v[206:209], v[84:87]
	v_mfma_f32_16x16x32_bf16 v[80:83], v[180:183], v[206:209], v[80:83]
	v_mfma_f32_16x16x32_bf16 v[68:71], v[172:175], v[214:217], v[68:71]
	v_mfma_f32_16x16x32_bf16 v[64:67], v[180:183], v[214:217], v[64:67]
	s_barrier
	s_add_i32 s48, s64, s50
	s_mov_b32 m0, s48
	ds_read_b128 v[184:187], v153 offset:49152
	ds_read_b128 v[188:191], v153 offset:50176
	ds_read_b128 v[194:197], v153 offset:51200
	ds_read_b128 v[198:201], v153 offset:52224
	ds_read_b128 v[202:205], v153 offset:53248
	ds_read_b128 v[206:209], v153 offset:54272
	ds_read_b128 v[210:213], v153 offset:55296
	ds_read_b128 v[214:217], v153 offset:56320
	global_load_lds_dwordx4 v130, s[98:99]
	s_add_i32 m0, s48, 0x2000
	s_add_u32 s44, s44, 0x40080
	s_addc_u32 s45, s45, 0
	s_add_i32 s48, s65, s50
	global_load_lds_dwordx4 v134, s[98:99]
	s_mov_b32 m0, s48
	s_nop 0
	global_load_lds_dwordx4 v130, s[44:45]
	s_add_i32 m0, s48, 0x2000
	s_nop 0
	global_load_lds_dwordx4 v134, s[44:45]
	s_mov_b32 m0, s57
	s_nop 0
	global_load_lds_dwordx4 v128, s[100:101]
	s_mov_b32 m0, s58
	s_nop 0
	global_load_lds_dwordx4 v132, s[100:101]
	s_waitcnt vmcnt(8)
	s_waitcnt lgkmcnt(0)
	s_barrier
	s_waitcnt lgkmcnt(0)
	v_mfma_f32_16x16x32_bf16 v[60:63], v[144:147], v[184:187], v[60:63]
	v_mfma_f32_16x16x32_bf16 v[56:59], v[160:163], v[184:187], v[56:59]
	v_mfma_f32_16x16x32_bf16 v[44:47], v[144:147], v[194:197], v[44:47]
	v_mfma_f32_16x16x32_bf16 v[40:43], v[160:163], v[194:197], v[40:43]
	v_mfma_f32_16x16x32_bf16 v[28:31], v[144:147], v[202:205], v[28:31]
	v_mfma_f32_16x16x32_bf16 v[24:27], v[160:163], v[202:205], v[24:27]
	v_mfma_f32_16x16x32_bf16 v[12:15], v[144:147], v[210:213], v[12:15]
	v_mfma_f32_16x16x32_bf16 v[8:11], v[160:163], v[210:213], v[8:11]
	v_mfma_f32_16x16x32_bf16 v[60:63], v[156:159], v[188:191], v[60:63]
	v_mfma_f32_16x16x32_bf16 v[56:59], v[164:167], v[188:191], v[56:59]
	v_mfma_f32_16x16x32_bf16 v[44:47], v[156:159], v[198:201], v[44:47]
	v_mfma_f32_16x16x32_bf16 v[40:43], v[164:167], v[198:201], v[40:43]
	v_mfma_f32_16x16x32_bf16 v[28:31], v[156:159], v[206:209], v[28:31]
	v_mfma_f32_16x16x32_bf16 v[24:27], v[164:167], v[206:209], v[24:27]
	v_mfma_f32_16x16x32_bf16 v[12:15], v[156:159], v[214:217], v[12:15]
	v_mfma_f32_16x16x32_bf16 v[8:11], v[164:167], v[214:217], v[8:11]
	v_mfma_f32_16x16x32_bf16 v[52:55], v[168:171], v[184:187], v[52:55]
	v_mfma_f32_16x16x32_bf16 v[48:51], v[176:179], v[184:187], v[48:51]
	v_mfma_f32_16x16x32_bf16 v[36:39], v[168:171], v[194:197], v[36:39]
	v_mfma_f32_16x16x32_bf16 v[32:35], v[176:179], v[194:197], v[32:35]
	v_mfma_f32_16x16x32_bf16 v[20:23], v[168:171], v[202:205], v[20:23]
	v_mfma_f32_16x16x32_bf16 v[16:19], v[176:179], v[202:205], v[16:19]
	v_mfma_f32_16x16x32_bf16 v[4:7], v[168:171], v[210:213], v[4:7]
	v_mfma_f32_16x16x32_bf16 v[0:3], v[176:179], v[210:213], v[0:3]
	v_mfma_f32_16x16x32_bf16 v[52:55], v[172:175], v[188:191], v[52:55]
	v_mfma_f32_16x16x32_bf16 v[48:51], v[180:183], v[188:191], v[48:51]
	v_mfma_f32_16x16x32_bf16 v[36:39], v[172:175], v[198:201], v[36:39]
	v_mfma_f32_16x16x32_bf16 v[32:35], v[180:183], v[198:201], v[32:35]
	v_mfma_f32_16x16x32_bf16 v[20:23], v[172:175], v[206:209], v[20:23]
	v_mfma_f32_16x16x32_bf16 v[16:19], v[180:183], v[206:209], v[16:19]
	v_mfma_f32_16x16x32_bf16 v[4:7], v[172:175], v[214:217], v[4:7]
	v_mfma_f32_16x16x32_bf16 v[0:3], v[180:183], v[214:217], v[0:3]
	s_barrier
	s_add_i32 s63, s63, 2
	s_add_u32 s40, s40, 0x100
	s_addc_u32 s41, s41, 0
	s_add_u32 s42, s42, 0x100
	s_addc_u32 s62, s62, 0
	s_cmp_gt_u32 s63, 13
	s_cbranch_scc0 .LBB0_724
	s_and_b64 vcc, exec, s[12:13]
	s_cbranch_vccz .LBB0_727
	s_barrier
